# saddr-form LDS-DMA also for the SB(0,0)/SB(1,0) stages (scratch SGPR pair s[98:99] = b2 + K-step): 4 more 64-bit VALU adds per K-iteration removed
# baseline (speedup 1.0000x reference)
; #define PG8_STAGE(bufoff, gbase, voff) do { _Pragma("unroll") for (int _i = 0; _i < 2; ++_i) \
;         __builtin_amdgcn_global_load_lds((const unsigned*)((const char*)(gbase) + (voff)[_i]), (PG8_LAS unsigned*)(lds + (bufoff) + ldsw + _i * 8192), 16, 0, 0); } while (0)
; #define PG8_LDA(dst, b, h) do { _Pragma("unroll") for (int m = 0; m < 4; ++m) _Pragma("unroll") for (int k = 0; k < 2; ++k) dst[m][k] = *(const PG8_LAS bf16x8*)(lds + PG8_SA(b, h) + aoff + m * 2048 + k * 1024); } while (0)
; #define PG8_LDB(dst, b, h) do { _Pragma("unroll") for (int n = 0; n < 2; ++n) _Pragma("unroll") for (int k = 0; k < 2; ++k) dst[n][k] = *(const PG8_LAS bf16x8*)(lds + PG8_SB(b, h) + boff + n * 2048 + k * 1024); } while (0)
; #define PG8_WAIT_V(n) asm volatile("s_waitcnt vmcnt(" #n ")" ::: "memory")
; #define PG8_WAIT_L(n) asm volatile("s_waitcnt lgkmcnt(" #n ")" ::: "memory")
; #define PG8_BAR __builtin_amdgcn_s_barrier()
; #define PG8_SCHED __builtin_amdgcn_sched_barrier(0)
; template <class Epi, class Sched, bool ALIGN_EPI = false, bool SP2 = false, bool I8 = false>
; __device__ __forceinline__ void gemm_phase(PG8_LAS unsigned char* lds, const Gemm g, const Sched& S, const Epi& E) {
;     ...
;         const bool has_next = S.next(ui + 1, nxt);
;         const char* nA = has_next ? (const char*)g.A + (size_t)nxt.pm * tstep : cA; const char* nB = has_next ? (const char*)g.Bt + (size_t)nxt.pn * tstep : cB;
;         for (int t = 0; t < nt; t += 2) {
;             const bool last = (t == nt - 2);
;             const char* a1 = cA + (size_t)(t + 1) * kstep;
;             const char* a2 = last ? nA : cA + (size_t)(t + 2) * kstep; const char* b2 = last ? nB : cB + (size_t)(t + 2) * kstep;
;             const char* a3 = a2 + kstep; const char* b3 = b2 + kstep;
;             if (last && has_next) S.a_ready(nxt);
;             if constexpr (SP2) {
;             PG8_LDB(B0, 0, 0); PG8_LDB(B1, 0, 1); PG8_SCHED; PG8_LDA(At, 0, 0); PG8_STAGE(PG8_SA(1, 1), a1 + hstep, voffA);
;             PG8_WAIT_V(8); PG8_WAIT_L(0); PG8_BAR; PG8_MMA(0, 0, At, B0); PG8_MMA(0, 1, At, B1); PG8_BAR; PG8_SCHED;
;             PG8_LDA(At, 0, 1); PG8_STAGE(PG8_SB(0, 0), b2, voffB); PG8_STAGE(PG8_SB(0, 1), b2 + hstep, voffB); PG8_STAGE(PG8_SA(0, 0), a2, voffA);
;             PG8_WAIT_V(8); PG8_WAIT_L(0); PG8_BAR; PG8_MMA(1, 0, At, B0); PG8_MMA(1, 1, At, B1); PG8_BAR; PG8_SCHED;
.LBB0_207:
	s_ashr_i32 s19, s18, 31
	s_lshl_b64 s[22:23], s[18:19], 20
	s_add_u32 s22, s28, s22
	s_addc_u32 s23, s34, s23
	s_and_b64 s[24:25], s[6:7], exec
	s_cselect_b32 s19, s23, s27
	s_cselect_b32 s64, s22, s26
	s_ashr_i32 s17, s16, 31
	s_lshl_b64 s[24:25], s[16:17], 20
	s_add_u32 s24, s35, s24
	s_addc_u32 s25, s42, s25
	s_and_b64 s[40:41], s[6:7], exec
	s_cselect_b32 s17, s25, s37
	s_cselect_b32 s65, s24, s36
	s_add_u32 s26, s26, 0x80080
	s_addc_u32 s27, s27, 0
	s_add_u32 s72, s36, 0x100
	s_addc_u32 s73, s37, 0
	s_mov_b32 s76, -2
	s_add_u32 s36, s26, 0xfff80080
	s_addc_u32 s37, s27, -1
	s_add_i32 s50, 0, 0x10000
	s_cmp_eq_u32 s76, 28
	s_cselect_b32 s41, s19, s37
	s_cselect_b32 s40, s64, s36
	s_cselect_b32 s37, s17, s73
	s_cselect_b32 s36, s65, s72
	s_add_i32 s56, 0, 0x14000
	v_add_u32_e32 v136, s50, v175
	v_add_u32_e32 v172, s56, v175
	ds_read_b128 v[116:119], v136
	ds_read_b128 v[124:127], v136 offset:1024
	ds_read_b128 v[132:135], v136 offset:2048
	ds_read_b128 v[136:139], v136 offset:3072
	ds_read_b128 v[160:163], v172
	ds_read_b128 v[164:167], v172 offset:1024
	ds_read_b128 v[168:171], v172 offset:2048
	ds_read_b128 v[178:181], v172 offset:3072
	s_add_i32 m0, s44, 0xc000
	ds_read_b128 v[182:185], v177
	ds_read_b128 v[186:189], v177 offset:1024
	ds_read_b128 v[204:207], v177 offset:2048
	ds_read_b128 v[208:211], v177 offset:3072
	ds_read_b128 v[212:215], v177 offset:4096
	ds_read_b128 v[216:219], v177 offset:5120
	ds_read_b128 v[220:223], v177 offset:6144
	ds_read_b128 v[224:227], v177 offset:7168
	global_load_lds_dwordx4 v156, s[26:27]
	s_add_i32 m0, s44, 0xe000
	s_nop 0
	global_load_lds_dwordx4 v158, s[26:27]
	s_waitcnt vmcnt(8)
	s_waitcnt lgkmcnt(0)
	s_barrier
	s_setprio 1
	s_waitcnt lgkmcnt(0)
	v_mfma_i32_16x16x64_i8 v[144:147], v[116:119], v[182:185], 0
	v_mfma_i32_16x16x64_i8 v[144:147], v[124:127], v[186:189], v[144:147]
	v_mfma_i32_16x16x64_i8 v[112:115], v[124:127], v[208:211], 0
	v_mfma_i32_16x16x64_i8 v[112:115], v[116:119], v[204:207], v[112:115]
	v_mfma_i32_16x16x64_i8 v[96:99], v[116:119], v[212:215], 0
	v_mfma_i32_16x16x64_i8 v[96:99], v[124:127], v[216:219], v[96:99]
	v_mfma_i32_16x16x64_i8 v[80:83], v[124:127], v[224:227], 0
	v_mfma_i32_16x16x64_i8 v[80:83], v[116:119], v[220:223], v[80:83]
	v_mfma_i32_16x16x64_i8 v[76:79], v[132:135], v[220:223], 0
	v_mfma_i32_16x16x64_i8 v[76:79], v[136:139], v[224:227], v[76:79]
	v_mfma_i32_16x16x64_i8 v[92:95], v[136:139], v[216:219], 0
	v_mfma_i32_16x16x64_i8 v[92:95], v[132:135], v[212:215], v[92:95]
	v_mfma_i32_16x16x64_i8 v[108:111], v[132:135], v[204:207], 0
	v_mfma_i32_16x16x64_i8 v[108:111], v[136:139], v[208:211], v[108:111]
	v_mfma_i32_16x16x64_i8 v[140:143], v[136:139], v[186:189], 0
	v_mfma_i32_16x16x64_i8 v[140:143], v[132:135], v[182:185], v[140:143]
	v_mfma_i32_16x16x64_i8 v[128:131], v[160:163], v[182:185], 0
	v_mfma_i32_16x16x64_i8 v[128:131], v[164:167], v[186:189], v[128:131]
	v_mfma_i32_16x16x64_i8 v[104:107], v[164:167], v[208:211], 0
	v_mfma_i32_16x16x64_i8 v[104:107], v[160:163], v[204:207], v[104:107]
	v_mfma_i32_16x16x64_i8 v[88:91], v[160:163], v[212:215], 0
	v_mfma_i32_16x16x64_i8 v[88:91], v[164:167], v[216:219], v[88:91]
	v_mfma_i32_16x16x64_i8 v[72:75], v[164:167], v[224:227], 0
	v_mfma_i32_16x16x64_i8 v[72:75], v[160:163], v[220:223], v[72:75]
	v_mfma_i32_16x16x64_i8 v[68:71], v[168:171], v[220:223], 0
	v_mfma_i32_16x16x64_i8 v[68:71], v[178:181], v[224:227], v[68:71]
	v_mfma_i32_16x16x64_i8 v[84:87], v[178:181], v[216:219], 0
	v_mfma_i32_16x16x64_i8 v[84:87], v[168:171], v[212:215], v[84:87]
	v_mfma_i32_16x16x64_i8 v[100:103], v[168:171], v[204:207], 0
	v_mfma_i32_16x16x64_i8 v[100:103], v[178:181], v[208:211], v[100:103]
	v_mfma_i32_16x16x64_i8 v[120:123], v[178:181], v[186:189], 0
	v_mfma_i32_16x16x64_i8 v[120:123], v[168:171], v[182:185], v[120:123]
	s_setprio 0
	s_barrier
	s_add_i32 s50, s50, s43
	s_mov_b32 m0, s50
	ds_read_b128 v[182:185], v177 offset:16384
	ds_read_b128 v[186:189], v177 offset:17408
	ds_read_b128 v[204:207], v177 offset:18432
	ds_read_b128 v[208:211], v177 offset:19456
	ds_read_b128 v[212:215], v177 offset:20480
	ds_read_b128 v[216:219], v177 offset:21504
	ds_read_b128 v[220:223], v177 offset:22528
	ds_read_b128 v[224:227], v177 offset:23552
	global_load_lds_dwordx4 v2, s[36:37]
	s_add_i32 m0, s50, 0x2000
	s_add_u32 s50, s36, 0x80000
	s_addc_u32 s51, s37, 0
	s_add_i32 s56, s56, s43
	global_load_lds_dwordx4 v148, s[36:37]
	s_mov_b32 m0, s56
	v_lshl_add_u64 v[240:241], s[40:41], 0, v[150:151]
	global_load_lds_dwordx4 v2, s[50:51]
	s_add_i32 m0, s56, 0x2000
	s_nop 0
	global_load_lds_dwordx4 v148, s[50:51]
	v_lshl_add_u64 v[228:229], s[40:41], 0, v[152:153]
	s_waitcnt vmcnt(6)
	s_waitcnt lgkmcnt(0)
	s_barrier
; #define PG8_STAGE(bufoff, gbase, voff) do { _Pragma("unroll") for (int _i = 0; _i < 2; ++_i) \
;         __builtin_amdgcn_global_load_lds((const unsigned*)((const char*)(gbase) + (voff)[_i]), (PG8_LAS unsigned*)(lds + (bufoff) + ldsw + _i * 8192), 16, 0, 0); } while (0)
; #define PG8_LDA(dst, b, h) do { _Pragma("unroll") for (int m = 0; m < 4; ++m) _Pragma("unroll") for (int k = 0; k < 2; ++k) dst[m][k] = *(const PG8_LAS bf16x8*)(lds + PG8_SA(b, h) + aoff + m * 2048 + k * 1024); } while (0)
; #define PG8_LDB(dst, b, h) do { _Pragma("unroll") for (int n = 0; n < 2; ++n) _Pragma("unroll") for (int k = 0; k < 2; ++k) dst[n][k] = *(const PG8_LAS bf16x8*)(lds + PG8_SB(b, h) + boff + n * 2048 + k * 1024); } while (0)
; #define PG8_WAIT_V(n) asm volatile("s_waitcnt vmcnt(" #n ")" ::: "memory")
; #define PG8_WAIT_L(n) asm volatile("s_waitcnt lgkmcnt(" #n ")" ::: "memory")
; #define PG8_BAR __builtin_amdgcn_s_barrier()
; #define PG8_SCHED __builtin_amdgcn_sched_barrier(0)
; template <class Epi, class Sched, bool ALIGN_EPI = false, bool SP2 = false, bool I8 = false>
; __device__ __forceinline__ void gemm_phase(PG8_LAS unsigned char* lds, const Gemm g, const Sched& S, const Epi& E) {
;     ...
;             PG8_WAIT_V(8); PG8_WAIT_L(0); PG8_BAR; PG8_MMA(1, 0, At, B0); PG8_MMA(1, 1, At, B1); PG8_BAR; PG8_SCHED;
;             PG8_LDB(B0, 1, 0); PG8_LDB(B1, 1, 1); PG8_SCHED; PG8_LDA(At, 1, 0); PG8_STAGE(PG8_SA(0, 1), a2 + hstep, voffA);
;             PG8_WAIT_V(8); PG8_WAIT_L(0); PG8_BAR; PG8_MMA(0, 0, At, B0); PG8_MMA(0, 1, At, B1); PG8_BAR; PG8_SCHED;
;             PG8_LDA(At, 1, 1); PG8_STAGE(PG8_SB(1, 0), b3, voffB); PG8_STAGE(PG8_SB(1, 1), b3 + hstep, voffB); PG8_STAGE(PG8_SA(1, 0), a3, voffA);
;             PG8_WAIT_V(8); PG8_WAIT_L(0); PG8_BAR; PG8_MMA(1, 0, At, B0); PG8_MMA(1, 1, At, B1); PG8_BAR; PG8_SCHED;
	s_setprio 1
	s_waitcnt lgkmcnt(0)
	v_mfma_i32_16x16x64_i8 v[64:67], v[116:119], v[182:185], 0
	v_mfma_i32_16x16x64_i8 v[64:67], v[124:127], v[186:189], v[64:67]
	v_mfma_i32_16x16x64_i8 v[48:51], v[124:127], v[208:211], 0
	v_mfma_i32_16x16x64_i8 v[48:51], v[116:119], v[204:207], v[48:51]
	v_mfma_i32_16x16x64_i8 v[32:35], v[116:119], v[212:215], 0
	v_mfma_i32_16x16x64_i8 v[32:35], v[124:127], v[216:219], v[32:35]
	v_mfma_i32_16x16x64_i8 v[16:19], v[124:127], v[224:227], 0
	v_mfma_i32_16x16x64_i8 v[16:19], v[116:119], v[220:223], v[16:19]
	v_mfma_i32_16x16x64_i8 v[12:15], v[132:135], v[220:223], 0
	v_mfma_i32_16x16x64_i8 v[12:15], v[136:139], v[224:227], v[12:15]
	v_mfma_i32_16x16x64_i8 v[28:31], v[136:139], v[216:219], 0
	v_mfma_i32_16x16x64_i8 v[28:31], v[132:135], v[212:215], v[28:31]
	v_mfma_i32_16x16x64_i8 v[44:47], v[132:135], v[204:207], 0
	v_mfma_i32_16x16x64_i8 v[44:47], v[136:139], v[208:211], v[44:47]
	v_mfma_i32_16x16x64_i8 v[60:63], v[136:139], v[186:189], 0
	v_mfma_i32_16x16x64_i8 v[60:63], v[132:135], v[182:185], v[60:63]
	v_mfma_i32_16x16x64_i8 v[56:59], v[160:163], v[182:185], 0
	v_mfma_i32_16x16x64_i8 v[56:59], v[164:167], v[186:189], v[56:59]
	v_mfma_i32_16x16x64_i8 v[40:43], v[164:167], v[208:211], 0
	v_mfma_i32_16x16x64_i8 v[40:43], v[160:163], v[204:207], v[40:43]
	v_mfma_i32_16x16x64_i8 v[24:27], v[160:163], v[212:215], 0
	v_mfma_i32_16x16x64_i8 v[24:27], v[164:167], v[216:219], v[24:27]
	v_mfma_i32_16x16x64_i8 v[8:11], v[164:167], v[224:227], 0
	v_mfma_i32_16x16x64_i8 v[8:11], v[160:163], v[220:223], v[8:11]
	v_mfma_i32_16x16x64_i8 v[4:7], v[168:171], v[220:223], 0
	v_mfma_i32_16x16x64_i8 v[4:7], v[178:181], v[224:227], v[4:7]
	v_mfma_i32_16x16x64_i8 v[20:23], v[178:181], v[216:219], 0
	v_mfma_i32_16x16x64_i8 v[20:23], v[168:171], v[212:215], v[20:23]
	v_mfma_i32_16x16x64_i8 v[36:39], v[168:171], v[204:207], 0
	v_mfma_i32_16x16x64_i8 v[36:39], v[178:181], v[208:211], v[36:39]
	v_mfma_i32_16x16x64_i8 v[52:55], v[178:181], v[186:189], 0
	v_mfma_i32_16x16x64_i8 v[52:55], v[168:171], v[182:185], v[52:55]
	s_setprio 0
	s_barrier
	s_mov_b32 m0, s44
	s_nop 0
	global_load_lds_dwordx4 v[228:229], off
	s_mov_b32 m0, s45
	s_nop 0
	global_load_lds_dwordx4 v[240:241], off
	s_add_i32 s50, 0, 0x18000
	s_add_i32 s51, 0, 0x1c000
	v_add_u32_e32 v136, s50, v175
	v_add_u32_e32 v178, s51, v175
	ds_read_b128 v[116:119], v136
	ds_read_b128 v[124:127], v136 offset:1024
	ds_read_b128 v[132:135], v136 offset:2048
	ds_read_b128 v[136:139], v136 offset:3072
	ds_read_b128 v[160:163], v178
	ds_read_b128 v[164:167], v178 offset:1024
	ds_read_b128 v[168:171], v178 offset:2048
	ds_read_b128 v[178:181], v178 offset:3072
	s_add_u32 s40, s40, 0x80000
	s_addc_u32 s41, s41, 0
	s_mov_b32 m0, s46
	ds_read_b128 v[182:185], v177 offset:32768
	ds_read_b128 v[186:189], v177 offset:33792
	ds_read_b128 v[204:207], v177 offset:34816
	ds_read_b128 v[208:211], v177 offset:35840
	ds_read_b128 v[212:215], v177 offset:36864
	ds_read_b128 v[216:219], v177 offset:37888
	ds_read_b128 v[220:223], v177 offset:38912
	ds_read_b128 v[224:227], v177 offset:39936
	global_load_lds_dwordx4 v152, s[40:41]
	s_mov_b32 m0, s47
	s_nop 0
	global_load_lds_dwordx4 v150, s[40:41]
	s_waitcnt vmcnt(8)
	s_waitcnt lgkmcnt(0)
	s_barrier
	s_setprio 1
	s_waitcnt lgkmcnt(0)
	v_mfma_i32_16x16x64_i8 v[144:147], v[116:119], v[182:185], v[144:147]
	v_mfma_i32_16x16x64_i8 v[144:147], v[124:127], v[186:189], v[144:147]
	v_mfma_i32_16x16x64_i8 v[112:115], v[124:127], v[208:211], v[112:115]
	v_mfma_i32_16x16x64_i8 v[112:115], v[116:119], v[204:207], v[112:115]
	v_mfma_i32_16x16x64_i8 v[96:99], v[116:119], v[212:215], v[96:99]
	v_mfma_i32_16x16x64_i8 v[96:99], v[124:127], v[216:219], v[96:99]
	v_mfma_i32_16x16x64_i8 v[80:83], v[124:127], v[224:227], v[80:83]
	v_mfma_i32_16x16x64_i8 v[80:83], v[116:119], v[220:223], v[80:83]
	v_mfma_i32_16x16x64_i8 v[76:79], v[132:135], v[220:223], v[76:79]
	v_mfma_i32_16x16x64_i8 v[76:79], v[136:139], v[224:227], v[76:79]
	v_mfma_i32_16x16x64_i8 v[92:95], v[136:139], v[216:219], v[92:95]
	v_mfma_i32_16x16x64_i8 v[92:95], v[132:135], v[212:215], v[92:95]
	v_mfma_i32_16x16x64_i8 v[108:111], v[132:135], v[204:207], v[108:111]
	v_mfma_i32_16x16x64_i8 v[108:111], v[136:139], v[208:211], v[108:111]
	v_mfma_i32_16x16x64_i8 v[140:143], v[136:139], v[186:189], v[140:143]
	v_mfma_i32_16x16x64_i8 v[140:143], v[132:135], v[182:185], v[140:143]
	v_mfma_i32_16x16x64_i8 v[128:131], v[160:163], v[182:185], v[128:131]
	v_mfma_i32_16x16x64_i8 v[128:131], v[164:167], v[186:189], v[128:131]
	v_mfma_i32_16x16x64_i8 v[104:107], v[164:167], v[208:211], v[104:107]
	v_mfma_i32_16x16x64_i8 v[104:107], v[160:163], v[204:207], v[104:107]
	v_mfma_i32_16x16x64_i8 v[88:91], v[160:163], v[212:215], v[88:91]
	v_mfma_i32_16x16x64_i8 v[88:91], v[164:167], v[216:219], v[88:91]
	v_mfma_i32_16x16x64_i8 v[72:75], v[164:167], v[224:227], v[72:75]
	v_mfma_i32_16x16x64_i8 v[72:75], v[160:163], v[220:223], v[72:75]
	v_mfma_i32_16x16x64_i8 v[68:71], v[168:171], v[220:223], v[68:71]
	v_mfma_i32_16x16x64_i8 v[68:71], v[178:181], v[224:227], v[68:71]
	v_mfma_i32_16x16x64_i8 v[84:87], v[178:181], v[216:219], v[84:87]
	v_mfma_i32_16x16x64_i8 v[84:87], v[168:171], v[212:215], v[84:87]
	v_mfma_i32_16x16x64_i8 v[100:103], v[168:171], v[204:207], v[100:103]
	v_mfma_i32_16x16x64_i8 v[100:103], v[178:181], v[208:211], v[100:103]
	v_mfma_i32_16x16x64_i8 v[120:123], v[178:181], v[186:189], v[120:123]
	v_mfma_i32_16x16x64_i8 v[120:123], v[168:171], v[182:185], v[120:123]
	s_setprio 0
	s_barrier
	s_add_u32 s98, s36, 0x80
	s_addc_u32 s99, s37, 0
	s_add_i32 s40, s50, s43
	s_mov_b32 m0, s40
	ds_read_b128 v[182:185], v177 offset:49152
	ds_read_b128 v[186:189], v177 offset:50176
	ds_read_b128 v[204:207], v177 offset:51200
	ds_read_b128 v[208:211], v177 offset:52224
	ds_read_b128 v[212:215], v177 offset:53248
	ds_read_b128 v[216:219], v177 offset:54272
	ds_read_b128 v[220:223], v177 offset:55296
	ds_read_b128 v[224:227], v177 offset:56320
	global_load_lds_dwordx4 v2, s[98:99]
	s_add_i32 m0, s40, 0x2000
	s_add_u32 s36, s36, 0x80080
	s_addc_u32 s37, s37, 0
	s_add_i32 s40, s51, s43
	global_load_lds_dwordx4 v148, s[98:99]
	s_mov_b32 m0, s40
	s_nop 0
	global_load_lds_dwordx4 v2, s[36:37]
	s_add_i32 m0, s40, 0x2000
	s_nop 0
	global_load_lds_dwordx4 v148, s[36:37]
	s_cmp_eq_u32 s76, 28
	s_cbranch_scc0 .Ldefer_208_peel
	v_lshl_add_u64 v[172:173], v[228:229], 0, s[84:85]
	s_mov_b32 m0, s52
	s_nop 0
	global_load_lds_dwordx4 v[172:173], off
	v_lshl_add_u64 v[172:173], v[240:241], 0, s[84:85]
	s_mov_b32 m0, s53
	s_nop 0
	global_load_lds_dwordx4 v[172:173], off

; #define PG8_STAGE(bufoff, gbase, voff) do { _Pragma("unroll") for (int _i = 0; _i < 2; ++_i) \
;         __builtin_amdgcn_global_load_lds((const unsigned*)((const char*)(gbase) + (voff)[_i]), (PG8_LAS unsigned*)(lds + (bufoff) + ldsw + _i * 8192), 16, 0, 0); } while (0)
; #define PG8_LDA(dst, b, h) do { _Pragma("unroll") for (int m = 0; m < 4; ++m) _Pragma("unroll") for (int k = 0; k < 2; ++k) dst[m][k] = *(const PG8_LAS bf16x8*)(lds + PG8_SA(b, h) + aoff + m * 2048 + k * 1024); } while (0)
; #define PG8_LDB(dst, b, h) do { _Pragma("unroll") for (int n = 0; n < 2; ++n) _Pragma("unroll") for (int k = 0; k < 2; ++k) dst[n][k] = *(const PG8_LAS bf16x8*)(lds + PG8_SB(b, h) + boff + n * 2048 + k * 1024); } while (0)
; #define PG8_WAIT_V(n) asm volatile("s_waitcnt vmcnt(" #n ")" ::: "memory")
; #define PG8_WAIT_L(n) asm volatile("s_waitcnt lgkmcnt(" #n ")" ::: "memory")
; #define PG8_BAR __builtin_amdgcn_s_barrier()
; #define PG8_SCHED __builtin_amdgcn_sched_barrier(0)
; template <class Epi, class Sched, bool ALIGN_EPI = false, bool SP2 = false, bool I8 = false>
; __device__ __forceinline__ void gemm_phase(PG8_LAS unsigned char* lds, const Gemm g, const Sched& S, const Epi& E) {
;     ...
;         for (int t = 0; t < nt; t += 2) {
;             const bool last = (t == nt - 2);
;             const char* a1 = cA + (size_t)(t + 1) * kstep;
;             const char* a2 = last ? nA : cA + (size_t)(t + 2) * kstep; const char* b2 = last ? nB : cB + (size_t)(t + 2) * kstep;
;             const char* a3 = a2 + kstep; const char* b3 = b2 + kstep;
;             if (last && has_next) S.a_ready(nxt);
;             if constexpr (SP2) {
;             PG8_LDB(B0, 0, 0); PG8_LDB(B1, 0, 1); PG8_SCHED; PG8_LDA(At, 0, 0); PG8_STAGE(PG8_SA(1, 1), a1 + hstep, voffA);
;             PG8_WAIT_V(8); PG8_WAIT_L(0); PG8_BAR; PG8_MMA(0, 0, At, B0); PG8_MMA(0, 1, At, B1); PG8_BAR; PG8_SCHED;
;             PG8_LDA(At, 0, 1); PG8_STAGE(PG8_SB(0, 0), b2, voffB); PG8_STAGE(PG8_SB(0, 1), b2 + hstep, voffB); PG8_STAGE(PG8_SA(0, 0), a2, voffA);
;             PG8_WAIT_V(8); PG8_WAIT_L(0); PG8_BAR; PG8_MMA(1, 0, At, B0); PG8_MMA(1, 1, At, B1); PG8_BAR; PG8_SCHED;
.LBB0_208:
	s_add_u32 s36, s26, 0xfff80080
	s_addc_u32 s37, s27, -1
	s_add_i32 s50, 0, 0x10000
	s_cmp_eq_u32 s76, 28
	s_cselect_b32 s41, s19, s37
	s_cselect_b32 s40, s64, s36
	s_cselect_b32 s37, s17, s73
	s_cselect_b32 s36, s65, s72
	s_add_i32 s56, 0, 0x14000
	v_add_u32_e32 v136, s50, v175
	v_add_u32_e32 v172, s56, v175
	ds_read_b128 v[116:119], v136
	ds_read_b128 v[124:127], v136 offset:1024
	ds_read_b128 v[132:135], v136 offset:2048
	ds_read_b128 v[136:139], v136 offset:3072
	ds_read_b128 v[160:163], v172
	ds_read_b128 v[164:167], v172 offset:1024
	ds_read_b128 v[168:171], v172 offset:2048
	ds_read_b128 v[178:181], v172 offset:3072
	v_lshl_add_u64 v[172:173], v[228:229], 0, s[84:85]
	s_mov_b32 m0, s52
	s_nop 0
	global_load_lds_dwordx4 v[172:173], off
	v_lshl_add_u64 v[172:173], v[240:241], 0, s[84:85]
	s_mov_b32 m0, s53
	s_nop 0
	global_load_lds_dwordx4 v[172:173], off
	s_add_i32 m0, s44, 0xc000
	ds_read_b128 v[182:185], v177
	ds_read_b128 v[186:189], v177 offset:1024
	ds_read_b128 v[204:207], v177 offset:2048
	ds_read_b128 v[208:211], v177 offset:3072
	ds_read_b128 v[212:215], v177 offset:4096
	ds_read_b128 v[216:219], v177 offset:5120
	ds_read_b128 v[220:223], v177 offset:6144
	ds_read_b128 v[224:227], v177 offset:7168
	global_load_lds_dwordx4 v156, s[26:27]
	s_add_i32 m0, s44, 0xe000
	s_nop 0
	global_load_lds_dwordx4 v158, s[26:27]
	s_waitcnt vmcnt(8)
	s_waitcnt lgkmcnt(0)
	s_barrier
	s_setprio 1
	s_waitcnt lgkmcnt(0)
	v_mfma_i32_16x16x64_i8 v[144:147], v[116:119], v[182:185], v[144:147]
	v_mfma_i32_16x16x64_i8 v[144:147], v[124:127], v[186:189], v[144:147]
	v_mfma_i32_16x16x64_i8 v[112:115], v[124:127], v[208:211], v[112:115]
	v_mfma_i32_16x16x64_i8 v[112:115], v[116:119], v[204:207], v[112:115]
	v_mfma_i32_16x16x64_i8 v[96:99], v[116:119], v[212:215], v[96:99]
	v_mfma_i32_16x16x64_i8 v[96:99], v[124:127], v[216:219], v[96:99]
	v_mfma_i32_16x16x64_i8 v[80:83], v[124:127], v[224:227], v[80:83]
	v_mfma_i32_16x16x64_i8 v[80:83], v[116:119], v[220:223], v[80:83]
	v_mfma_i32_16x16x64_i8 v[76:79], v[132:135], v[220:223], v[76:79]
	v_mfma_i32_16x16x64_i8 v[76:79], v[136:139], v[224:227], v[76:79]
	v_mfma_i32_16x16x64_i8 v[92:95], v[136:139], v[216:219], v[92:95]
	v_mfma_i32_16x16x64_i8 v[92:95], v[132:135], v[212:215], v[92:95]
	v_mfma_i32_16x16x64_i8 v[108:111], v[132:135], v[204:207], v[108:111]
	v_mfma_i32_16x16x64_i8 v[108:111], v[136:139], v[208:211], v[108:111]
	v_mfma_i32_16x16x64_i8 v[140:143], v[136:139], v[186:189], v[140:143]
	v_mfma_i32_16x16x64_i8 v[140:143], v[132:135], v[182:185], v[140:143]
	v_mfma_i32_16x16x64_i8 v[128:131], v[160:163], v[182:185], v[128:131]
	v_mfma_i32_16x16x64_i8 v[128:131], v[164:167], v[186:189], v[128:131]
	v_mfma_i32_16x16x64_i8 v[104:107], v[164:167], v[208:211], v[104:107]
	v_mfma_i32_16x16x64_i8 v[104:107], v[160:163], v[204:207], v[104:107]
	v_mfma_i32_16x16x64_i8 v[88:91], v[160:163], v[212:215], v[88:91]
	v_mfma_i32_16x16x64_i8 v[88:91], v[164:167], v[216:219], v[88:91]
	v_mfma_i32_16x16x64_i8 v[72:75], v[164:167], v[224:227], v[72:75]
	v_mfma_i32_16x16x64_i8 v[72:75], v[160:163], v[220:223], v[72:75]
	v_mfma_i32_16x16x64_i8 v[68:71], v[168:171], v[220:223], v[68:71]
	v_mfma_i32_16x16x64_i8 v[68:71], v[178:181], v[224:227], v[68:71]
	v_mfma_i32_16x16x64_i8 v[84:87], v[178:181], v[216:219], v[84:87]
	v_mfma_i32_16x16x64_i8 v[84:87], v[168:171], v[212:215], v[84:87]
	v_mfma_i32_16x16x64_i8 v[100:103], v[168:171], v[204:207], v[100:103]
	v_mfma_i32_16x16x64_i8 v[100:103], v[178:181], v[208:211], v[100:103]
	v_mfma_i32_16x16x64_i8 v[120:123], v[178:181], v[186:189], v[120:123]
	v_mfma_i32_16x16x64_i8 v[120:123], v[168:171], v[182:185], v[120:123]
	s_setprio 0
	s_barrier
	s_add_i32 s50, s50, s43
	s_mov_b32 m0, s50
	ds_read_b128 v[182:185], v177 offset:16384
	ds_read_b128 v[186:189], v177 offset:17408
	ds_read_b128 v[204:207], v177 offset:18432
	ds_read_b128 v[208:211], v177 offset:19456
	ds_read_b128 v[212:215], v177 offset:20480
	ds_read_b128 v[216:219], v177 offset:21504
	ds_read_b128 v[220:223], v177 offset:22528
	ds_read_b128 v[224:227], v177 offset:23552
	global_load_lds_dwordx4 v2, s[36:37]
	s_add_i32 m0, s50, 0x2000
	s_add_u32 s50, s36, 0x80000
	s_addc_u32 s51, s37, 0
	s_add_i32 s56, s56, s43
	global_load_lds_dwordx4 v148, s[36:37]
	s_mov_b32 m0, s56
	v_lshl_add_u64 v[240:241], s[40:41], 0, v[150:151]
	global_load_lds_dwordx4 v2, s[50:51]
	s_add_i32 m0, s56, 0x2000
	s_nop 0
	global_load_lds_dwordx4 v148, s[50:51]
	v_lshl_add_u64 v[228:229], s[40:41], 0, v[152:153]
	s_waitcnt vmcnt(6)
	s_waitcnt lgkmcnt(0)
	s_barrier
; #define PG8_STAGE(bufoff, gbase, voff) do { _Pragma("unroll") for (int _i = 0; _i < 2; ++_i) \
;         __builtin_amdgcn_global_load_lds((const unsigned*)((const char*)(gbase) + (voff)[_i]), (PG8_LAS unsigned*)(lds + (bufoff) + ldsw + _i * 8192), 16, 0, 0); } while (0)
; #define PG8_LDA(dst, b, h) do { _Pragma("unroll") for (int m = 0; m < 4; ++m) _Pragma("unroll") for (int k = 0; k < 2; ++k) dst[m][k] = *(const PG8_LAS bf16x8*)(lds + PG8_SA(b, h) + aoff + m * 2048 + k * 1024); } while (0)
; #define PG8_LDB(dst, b, h) do { _Pragma("unroll") for (int n = 0; n < 2; ++n) _Pragma("unroll") for (int k = 0; k < 2; ++k) dst[n][k] = *(const PG8_LAS bf16x8*)(lds + PG8_SB(b, h) + boff + n * 2048 + k * 1024); } while (0)
; #define PG8_WAIT_V(n) asm volatile("s_waitcnt vmcnt(" #n ")" ::: "memory")
; #define PG8_WAIT_L(n) asm volatile("s_waitcnt lgkmcnt(" #n ")" ::: "memory")
; #define PG8_BAR __builtin_amdgcn_s_barrier()
; #define PG8_SCHED __builtin_amdgcn_sched_barrier(0)
; template <class Epi, class Sched, bool ALIGN_EPI = false, bool SP2 = false, bool I8 = false>
; __device__ __forceinline__ void gemm_phase(PG8_LAS unsigned char* lds, const Gemm g, const Sched& S, const Epi& E) {
;     ...
;             PG8_WAIT_V(8); PG8_WAIT_L(0); PG8_BAR; PG8_MMA(1, 0, At, B0); PG8_MMA(1, 1, At, B1); PG8_BAR; PG8_SCHED;
;             PG8_LDB(B0, 1, 0); PG8_LDB(B1, 1, 1); PG8_SCHED; PG8_LDA(At, 1, 0); PG8_STAGE(PG8_SA(0, 1), a2 + hstep, voffA);
;             PG8_WAIT_V(8); PG8_WAIT_L(0); PG8_BAR; PG8_MMA(0, 0, At, B0); PG8_MMA(0, 1, At, B1); PG8_BAR; PG8_SCHED;
;             PG8_LDA(At, 1, 1); PG8_STAGE(PG8_SB(1, 0), b3, voffB); PG8_STAGE(PG8_SB(1, 1), b3 + hstep, voffB); PG8_STAGE(PG8_SA(1, 0), a3, voffA);
;             PG8_WAIT_V(8); PG8_WAIT_L(0); PG8_BAR; PG8_MMA(1, 0, At, B0); PG8_MMA(1, 1, At, B1); PG8_BAR; PG8_SCHED;
	s_setprio 1
	s_waitcnt lgkmcnt(0)
	v_mfma_i32_16x16x64_i8 v[64:67], v[116:119], v[182:185], v[64:67]
	v_mfma_i32_16x16x64_i8 v[64:67], v[124:127], v[186:189], v[64:67]
	v_mfma_i32_16x16x64_i8 v[48:51], v[124:127], v[208:211], v[48:51]
	v_mfma_i32_16x16x64_i8 v[48:51], v[116:119], v[204:207], v[48:51]
	v_mfma_i32_16x16x64_i8 v[32:35], v[116:119], v[212:215], v[32:35]
	v_mfma_i32_16x16x64_i8 v[32:35], v[124:127], v[216:219], v[32:35]
	v_mfma_i32_16x16x64_i8 v[16:19], v[124:127], v[224:227], v[16:19]
	v_mfma_i32_16x16x64_i8 v[16:19], v[116:119], v[220:223], v[16:19]
	v_mfma_i32_16x16x64_i8 v[12:15], v[132:135], v[220:223], v[12:15]
	v_mfma_i32_16x16x64_i8 v[12:15], v[136:139], v[224:227], v[12:15]
	v_mfma_i32_16x16x64_i8 v[28:31], v[136:139], v[216:219], v[28:31]
	v_mfma_i32_16x16x64_i8 v[28:31], v[132:135], v[212:215], v[28:31]
	v_mfma_i32_16x16x64_i8 v[44:47], v[132:135], v[204:207], v[44:47]
	v_mfma_i32_16x16x64_i8 v[44:47], v[136:139], v[208:211], v[44:47]
	v_mfma_i32_16x16x64_i8 v[60:63], v[136:139], v[186:189], v[60:63]
	v_mfma_i32_16x16x64_i8 v[60:63], v[132:135], v[182:185], v[60:63]
	v_mfma_i32_16x16x64_i8 v[56:59], v[160:163], v[182:185], v[56:59]
	v_mfma_i32_16x16x64_i8 v[56:59], v[164:167], v[186:189], v[56:59]
	v_mfma_i32_16x16x64_i8 v[40:43], v[164:167], v[208:211], v[40:43]
	v_mfma_i32_16x16x64_i8 v[40:43], v[160:163], v[204:207], v[40:43]
	v_mfma_i32_16x16x64_i8 v[24:27], v[160:163], v[212:215], v[24:27]
	v_mfma_i32_16x16x64_i8 v[24:27], v[164:167], v[216:219], v[24:27]
	v_mfma_i32_16x16x64_i8 v[8:11], v[164:167], v[224:227], v[8:11]
	v_mfma_i32_16x16x64_i8 v[8:11], v[160:163], v[220:223], v[8:11]
	v_mfma_i32_16x16x64_i8 v[4:7], v[168:171], v[220:223], v[4:7]
	v_mfma_i32_16x16x64_i8 v[4:7], v[178:181], v[224:227], v[4:7]
	v_mfma_i32_16x16x64_i8 v[20:23], v[178:181], v[216:219], v[20:23]
	v_mfma_i32_16x16x64_i8 v[20:23], v[168:171], v[212:215], v[20:23]
	v_mfma_i32_16x16x64_i8 v[36:39], v[168:171], v[204:207], v[36:39]
	v_mfma_i32_16x16x64_i8 v[36:39], v[178:181], v[208:211], v[36:39]
	v_mfma_i32_16x16x64_i8 v[52:55], v[178:181], v[186:189], v[52:55]
	v_mfma_i32_16x16x64_i8 v[52:55], v[168:171], v[182:185], v[52:55]
	s_setprio 0
	s_barrier
	s_mov_b32 m0, s44
	s_nop 0
	global_load_lds_dwordx4 v[228:229], off
	s_mov_b32 m0, s45
	s_nop 0
	global_load_lds_dwordx4 v[240:241], off
	s_add_i32 s50, 0, 0x18000
	s_add_i32 s51, 0, 0x1c000
	v_add_u32_e32 v136, s50, v175
	v_add_u32_e32 v178, s51, v175
	ds_read_b128 v[116:119], v136
	ds_read_b128 v[124:127], v136 offset:1024
	ds_read_b128 v[132:135], v136 offset:2048
	ds_read_b128 v[136:139], v136 offset:3072
	ds_read_b128 v[160:163], v178
	ds_read_b128 v[164:167], v178 offset:1024
	ds_read_b128 v[168:171], v178 offset:2048
	ds_read_b128 v[178:181], v178 offset:3072
	s_add_u32 s40, s40, 0x80000
	s_addc_u32 s41, s41, 0
	s_mov_b32 m0, s46
	ds_read_b128 v[182:185], v177 offset:32768
	ds_read_b128 v[186:189], v177 offset:33792
	ds_read_b128 v[204:207], v177 offset:34816
	ds_read_b128 v[208:211], v177 offset:35840
	ds_read_b128 v[212:215], v177 offset:36864
	ds_read_b128 v[216:219], v177 offset:37888
	ds_read_b128 v[220:223], v177 offset:38912
	ds_read_b128 v[224:227], v177 offset:39936
	global_load_lds_dwordx4 v152, s[40:41]
	s_mov_b32 m0, s47
	s_nop 0
	global_load_lds_dwordx4 v150, s[40:41]
	s_waitcnt vmcnt(8)
	s_waitcnt lgkmcnt(0)
	s_barrier
	s_setprio 1
	s_waitcnt lgkmcnt(0)
	v_mfma_i32_16x16x64_i8 v[144:147], v[116:119], v[182:185], v[144:147]
	v_mfma_i32_16x16x64_i8 v[144:147], v[124:127], v[186:189], v[144:147]
	v_mfma_i32_16x16x64_i8 v[112:115], v[124:127], v[208:211], v[112:115]
	v_mfma_i32_16x16x64_i8 v[112:115], v[116:119], v[204:207], v[112:115]
	v_mfma_i32_16x16x64_i8 v[96:99], v[116:119], v[212:215], v[96:99]
	v_mfma_i32_16x16x64_i8 v[96:99], v[124:127], v[216:219], v[96:99]
	v_mfma_i32_16x16x64_i8 v[80:83], v[124:127], v[224:227], v[80:83]
	v_mfma_i32_16x16x64_i8 v[80:83], v[116:119], v[220:223], v[80:83]
	v_mfma_i32_16x16x64_i8 v[76:79], v[132:135], v[220:223], v[76:79]
	v_mfma_i32_16x16x64_i8 v[76:79], v[136:139], v[224:227], v[76:79]
	v_mfma_i32_16x16x64_i8 v[92:95], v[136:139], v[216:219], v[92:95]
	v_mfma_i32_16x16x64_i8 v[92:95], v[132:135], v[212:215], v[92:95]
	v_mfma_i32_16x16x64_i8 v[108:111], v[132:135], v[204:207], v[108:111]
	v_mfma_i32_16x16x64_i8 v[108:111], v[136:139], v[208:211], v[108:111]
	v_mfma_i32_16x16x64_i8 v[140:143], v[136:139], v[186:189], v[140:143]
	v_mfma_i32_16x16x64_i8 v[140:143], v[132:135], v[182:185], v[140:143]
	v_mfma_i32_16x16x64_i8 v[128:131], v[160:163], v[182:185], v[128:131]
	v_mfma_i32_16x16x64_i8 v[128:131], v[164:167], v[186:189], v[128:131]
	v_mfma_i32_16x16x64_i8 v[104:107], v[164:167], v[208:211], v[104:107]
	v_mfma_i32_16x16x64_i8 v[104:107], v[160:163], v[204:207], v[104:107]
	v_mfma_i32_16x16x64_i8 v[88:91], v[160:163], v[212:215], v[88:91]
	v_mfma_i32_16x16x64_i8 v[88:91], v[164:167], v[216:219], v[88:91]
	v_mfma_i32_16x16x64_i8 v[72:75], v[164:167], v[224:227], v[72:75]
	v_mfma_i32_16x16x64_i8 v[72:75], v[160:163], v[220:223], v[72:75]
	v_mfma_i32_16x16x64_i8 v[68:71], v[168:171], v[220:223], v[68:71]
	v_mfma_i32_16x16x64_i8 v[68:71], v[178:181], v[224:227], v[68:71]
	v_mfma_i32_16x16x64_i8 v[84:87], v[178:181], v[216:219], v[84:87]
	v_mfma_i32_16x16x64_i8 v[84:87], v[168:171], v[212:215], v[84:87]
	v_mfma_i32_16x16x64_i8 v[100:103], v[168:171], v[204:207], v[100:103]
	v_mfma_i32_16x16x64_i8 v[100:103], v[178:181], v[208:211], v[100:103]
	v_mfma_i32_16x16x64_i8 v[120:123], v[178:181], v[186:189], v[120:123]
	v_mfma_i32_16x16x64_i8 v[120:123], v[168:171], v[182:185], v[120:123]
	s_setprio 0
	s_barrier
	s_add_u32 s98, s36, 0x80
	s_addc_u32 s99, s37, 0
	s_add_i32 s40, s50, s43
	s_mov_b32 m0, s40
	ds_read_b128 v[182:185], v177 offset:49152
	ds_read_b128 v[186:189], v177 offset:50176
	ds_read_b128 v[204:207], v177 offset:51200
	ds_read_b128 v[208:211], v177 offset:52224
	ds_read_b128 v[212:215], v177 offset:53248
	ds_read_b128 v[216:219], v177 offset:54272
	ds_read_b128 v[220:223], v177 offset:55296
	ds_read_b128 v[224:227], v177 offset:56320
	global_load_lds_dwordx4 v2, s[98:99]
	s_add_i32 m0, s40, 0x2000
	s_add_u32 s36, s36, 0x80080
	s_addc_u32 s37, s37, 0
	s_add_i32 s40, s51, s43
	global_load_lds_dwordx4 v148, s[98:99]
	s_mov_b32 m0, s40
	s_nop 0
	global_load_lds_dwordx4 v2, s[36:37]
	s_add_i32 m0, s40, 0x2000
	s_nop 0
	global_load_lds_dwordx4 v148, s[36:37]
	s_cmp_eq_u32 s76, 28
	s_cbranch_scc0 .Ldefer_208_body
	v_lshl_add_u64 v[172:173], v[228:229], 0, s[84:85]
	s_mov_b32 m0, s52
	s_nop 0
	global_load_lds_dwordx4 v[172:173], off
	v_lshl_add_u64 v[172:173], v[240:241], 0, s[84:85]
	s_mov_b32 m0, s53
	s_nop 0
	global_load_lds_dwordx4 v[172:173], off

; #define PG8_STAGE(bufoff, gbase, voff) do { _Pragma("unroll") for (int _i = 0; _i < 2; ++_i) \
;         __builtin_amdgcn_global_load_lds((const unsigned*)((const char*)(gbase) + (voff)[_i]), (PG8_LAS unsigned*)(lds + (bufoff) + ldsw + _i * 8192), 16, 0, 0); } while (0)
; #define PG8_LDA(dst, b, h) do { _Pragma("unroll") for (int m = 0; m < 4; ++m) _Pragma("unroll") for (int k = 0; k < 2; ++k) dst[m][k] = *(const PG8_LAS bf16x8*)(lds + PG8_SA(b, h) + aoff + m * 2048 + k * 1024); } while (0)
; #define PG8_LDB(dst, b, h) do { _Pragma("unroll") for (int n = 0; n < 2; ++n) _Pragma("unroll") for (int k = 0; k < 2; ++k) dst[n][k] = *(const PG8_LAS bf16x8*)(lds + PG8_SB(b, h) + boff + n * 2048 + k * 1024); } while (0)
; #define PG8_WAIT_V(n) asm volatile("s_waitcnt vmcnt(" #n ")" ::: "memory")
; #define PG8_WAIT_L(n) asm volatile("s_waitcnt lgkmcnt(" #n ")" ::: "memory")
; #define PG8_BAR __builtin_amdgcn_s_barrier()
; #define PG8_SCHED __builtin_amdgcn_sched_barrier(0)
; template <class Epi, class Sched, bool ALIGN_EPI = false, bool SP2 = false, bool I8 = false>
; __device__ __forceinline__ void gemm_phase(PG8_LAS unsigned char* lds, const Gemm g, const Sched& S, const Epi& E) {
;     ...
;         const bool has_next = S.next(ui + 1, nxt);
;         const char* nA = has_next ? (const char*)g.A + (size_t)nxt.pm * tstep : cA; const char* nB = has_next ? (const char*)g.Bt + (size_t)nxt.pn * tstep : cB;
;         for (int t = 0; t < nt; t += 2) {
;             const bool last = (t == nt - 2);
;             const char* a1 = cA + (size_t)(t + 1) * kstep;
;             const char* a2 = last ? nA : cA + (size_t)(t + 2) * kstep; const char* b2 = last ? nB : cB + (size_t)(t + 2) * kstep;
;             const char* a3 = a2 + kstep; const char* b3 = b2 + kstep;
;             if (last && has_next) S.a_ready(nxt);
;             if constexpr (SP2) {
;             PG8_LDB(B0, 0, 0); PG8_LDB(B1, 0, 1); PG8_SCHED; PG8_LDA(At, 0, 0); PG8_STAGE(PG8_SA(1, 1), a1 + hstep, voffA);
;             PG8_WAIT_V(8); PG8_WAIT_L(0); PG8_BAR; PG8_MMA(0, 0, At, B0); PG8_MMA(0, 1, At, B1); PG8_BAR; PG8_SCHED;
;             PG8_LDA(At, 0, 1); PG8_STAGE(PG8_SB(0, 0), b2, voffB); PG8_STAGE(PG8_SB(0, 1), b2 + hstep, voffB); PG8_STAGE(PG8_SA(0, 0), a2, voffA);
;             PG8_WAIT_V(8); PG8_WAIT_L(0); PG8_BAR; PG8_MMA(1, 0, At, B0); PG8_MMA(1, 1, At, B1); PG8_BAR; PG8_SCHED;
.LBB0_229:
	s_ashr_i32 s37, s36, 31
	s_lshl_b64 s[34:35], s[36:37], 21
	s_add_u32 s40, s42, s34
	s_addc_u32 s41, s43, s35
	s_and_b64 s[34:35], s[8:9], exec
	s_cselect_b32 s11, s41, s13
	s_cselect_b32 s34, s40, s12
	s_ashr_i32 s27, s26, 31
	s_lshl_b64 s[50:51], s[26:27], 21
	s_add_u32 s54, s44, s50
	s_addc_u32 s55, s45, s51
	s_and_b64 s[50:51], s[8:9], exec
	s_cselect_b32 s27, s55, s73
	s_cselect_b32 s35, s54, s72
	s_add_u32 s12, s12, 0x100080
	s_addc_u32 s13, s13, 0
	s_add_u32 s37, s72, 0x100
	s_addc_u32 s61, s73, 0
	s_mov_b32 s97, -2
	s_add_u32 s50, s12, 0xfff00080
	s_addc_u32 s51, s13, -1
	s_add_i32 s56, 0, 0x10000
	s_cmp_eq_u32 s97, 60
	s_cselect_b32 s77, s11, s51
	s_cselect_b32 s76, s34, s50
	s_cselect_b32 s73, s27, s61
	s_cselect_b32 s72, s35, s37
	s_add_i32 s57, 0, 0x14000
	v_add_u32_e32 v156, s56, v171
	v_add_u32_e32 v168, s57, v171
	s_waitcnt vmcnt(0)
	ds_read_b128 v[112:115], v156
	ds_read_b128 v[120:123], v156 offset:1024
	ds_read_b128 v[152:155], v156 offset:2048
	ds_read_b128 v[156:159], v156 offset:3072
	ds_read_b128 v[160:163], v168
	ds_read_b128 v[164:167], v168 offset:1024
	s_waitcnt lgkmcnt(0)
	ds_read_b128 v[176:179], v168 offset:2048
	ds_read_b128 v[180:183], v168 offset:3072
	s_add_i32 m0, s47, 0xc000
	ds_read_b128 v[184:187], v173
	ds_read_b128 v[188:191], v173 offset:1024
	ds_read_b128 v[204:207], v173 offset:2048
	ds_read_b128 v[208:211], v173 offset:3072
	ds_read_b128 v[212:215], v173 offset:4096
	ds_read_b128 v[216:219], v173 offset:5120
	ds_read_b128 v[220:223], v173 offset:6144
	ds_read_b128 v[224:227], v173 offset:7168
	global_load_lds_dwordx4 v148, s[12:13]
	s_add_i32 m0, s47, 0xe000
	s_nop 0
	global_load_lds_dwordx4 v150, s[12:13]
	s_waitcnt vmcnt(8)
	s_waitcnt lgkmcnt(0)
	s_barrier
	s_setprio 1
	s_waitcnt lgkmcnt(0)
	v_mfma_f32_16x16x32_bf16 v[136:139], v[112:115], v[184:187], 0
	v_mfma_f32_16x16x32_bf16 v[136:139], v[120:123], v[188:191], v[136:139]
	v_mfma_f32_16x16x32_bf16 v[116:119], v[120:123], v[208:211], 0
	v_mfma_f32_16x16x32_bf16 v[116:119], v[112:115], v[204:207], v[116:119]
	v_mfma_f32_16x16x32_bf16 v[96:99], v[112:115], v[212:215], 0
	v_mfma_f32_16x16x32_bf16 v[96:99], v[120:123], v[216:219], v[96:99]
	v_mfma_f32_16x16x32_bf16 v[80:83], v[120:123], v[224:227], 0
	v_mfma_f32_16x16x32_bf16 v[80:83], v[112:115], v[220:223], v[80:83]
	v_mfma_f32_16x16x32_bf16 v[76:79], v[152:155], v[220:223], 0
	v_mfma_f32_16x16x32_bf16 v[76:79], v[156:159], v[224:227], v[76:79]
	v_mfma_f32_16x16x32_bf16 v[92:95], v[156:159], v[216:219], 0
	v_mfma_f32_16x16x32_bf16 v[92:95], v[152:155], v[212:215], v[92:95]
	v_mfma_f32_16x16x32_bf16 v[108:111], v[152:155], v[204:207], 0
	v_mfma_f32_16x16x32_bf16 v[108:111], v[156:159], v[208:211], v[108:111]
	v_mfma_f32_16x16x32_bf16 v[132:135], v[156:159], v[188:191], 0
	v_mfma_f32_16x16x32_bf16 v[132:135], v[152:155], v[184:187], v[132:135]
	v_mfma_f32_16x16x32_bf16 v[128:131], v[160:163], v[184:187], 0
	v_mfma_f32_16x16x32_bf16 v[128:131], v[164:167], v[188:191], v[128:131]
	v_mfma_f32_16x16x32_bf16 v[104:107], v[164:167], v[208:211], 0
	v_mfma_f32_16x16x32_bf16 v[104:107], v[160:163], v[204:207], v[104:107]
	v_mfma_f32_16x16x32_bf16 v[88:91], v[160:163], v[212:215], 0
	v_mfma_f32_16x16x32_bf16 v[88:91], v[164:167], v[216:219], v[88:91]
	v_mfma_f32_16x16x32_bf16 v[72:75], v[164:167], v[224:227], 0
	v_mfma_f32_16x16x32_bf16 v[72:75], v[160:163], v[220:223], v[72:75]
	v_mfma_f32_16x16x32_bf16 v[68:71], v[176:179], v[220:223], 0
	v_mfma_f32_16x16x32_bf16 v[68:71], v[180:183], v[224:227], v[68:71]
	v_mfma_f32_16x16x32_bf16 v[84:87], v[180:183], v[216:219], 0
	v_mfma_f32_16x16x32_bf16 v[84:87], v[176:179], v[212:215], v[84:87]
	v_mfma_f32_16x16x32_bf16 v[100:103], v[176:179], v[204:207], 0
	v_mfma_f32_16x16x32_bf16 v[100:103], v[180:183], v[208:211], v[100:103]
	v_mfma_f32_16x16x32_bf16 v[124:127], v[180:183], v[188:191], 0
	v_mfma_f32_16x16x32_bf16 v[124:127], v[176:179], v[184:187], v[124:127]
	s_setprio 0
	s_barrier
	s_add_i32 s50, s56, s46
	s_mov_b32 m0, s50
	ds_read_b128 v[184:187], v173 offset:16384
	ds_read_b128 v[188:191], v173 offset:17408
	ds_read_b128 v[204:207], v173 offset:18432
	ds_read_b128 v[208:211], v173 offset:19456
	ds_read_b128 v[212:215], v173 offset:20480
	ds_read_b128 v[216:219], v173 offset:21504
	ds_read_b128 v[220:223], v173 offset:22528
	ds_read_b128 v[224:227], v173 offset:23552
	global_load_lds_dwordx4 v2, s[72:73]
	s_add_i32 m0, s50, 0x2000
	s_add_u32 s50, s72, 0x100000
	s_addc_u32 s51, s73, 0
	s_add_i32 s56, s57, s46
	global_load_lds_dwordx4 v144, s[72:73]
	s_mov_b32 m0, s56
	v_lshl_add_u64 v[242:243], s[76:77], 0, v[142:143]
	global_load_lds_dwordx4 v2, s[50:51]
	s_add_i32 m0, s56, 0x2000
	s_nop 0
	global_load_lds_dwordx4 v144, s[50:51]
	v_lshl_add_u64 v[240:241], s[76:77], 0, v[140:141]
	s_waitcnt vmcnt(6)
	s_waitcnt lgkmcnt(0)
	s_barrier
; #define PG8_STAGE(bufoff, gbase, voff) do { _Pragma("unroll") for (int _i = 0; _i < 2; ++_i) \
;         __builtin_amdgcn_global_load_lds((const unsigned*)((const char*)(gbase) + (voff)[_i]), (PG8_LAS unsigned*)(lds + (bufoff) + ldsw + _i * 8192), 16, 0, 0); } while (0)
; #define PG8_LDA(dst, b, h) do { _Pragma("unroll") for (int m = 0; m < 4; ++m) _Pragma("unroll") for (int k = 0; k < 2; ++k) dst[m][k] = *(const PG8_LAS bf16x8*)(lds + PG8_SA(b, h) + aoff + m * 2048 + k * 1024); } while (0)
; #define PG8_LDB(dst, b, h) do { _Pragma("unroll") for (int n = 0; n < 2; ++n) _Pragma("unroll") for (int k = 0; k < 2; ++k) dst[n][k] = *(const PG8_LAS bf16x8*)(lds + PG8_SB(b, h) + boff + n * 2048 + k * 1024); } while (0)
; #define PG8_WAIT_V(n) asm volatile("s_waitcnt vmcnt(" #n ")" ::: "memory")
; #define PG8_WAIT_L(n) asm volatile("s_waitcnt lgkmcnt(" #n ")" ::: "memory")
; #define PG8_BAR __builtin_amdgcn_s_barrier()
; #define PG8_SCHED __builtin_amdgcn_sched_barrier(0)
; template <class Epi, class Sched, bool ALIGN_EPI = false, bool SP2 = false, bool I8 = false>
; __device__ __forceinline__ void gemm_phase(PG8_LAS unsigned char* lds, const Gemm g, const Sched& S, const Epi& E) {
;     ...
;             PG8_WAIT_V(8); PG8_WAIT_L(0); PG8_BAR; PG8_MMA(1, 0, At, B0); PG8_MMA(1, 1, At, B1); PG8_BAR; PG8_SCHED;
;             PG8_LDB(B0, 1, 0); PG8_LDB(B1, 1, 1); PG8_SCHED; PG8_LDA(At, 1, 0); PG8_STAGE(PG8_SA(0, 1), a2 + hstep, voffA);
;             PG8_WAIT_V(8); PG8_WAIT_L(0); PG8_BAR; PG8_MMA(0, 0, At, B0); PG8_MMA(0, 1, At, B1); PG8_BAR; PG8_SCHED;
;             PG8_LDA(At, 1, 1); PG8_STAGE(PG8_SB(1, 0), b3, voffB); PG8_STAGE(PG8_SB(1, 1), b3 + hstep, voffB); PG8_STAGE(PG8_SA(1, 0), a3, voffA);
;             PG8_WAIT_V(8); PG8_WAIT_L(0); PG8_BAR; PG8_MMA(1, 0, At, B0); PG8_MMA(1, 1, At, B1); PG8_BAR; PG8_SCHED;
	s_setprio 1
	s_waitcnt lgkmcnt(0)
	v_mfma_f32_16x16x32_bf16 v[64:67], v[112:115], v[184:187], 0
	v_mfma_f32_16x16x32_bf16 v[64:67], v[120:123], v[188:191], v[64:67]
	v_mfma_f32_16x16x32_bf16 v[48:51], v[120:123], v[208:211], 0
	v_mfma_f32_16x16x32_bf16 v[48:51], v[112:115], v[204:207], v[48:51]
	v_mfma_f32_16x16x32_bf16 v[32:35], v[112:115], v[212:215], 0
	v_mfma_f32_16x16x32_bf16 v[32:35], v[120:123], v[216:219], v[32:35]
	v_mfma_f32_16x16x32_bf16 v[16:19], v[120:123], v[224:227], 0
	v_mfma_f32_16x16x32_bf16 v[16:19], v[112:115], v[220:223], v[16:19]
	v_mfma_f32_16x16x32_bf16 v[12:15], v[152:155], v[220:223], 0
	v_mfma_f32_16x16x32_bf16 v[12:15], v[156:159], v[224:227], v[12:15]
	v_mfma_f32_16x16x32_bf16 v[28:31], v[156:159], v[216:219], 0
	v_mfma_f32_16x16x32_bf16 v[28:31], v[152:155], v[212:215], v[28:31]
	v_mfma_f32_16x16x32_bf16 v[44:47], v[152:155], v[204:207], 0
	v_mfma_f32_16x16x32_bf16 v[44:47], v[156:159], v[208:211], v[44:47]
	v_mfma_f32_16x16x32_bf16 v[60:63], v[156:159], v[188:191], 0
	v_mfma_f32_16x16x32_bf16 v[60:63], v[152:155], v[184:187], v[60:63]
	v_mfma_f32_16x16x32_bf16 v[56:59], v[160:163], v[184:187], 0
	v_mfma_f32_16x16x32_bf16 v[56:59], v[164:167], v[188:191], v[56:59]
	v_mfma_f32_16x16x32_bf16 v[40:43], v[164:167], v[208:211], 0
	v_mfma_f32_16x16x32_bf16 v[40:43], v[160:163], v[204:207], v[40:43]
	v_mfma_f32_16x16x32_bf16 v[24:27], v[160:163], v[212:215], 0
	v_mfma_f32_16x16x32_bf16 v[24:27], v[164:167], v[216:219], v[24:27]
	v_mfma_f32_16x16x32_bf16 v[8:11], v[164:167], v[224:227], 0
	v_mfma_f32_16x16x32_bf16 v[8:11], v[160:163], v[220:223], v[8:11]
	v_mfma_f32_16x16x32_bf16 v[4:7], v[176:179], v[220:223], 0
	v_mfma_f32_16x16x32_bf16 v[4:7], v[180:183], v[224:227], v[4:7]
	v_mfma_f32_16x16x32_bf16 v[20:23], v[180:183], v[216:219], 0
	v_mfma_f32_16x16x32_bf16 v[20:23], v[176:179], v[212:215], v[20:23]
	v_mfma_f32_16x16x32_bf16 v[36:39], v[176:179], v[204:207], 0
	v_mfma_f32_16x16x32_bf16 v[36:39], v[180:183], v[208:211], v[36:39]
	v_mfma_f32_16x16x32_bf16 v[52:55], v[180:183], v[188:191], 0
	v_mfma_f32_16x16x32_bf16 v[52:55], v[176:179], v[184:187], v[52:55]
	s_setprio 0
	s_barrier
	s_mov_b32 m0, s47
	s_nop 0
	global_load_lds_dwordx4 v[240:241], off
	s_mov_b32 m0, s52
	s_nop 0
	global_load_lds_dwordx4 v[242:243], off
	s_add_i32 s56, 0, 0x18000
	s_add_i32 s57, 0, 0x1c000
	v_add_u32_e32 v156, s56, v171
	v_add_u32_e32 v175, s57, v171
	ds_read_b128 v[112:115], v156
	ds_read_b128 v[120:123], v156 offset:1024
	ds_read_b128 v[152:155], v156 offset:2048
	ds_read_b128 v[156:159], v156 offset:3072
	ds_read_b128 v[160:163], v175
	ds_read_b128 v[164:167], v175 offset:1024
	ds_read_b128 v[176:179], v175 offset:2048
	ds_read_b128 v[180:183], v175 offset:3072
	s_add_u32 s50, s76, 0x100000
	s_addc_u32 s51, s77, 0
	s_mov_b32 m0, s53
	ds_read_b128 v[184:187], v173 offset:32768
	ds_read_b128 v[188:191], v173 offset:33792
	ds_read_b128 v[204:207], v173 offset:34816
	ds_read_b128 v[208:211], v173 offset:35840
	ds_read_b128 v[212:215], v173 offset:36864
	ds_read_b128 v[216:219], v173 offset:37888
	ds_read_b128 v[220:223], v173 offset:38912
	ds_read_b128 v[224:227], v173 offset:39936
	global_load_lds_dwordx4 v140, s[50:51]
	s_mov_b32 m0, s64
	s_nop 0
	global_load_lds_dwordx4 v142, s[50:51]
	s_waitcnt vmcnt(8)
	s_waitcnt lgkmcnt(0)
	s_barrier
	s_setprio 1
	s_waitcnt lgkmcnt(0)
	v_mfma_f32_16x16x32_bf16 v[136:139], v[112:115], v[184:187], v[136:139]
	v_mfma_f32_16x16x32_bf16 v[136:139], v[120:123], v[188:191], v[136:139]
	v_mfma_f32_16x16x32_bf16 v[116:119], v[120:123], v[208:211], v[116:119]
	v_mfma_f32_16x16x32_bf16 v[116:119], v[112:115], v[204:207], v[116:119]
	v_mfma_f32_16x16x32_bf16 v[96:99], v[112:115], v[212:215], v[96:99]
	v_mfma_f32_16x16x32_bf16 v[96:99], v[120:123], v[216:219], v[96:99]
	v_mfma_f32_16x16x32_bf16 v[80:83], v[120:123], v[224:227], v[80:83]
	v_mfma_f32_16x16x32_bf16 v[80:83], v[112:115], v[220:223], v[80:83]
	v_mfma_f32_16x16x32_bf16 v[76:79], v[152:155], v[220:223], v[76:79]
	v_mfma_f32_16x16x32_bf16 v[76:79], v[156:159], v[224:227], v[76:79]
	v_mfma_f32_16x16x32_bf16 v[92:95], v[156:159], v[216:219], v[92:95]
	v_mfma_f32_16x16x32_bf16 v[92:95], v[152:155], v[212:215], v[92:95]
	v_mfma_f32_16x16x32_bf16 v[108:111], v[152:155], v[204:207], v[108:111]
	v_mfma_f32_16x16x32_bf16 v[108:111], v[156:159], v[208:211], v[108:111]
	v_mfma_f32_16x16x32_bf16 v[132:135], v[156:159], v[188:191], v[132:135]
	v_mfma_f32_16x16x32_bf16 v[132:135], v[152:155], v[184:187], v[132:135]
	v_mfma_f32_16x16x32_bf16 v[128:131], v[160:163], v[184:187], v[128:131]
	v_mfma_f32_16x16x32_bf16 v[128:131], v[164:167], v[188:191], v[128:131]
	v_mfma_f32_16x16x32_bf16 v[104:107], v[164:167], v[208:211], v[104:107]
	v_mfma_f32_16x16x32_bf16 v[104:107], v[160:163], v[204:207], v[104:107]
	v_mfma_f32_16x16x32_bf16 v[88:91], v[160:163], v[212:215], v[88:91]
	v_mfma_f32_16x16x32_bf16 v[88:91], v[164:167], v[216:219], v[88:91]
	v_mfma_f32_16x16x32_bf16 v[72:75], v[164:167], v[224:227], v[72:75]
	v_mfma_f32_16x16x32_bf16 v[72:75], v[160:163], v[220:223], v[72:75]
	v_mfma_f32_16x16x32_bf16 v[68:71], v[176:179], v[220:223], v[68:71]
	v_mfma_f32_16x16x32_bf16 v[68:71], v[180:183], v[224:227], v[68:71]
	v_mfma_f32_16x16x32_bf16 v[84:87], v[180:183], v[216:219], v[84:87]
	v_mfma_f32_16x16x32_bf16 v[84:87], v[176:179], v[212:215], v[84:87]
	v_mfma_f32_16x16x32_bf16 v[100:103], v[176:179], v[204:207], v[100:103]
	v_mfma_f32_16x16x32_bf16 v[100:103], v[180:183], v[208:211], v[100:103]
	v_mfma_f32_16x16x32_bf16 v[124:127], v[180:183], v[188:191], v[124:127]
	v_mfma_f32_16x16x32_bf16 v[124:127], v[176:179], v[184:187], v[124:127]
	s_setprio 0
	s_barrier
	s_add_u32 s98, s72, 0x80
	s_addc_u32 s99, s73, 0
	s_add_i32 s50, s56, s46
	s_mov_b32 m0, s50
	ds_read_b128 v[184:187], v173 offset:49152
	ds_read_b128 v[188:191], v173 offset:50176
	ds_read_b128 v[204:207], v173 offset:51200
	ds_read_b128 v[208:211], v173 offset:52224
	ds_read_b128 v[212:215], v173 offset:53248
	ds_read_b128 v[216:219], v173 offset:54272
	ds_read_b128 v[220:223], v173 offset:55296
	ds_read_b128 v[224:227], v173 offset:56320
	global_load_lds_dwordx4 v2, s[98:99]
	s_add_i32 m0, s50, 0x2000
	s_add_u32 s50, s72, 0x100080
	s_addc_u32 s51, s73, 0
	s_add_i32 s56, s57, s46
	global_load_lds_dwordx4 v144, s[98:99]
	s_mov_b32 m0, s56
	s_nop 0
	global_load_lds_dwordx4 v2, s[50:51]
	s_add_i32 m0, s56, 0x2000
	s_nop 0
	global_load_lds_dwordx4 v144, s[50:51]
	s_cmp_eq_u32 s97, 60
	s_cbranch_scc0 .Ldefer_230_peel
	v_lshl_add_u64 v[168:169], v[240:241], 0, s[84:85]
	s_mov_b32 m0, s28
	s_nop 0
	global_load_lds_dwordx4 v[168:169], off
	v_lshl_add_u64 v[168:169], v[242:243], 0, s[84:85]
	s_mov_b32 m0, s65
	s_nop 0
	global_load_lds_dwordx4 v[168:169], off

; #define PG8_STAGE(bufoff, gbase, voff) do { _Pragma("unroll") for (int _i = 0; _i < 2; ++_i) \
;         __builtin_amdgcn_global_load_lds((const unsigned*)((const char*)(gbase) + (voff)[_i]), (PG8_LAS unsigned*)(lds + (bufoff) + ldsw + _i * 8192), 16, 0, 0); } while (0)
; #define PG8_LDA(dst, b, h) do { _Pragma("unroll") for (int m = 0; m < 4; ++m) _Pragma("unroll") for (int k = 0; k < 2; ++k) dst[m][k] = *(const PG8_LAS bf16x8*)(lds + PG8_SA(b, h) + aoff + m * 2048 + k * 1024); } while (0)
; #define PG8_LDB(dst, b, h) do { _Pragma("unroll") for (int n = 0; n < 2; ++n) _Pragma("unroll") for (int k = 0; k < 2; ++k) dst[n][k] = *(const PG8_LAS bf16x8*)(lds + PG8_SB(b, h) + boff + n * 2048 + k * 1024); } while (0)
; #define PG8_WAIT_V(n) asm volatile("s_waitcnt vmcnt(" #n ")" ::: "memory")
; #define PG8_WAIT_L(n) asm volatile("s_waitcnt lgkmcnt(" #n ")" ::: "memory")
; #define PG8_BAR __builtin_amdgcn_s_barrier()
; #define PG8_SCHED __builtin_amdgcn_sched_barrier(0)
; template <class Epi, class Sched, bool ALIGN_EPI = false, bool SP2 = false, bool I8 = false>
; __device__ __forceinline__ void gemm_phase(PG8_LAS unsigned char* lds, const Gemm g, const Sched& S, const Epi& E) {
;     ...
;         for (int t = 0; t < nt; t += 2) {
;             const bool last = (t == nt - 2);
;             const char* a1 = cA + (size_t)(t + 1) * kstep;
;             const char* a2 = last ? nA : cA + (size_t)(t + 2) * kstep; const char* b2 = last ? nB : cB + (size_t)(t + 2) * kstep;
;             const char* a3 = a2 + kstep; const char* b3 = b2 + kstep;
;             if (last && has_next) S.a_ready(nxt);
;             if constexpr (SP2) {
;             PG8_LDB(B0, 0, 0); PG8_LDB(B1, 0, 1); PG8_SCHED; PG8_LDA(At, 0, 0); PG8_STAGE(PG8_SA(1, 1), a1 + hstep, voffA);
;             PG8_WAIT_V(8); PG8_WAIT_L(0); PG8_BAR; PG8_MMA(0, 0, At, B0); PG8_MMA(0, 1, At, B1); PG8_BAR; PG8_SCHED;
;             PG8_LDA(At, 0, 1); PG8_STAGE(PG8_SB(0, 0), b2, voffB); PG8_STAGE(PG8_SB(0, 1), b2 + hstep, voffB); PG8_STAGE(PG8_SA(0, 0), a2, voffA);
;             PG8_WAIT_V(8); PG8_WAIT_L(0); PG8_BAR; PG8_MMA(1, 0, At, B0); PG8_MMA(1, 1, At, B1); PG8_BAR; PG8_SCHED;
.LBB0_230:
	s_add_u32 s50, s12, 0xfff00080
	s_addc_u32 s51, s13, -1
	s_add_i32 s56, 0, 0x10000
	s_cmp_eq_u32 s97, 60
	s_cselect_b32 s77, s11, s51
	s_cselect_b32 s76, s34, s50
	s_cselect_b32 s73, s27, s61
	s_cselect_b32 s72, s35, s37
	s_add_i32 s57, 0, 0x14000
	v_add_u32_e32 v156, s56, v171
	v_add_u32_e32 v168, s57, v171
	ds_read_b128 v[112:115], v156
	ds_read_b128 v[120:123], v156 offset:1024
	ds_read_b128 v[152:155], v156 offset:2048
	ds_read_b128 v[156:159], v156 offset:3072
	ds_read_b128 v[160:163], v168
	ds_read_b128 v[164:167], v168 offset:1024
	ds_read_b128 v[176:179], v168 offset:2048
	ds_read_b128 v[180:183], v168 offset:3072
	v_lshl_add_u64 v[168:169], v[240:241], 0, s[84:85]
	s_mov_b32 m0, s28
	s_nop 0
	global_load_lds_dwordx4 v[168:169], off
	v_lshl_add_u64 v[168:169], v[242:243], 0, s[84:85]
	s_mov_b32 m0, s65
	s_nop 0
	global_load_lds_dwordx4 v[168:169], off
	s_add_i32 m0, s47, 0xc000
	ds_read_b128 v[184:187], v173
	ds_read_b128 v[188:191], v173 offset:1024
	ds_read_b128 v[204:207], v173 offset:2048
	ds_read_b128 v[208:211], v173 offset:3072
	ds_read_b128 v[212:215], v173 offset:4096
	ds_read_b128 v[216:219], v173 offset:5120
	ds_read_b128 v[220:223], v173 offset:6144
	ds_read_b128 v[224:227], v173 offset:7168
	global_load_lds_dwordx4 v148, s[12:13]
	s_add_i32 m0, s47, 0xe000
	s_nop 0
	global_load_lds_dwordx4 v150, s[12:13]
	s_waitcnt vmcnt(8)
	s_waitcnt lgkmcnt(0)
	s_barrier
	s_setprio 1
	s_waitcnt lgkmcnt(0)
	v_mfma_f32_16x16x32_bf16 v[136:139], v[112:115], v[184:187], v[136:139]
	v_mfma_f32_16x16x32_bf16 v[136:139], v[120:123], v[188:191], v[136:139]
	v_mfma_f32_16x16x32_bf16 v[116:119], v[120:123], v[208:211], v[116:119]
	v_mfma_f32_16x16x32_bf16 v[116:119], v[112:115], v[204:207], v[116:119]
	v_mfma_f32_16x16x32_bf16 v[96:99], v[112:115], v[212:215], v[96:99]
	v_mfma_f32_16x16x32_bf16 v[96:99], v[120:123], v[216:219], v[96:99]
	v_mfma_f32_16x16x32_bf16 v[80:83], v[120:123], v[224:227], v[80:83]
	v_mfma_f32_16x16x32_bf16 v[80:83], v[112:115], v[220:223], v[80:83]
	v_mfma_f32_16x16x32_bf16 v[76:79], v[152:155], v[220:223], v[76:79]
	v_mfma_f32_16x16x32_bf16 v[76:79], v[156:159], v[224:227], v[76:79]
	v_mfma_f32_16x16x32_bf16 v[92:95], v[156:159], v[216:219], v[92:95]
	v_mfma_f32_16x16x32_bf16 v[92:95], v[152:155], v[212:215], v[92:95]
	v_mfma_f32_16x16x32_bf16 v[108:111], v[152:155], v[204:207], v[108:111]
	v_mfma_f32_16x16x32_bf16 v[108:111], v[156:159], v[208:211], v[108:111]
	v_mfma_f32_16x16x32_bf16 v[132:135], v[156:159], v[188:191], v[132:135]
	v_mfma_f32_16x16x32_bf16 v[132:135], v[152:155], v[184:187], v[132:135]
	v_mfma_f32_16x16x32_bf16 v[128:131], v[160:163], v[184:187], v[128:131]
	v_mfma_f32_16x16x32_bf16 v[128:131], v[164:167], v[188:191], v[128:131]
	v_mfma_f32_16x16x32_bf16 v[104:107], v[164:167], v[208:211], v[104:107]
	v_mfma_f32_16x16x32_bf16 v[104:107], v[160:163], v[204:207], v[104:107]
	v_mfma_f32_16x16x32_bf16 v[88:91], v[160:163], v[212:215], v[88:91]
	v_mfma_f32_16x16x32_bf16 v[88:91], v[164:167], v[216:219], v[88:91]
	v_mfma_f32_16x16x32_bf16 v[72:75], v[164:167], v[224:227], v[72:75]
	v_mfma_f32_16x16x32_bf16 v[72:75], v[160:163], v[220:223], v[72:75]
	v_mfma_f32_16x16x32_bf16 v[68:71], v[176:179], v[220:223], v[68:71]
	v_mfma_f32_16x16x32_bf16 v[68:71], v[180:183], v[224:227], v[68:71]
	v_mfma_f32_16x16x32_bf16 v[84:87], v[180:183], v[216:219], v[84:87]
	v_mfma_f32_16x16x32_bf16 v[84:87], v[176:179], v[212:215], v[84:87]
	v_mfma_f32_16x16x32_bf16 v[100:103], v[176:179], v[204:207], v[100:103]
	v_mfma_f32_16x16x32_bf16 v[100:103], v[180:183], v[208:211], v[100:103]
	v_mfma_f32_16x16x32_bf16 v[124:127], v[180:183], v[188:191], v[124:127]
	v_mfma_f32_16x16x32_bf16 v[124:127], v[176:179], v[184:187], v[124:127]
	s_setprio 0
	s_barrier
	s_add_i32 s50, s56, s46
	s_mov_b32 m0, s50
	ds_read_b128 v[184:187], v173 offset:16384
	ds_read_b128 v[188:191], v173 offset:17408
	ds_read_b128 v[204:207], v173 offset:18432
	ds_read_b128 v[208:211], v173 offset:19456
	ds_read_b128 v[212:215], v173 offset:20480
	ds_read_b128 v[216:219], v173 offset:21504
	ds_read_b128 v[220:223], v173 offset:22528
	ds_read_b128 v[224:227], v173 offset:23552
	global_load_lds_dwordx4 v2, s[72:73]
	s_add_i32 m0, s50, 0x2000
	s_add_u32 s50, s72, 0x100000
	s_addc_u32 s51, s73, 0
	s_add_i32 s56, s57, s46
	global_load_lds_dwordx4 v144, s[72:73]
	s_mov_b32 m0, s56
	v_lshl_add_u64 v[242:243], s[76:77], 0, v[142:143]
	global_load_lds_dwordx4 v2, s[50:51]
	s_add_i32 m0, s56, 0x2000
	s_nop 0
	global_load_lds_dwordx4 v144, s[50:51]
	v_lshl_add_u64 v[240:241], s[76:77], 0, v[140:141]
	s_waitcnt vmcnt(6)
	s_waitcnt lgkmcnt(0)
	s_barrier
; #define PG8_STAGE(bufoff, gbase, voff) do { _Pragma("unroll") for (int _i = 0; _i < 2; ++_i) \
;         __builtin_amdgcn_global_load_lds((const unsigned*)((const char*)(gbase) + (voff)[_i]), (PG8_LAS unsigned*)(lds + (bufoff) + ldsw + _i * 8192), 16, 0, 0); } while (0)
; #define PG8_LDA(dst, b, h) do { _Pragma("unroll") for (int m = 0; m < 4; ++m) _Pragma("unroll") for (int k = 0; k < 2; ++k) dst[m][k] = *(const PG8_LAS bf16x8*)(lds + PG8_SA(b, h) + aoff + m * 2048 + k * 1024); } while (0)
; #define PG8_LDB(dst, b, h) do { _Pragma("unroll") for (int n = 0; n < 2; ++n) _Pragma("unroll") for (int k = 0; k < 2; ++k) dst[n][k] = *(const PG8_LAS bf16x8*)(lds + PG8_SB(b, h) + boff + n * 2048 + k * 1024); } while (0)
; #define PG8_WAIT_V(n) asm volatile("s_waitcnt vmcnt(" #n ")" ::: "memory")
; #define PG8_WAIT_L(n) asm volatile("s_waitcnt lgkmcnt(" #n ")" ::: "memory")
; #define PG8_BAR __builtin_amdgcn_s_barrier()
; #define PG8_SCHED __builtin_amdgcn_sched_barrier(0)
; template <class Epi, class Sched, bool ALIGN_EPI = false, bool SP2 = false, bool I8 = false>
; __device__ __forceinline__ void gemm_phase(PG8_LAS unsigned char* lds, const Gemm g, const Sched& S, const Epi& E) {
;     ...
;             PG8_WAIT_V(8); PG8_WAIT_L(0); PG8_BAR; PG8_MMA(1, 0, At, B0); PG8_MMA(1, 1, At, B1); PG8_BAR; PG8_SCHED;
;             PG8_LDB(B0, 1, 0); PG8_LDB(B1, 1, 1); PG8_SCHED; PG8_LDA(At, 1, 0); PG8_STAGE(PG8_SA(0, 1), a2 + hstep, voffA);
;             PG8_WAIT_V(8); PG8_WAIT_L(0); PG8_BAR; PG8_MMA(0, 0, At, B0); PG8_MMA(0, 1, At, B1); PG8_BAR; PG8_SCHED;
;             PG8_LDA(At, 1, 1); PG8_STAGE(PG8_SB(1, 0), b3, voffB); PG8_STAGE(PG8_SB(1, 1), b3 + hstep, voffB); PG8_STAGE(PG8_SA(1, 0), a3, voffA);
;             PG8_WAIT_V(8); PG8_WAIT_L(0); PG8_BAR; PG8_MMA(1, 0, At, B0); PG8_MMA(1, 1, At, B1); PG8_BAR; PG8_SCHED;
	s_setprio 1
	s_waitcnt lgkmcnt(0)
	v_mfma_f32_16x16x32_bf16 v[64:67], v[112:115], v[184:187], v[64:67]
	v_mfma_f32_16x16x32_bf16 v[64:67], v[120:123], v[188:191], v[64:67]
	v_mfma_f32_16x16x32_bf16 v[48:51], v[120:123], v[208:211], v[48:51]
	v_mfma_f32_16x16x32_bf16 v[48:51], v[112:115], v[204:207], v[48:51]
	v_mfma_f32_16x16x32_bf16 v[32:35], v[112:115], v[212:215], v[32:35]
	v_mfma_f32_16x16x32_bf16 v[32:35], v[120:123], v[216:219], v[32:35]
	v_mfma_f32_16x16x32_bf16 v[16:19], v[120:123], v[224:227], v[16:19]
	v_mfma_f32_16x16x32_bf16 v[16:19], v[112:115], v[220:223], v[16:19]
	v_mfma_f32_16x16x32_bf16 v[12:15], v[152:155], v[220:223], v[12:15]
	v_mfma_f32_16x16x32_bf16 v[12:15], v[156:159], v[224:227], v[12:15]
	v_mfma_f32_16x16x32_bf16 v[28:31], v[156:159], v[216:219], v[28:31]
	v_mfma_f32_16x16x32_bf16 v[28:31], v[152:155], v[212:215], v[28:31]
	v_mfma_f32_16x16x32_bf16 v[44:47], v[152:155], v[204:207], v[44:47]
	v_mfma_f32_16x16x32_bf16 v[44:47], v[156:159], v[208:211], v[44:47]
	v_mfma_f32_16x16x32_bf16 v[60:63], v[156:159], v[188:191], v[60:63]
	v_mfma_f32_16x16x32_bf16 v[60:63], v[152:155], v[184:187], v[60:63]
	v_mfma_f32_16x16x32_bf16 v[56:59], v[160:163], v[184:187], v[56:59]
	v_mfma_f32_16x16x32_bf16 v[56:59], v[164:167], v[188:191], v[56:59]
	v_mfma_f32_16x16x32_bf16 v[40:43], v[164:167], v[208:211], v[40:43]
	v_mfma_f32_16x16x32_bf16 v[40:43], v[160:163], v[204:207], v[40:43]
	v_mfma_f32_16x16x32_bf16 v[24:27], v[160:163], v[212:215], v[24:27]
	v_mfma_f32_16x16x32_bf16 v[24:27], v[164:167], v[216:219], v[24:27]
	v_mfma_f32_16x16x32_bf16 v[8:11], v[164:167], v[224:227], v[8:11]
	v_mfma_f32_16x16x32_bf16 v[8:11], v[160:163], v[220:223], v[8:11]
	v_mfma_f32_16x16x32_bf16 v[4:7], v[176:179], v[220:223], v[4:7]
	v_mfma_f32_16x16x32_bf16 v[4:7], v[180:183], v[224:227], v[4:7]
	v_mfma_f32_16x16x32_bf16 v[20:23], v[180:183], v[216:219], v[20:23]
	v_mfma_f32_16x16x32_bf16 v[20:23], v[176:179], v[212:215], v[20:23]
	v_mfma_f32_16x16x32_bf16 v[36:39], v[176:179], v[204:207], v[36:39]
	v_mfma_f32_16x16x32_bf16 v[36:39], v[180:183], v[208:211], v[36:39]
	v_mfma_f32_16x16x32_bf16 v[52:55], v[180:183], v[188:191], v[52:55]
	v_mfma_f32_16x16x32_bf16 v[52:55], v[176:179], v[184:187], v[52:55]
	s_setprio 0
	s_barrier
	s_mov_b32 m0, s47
	s_nop 0
	global_load_lds_dwordx4 v[240:241], off
	s_mov_b32 m0, s52
	s_nop 0
	global_load_lds_dwordx4 v[242:243], off
	s_add_i32 s56, 0, 0x18000
	s_add_i32 s57, 0, 0x1c000
	v_add_u32_e32 v156, s56, v171
	v_add_u32_e32 v175, s57, v171
	ds_read_b128 v[112:115], v156
	ds_read_b128 v[120:123], v156 offset:1024
	ds_read_b128 v[152:155], v156 offset:2048
	ds_read_b128 v[156:159], v156 offset:3072
	ds_read_b128 v[160:163], v175
	ds_read_b128 v[164:167], v175 offset:1024
	ds_read_b128 v[176:179], v175 offset:2048
	ds_read_b128 v[180:183], v175 offset:3072
	s_add_u32 s50, s76, 0x100000
	s_addc_u32 s51, s77, 0
	s_mov_b32 m0, s53
	ds_read_b128 v[184:187], v173 offset:32768
	ds_read_b128 v[188:191], v173 offset:33792
	ds_read_b128 v[204:207], v173 offset:34816
	ds_read_b128 v[208:211], v173 offset:35840
	ds_read_b128 v[212:215], v173 offset:36864
	ds_read_b128 v[216:219], v173 offset:37888
	ds_read_b128 v[220:223], v173 offset:38912
	ds_read_b128 v[224:227], v173 offset:39936
	global_load_lds_dwordx4 v140, s[50:51]
	s_mov_b32 m0, s64
	s_nop 0
	global_load_lds_dwordx4 v142, s[50:51]
	s_waitcnt vmcnt(8)
	s_waitcnt lgkmcnt(0)
	s_barrier
	s_setprio 1
	s_waitcnt lgkmcnt(0)
	v_mfma_f32_16x16x32_bf16 v[136:139], v[112:115], v[184:187], v[136:139]
	v_mfma_f32_16x16x32_bf16 v[136:139], v[120:123], v[188:191], v[136:139]
	v_mfma_f32_16x16x32_bf16 v[116:119], v[120:123], v[208:211], v[116:119]
	v_mfma_f32_16x16x32_bf16 v[116:119], v[112:115], v[204:207], v[116:119]
	v_mfma_f32_16x16x32_bf16 v[96:99], v[112:115], v[212:215], v[96:99]
	v_mfma_f32_16x16x32_bf16 v[96:99], v[120:123], v[216:219], v[96:99]
	v_mfma_f32_16x16x32_bf16 v[80:83], v[120:123], v[224:227], v[80:83]
	v_mfma_f32_16x16x32_bf16 v[80:83], v[112:115], v[220:223], v[80:83]
	v_mfma_f32_16x16x32_bf16 v[76:79], v[152:155], v[220:223], v[76:79]
	v_mfma_f32_16x16x32_bf16 v[76:79], v[156:159], v[224:227], v[76:79]
	v_mfma_f32_16x16x32_bf16 v[92:95], v[156:159], v[216:219], v[92:95]
	v_mfma_f32_16x16x32_bf16 v[92:95], v[152:155], v[212:215], v[92:95]
	v_mfma_f32_16x16x32_bf16 v[108:111], v[152:155], v[204:207], v[108:111]
	v_mfma_f32_16x16x32_bf16 v[108:111], v[156:159], v[208:211], v[108:111]
	v_mfma_f32_16x16x32_bf16 v[132:135], v[156:159], v[188:191], v[132:135]
	v_mfma_f32_16x16x32_bf16 v[132:135], v[152:155], v[184:187], v[132:135]
	v_mfma_f32_16x16x32_bf16 v[128:131], v[160:163], v[184:187], v[128:131]
	v_mfma_f32_16x16x32_bf16 v[128:131], v[164:167], v[188:191], v[128:131]
	v_mfma_f32_16x16x32_bf16 v[104:107], v[164:167], v[208:211], v[104:107]
	v_mfma_f32_16x16x32_bf16 v[104:107], v[160:163], v[204:207], v[104:107]
	v_mfma_f32_16x16x32_bf16 v[88:91], v[160:163], v[212:215], v[88:91]
	v_mfma_f32_16x16x32_bf16 v[88:91], v[164:167], v[216:219], v[88:91]
	v_mfma_f32_16x16x32_bf16 v[72:75], v[164:167], v[224:227], v[72:75]
	v_mfma_f32_16x16x32_bf16 v[72:75], v[160:163], v[220:223], v[72:75]
	v_mfma_f32_16x16x32_bf16 v[68:71], v[176:179], v[220:223], v[68:71]
	v_mfma_f32_16x16x32_bf16 v[68:71], v[180:183], v[224:227], v[68:71]
	v_mfma_f32_16x16x32_bf16 v[84:87], v[180:183], v[216:219], v[84:87]
	v_mfma_f32_16x16x32_bf16 v[84:87], v[176:179], v[212:215], v[84:87]
	v_mfma_f32_16x16x32_bf16 v[100:103], v[176:179], v[204:207], v[100:103]
	v_mfma_f32_16x16x32_bf16 v[100:103], v[180:183], v[208:211], v[100:103]
	v_mfma_f32_16x16x32_bf16 v[124:127], v[180:183], v[188:191], v[124:127]
	v_mfma_f32_16x16x32_bf16 v[124:127], v[176:179], v[184:187], v[124:127]
	s_setprio 0
	s_barrier
	s_add_u32 s98, s72, 0x80
	s_addc_u32 s99, s73, 0
	s_add_i32 s50, s56, s46
	s_mov_b32 m0, s50
	ds_read_b128 v[184:187], v173 offset:49152
	ds_read_b128 v[188:191], v173 offset:50176
	ds_read_b128 v[204:207], v173 offset:51200
	ds_read_b128 v[208:211], v173 offset:52224
	ds_read_b128 v[212:215], v173 offset:53248
	ds_read_b128 v[216:219], v173 offset:54272
	ds_read_b128 v[220:223], v173 offset:55296
	ds_read_b128 v[224:227], v173 offset:56320
	global_load_lds_dwordx4 v2, s[98:99]
	s_add_i32 m0, s50, 0x2000
	s_add_u32 s50, s72, 0x100080
	s_addc_u32 s51, s73, 0
	s_add_i32 s56, s57, s46
	global_load_lds_dwordx4 v144, s[98:99]
	s_mov_b32 m0, s56
	s_nop 0
	global_load_lds_dwordx4 v2, s[50:51]
	s_add_i32 m0, s56, 0x2000
	s_nop 0
	global_load_lds_dwordx4 v144, s[50:51]
	s_cmp_eq_u32 s97, 60
	s_cbranch_scc0 .Ldefer_230_body
	v_lshl_add_u64 v[168:169], v[240:241], 0, s[84:85]
	s_mov_b32 m0, s28
	s_nop 0
	global_load_lds_dwordx4 v[168:169], off
	v_lshl_add_u64 v[168:169], v[242:243], 0, s[84:85]
	s_mov_b32 m0, s65
	s_nop 0
	global_load_lds_dwordx4 v[168:169], off

; #define PG8_STAGE(bufoff, gbase, voff) do { _Pragma("unroll") for (int _i = 0; _i < 2; ++_i) \
;         __builtin_amdgcn_global_load_lds((const unsigned*)((const char*)(gbase) + (voff)[_i]), (PG8_LAS unsigned*)(lds + (bufoff) + ldsw + _i * 8192), 16, 0, 0); } while (0)
; #define PG8_LDA(dst, b, h) do { _Pragma("unroll") for (int m = 0; m < 4; ++m) _Pragma("unroll") for (int k = 0; k < 2; ++k) dst[m][k] = *(const PG8_LAS bf16x8*)(lds + PG8_SA(b, h) + aoff + m * 2048 + k * 1024); } while (0)
; #define PG8_LDB(dst, b, h) do { _Pragma("unroll") for (int n = 0; n < 2; ++n) _Pragma("unroll") for (int k = 0; k < 2; ++k) dst[n][k] = *(const PG8_LAS bf16x8*)(lds + PG8_SB(b, h) + boff + n * 2048 + k * 1024); } while (0)
; #define PG8_WAIT_V(n) asm volatile("s_waitcnt vmcnt(" #n ")" ::: "memory")
; #define PG8_WAIT_L(n) asm volatile("s_waitcnt lgkmcnt(" #n ")" ::: "memory")
; #define PG8_BAR __builtin_amdgcn_s_barrier()
; #define PG8_SCHED __builtin_amdgcn_sched_barrier(0)
; template <class Epi, class Sched, bool ALIGN_EPI = false, bool SP2 = false, bool I8 = false>
; __device__ __forceinline__ void gemm_phase(PG8_LAS unsigned char* lds, const Gemm g, const Sched& S, const Epi& E) {
;     ...
;         const bool has_next = S.next(ui + 1, nxt);
;         const char* nA = has_next ? (const char*)g.A + (size_t)nxt.pm * tstep : cA; const char* nB = has_next ? (const char*)g.Bt + (size_t)nxt.pn * tstep : cB;
;         for (int t = 0; t < nt; t += 2) {
;             const bool last = (t == nt - 2);
;             const char* a1 = cA + (size_t)(t + 1) * kstep;
;             const char* a2 = last ? nA : cA + (size_t)(t + 2) * kstep; const char* b2 = last ? nB : cB + (size_t)(t + 2) * kstep;
;             const char* a3 = a2 + kstep; const char* b3 = b2 + kstep;
;             if (last && has_next) S.a_ready(nxt);
;             if constexpr (SP2) {
;             PG8_LDB(B0, 0, 0); PG8_LDB(B1, 0, 1); PG8_SCHED; PG8_LDA(At, 0, 0); PG8_STAGE(PG8_SA(1, 1), a1 + hstep, voffA);
;             PG8_WAIT_V(8); PG8_WAIT_L(0); PG8_BAR; PG8_MMA(0, 0, At, B0); PG8_MMA(0, 1, At, B1); PG8_BAR; PG8_SCHED;
;             PG8_LDA(At, 0, 1); PG8_STAGE(PG8_SB(0, 0), b2, voffB); PG8_STAGE(PG8_SB(0, 1), b2 + hstep, voffB); PG8_STAGE(PG8_SA(0, 0), a2, voffA);
;             PG8_WAIT_V(8); PG8_WAIT_L(0); PG8_BAR; PG8_MMA(1, 0, At, B0); PG8_MMA(1, 1, At, B1); PG8_BAR; PG8_SCHED;
.LBB0_1455:
	s_ashr_i32 s17, s16, 31
	s_lshl_b64 s[20:21], s[16:17], 21
	s_add_u32 s20, s28, s20
	s_addc_u32 s21, s34, s21
	s_and_b64 s[22:23], s[8:9], exec
	s_cselect_b32 s17, s21, s25
	s_cselect_b32 s51, s20, s24
	s_ashr_i32 s19, s18, 31
	s_lshl_b64 s[22:23], s[18:19], 21
	s_add_u32 s22, s35, s22
	s_addc_u32 s23, s39, s23
	s_and_b64 s[36:37], s[8:9], exec
	s_cselect_b32 s19, s23, s27
	s_cselect_b32 s52, s22, s26
	s_add_u32 s24, s24, 0x100080
	s_addc_u32 s25, s25, 0
	s_add_u32 s53, s26, 0x100
	s_addc_u32 s54, s27, 0
	s_mov_b32 s55, -2
	s_waitcnt vmcnt(0)
	s_add_u32 s26, s24, 0xfff00080
	s_addc_u32 s27, s25, -1
	s_add_i32 s56, 0, 0x10000
	s_cmp_eq_u32 s55, 60
	s_cselect_b32 s37, s17, s27
	s_cselect_b32 s36, s51, s26
	s_cselect_b32 s27, s19, s54
	s_cselect_b32 s26, s52, s53
	s_add_i32 s58, 0, 0x14000
	v_add_u32_e32 v144, s56, v240
	v_add_u32_e32 v160, s58, v240
	ds_read_b128 v[124:127], v144
	ds_read_b128 v[128:131], v144 offset:1024
	ds_read_b128 v[132:135], v144 offset:2048
	ds_read_b128 v[144:147], v144 offset:3072
	ds_read_b128 v[148:151], v160
	ds_read_b128 v[152:155], v160 offset:1024
	ds_read_b128 v[156:159], v160 offset:2048
	ds_read_b128 v[160:163], v160 offset:3072
	s_add_i32 m0, s41, 0xc000
	ds_read_b128 v[164:167], v242
	ds_read_b128 v[168:171], v242 offset:1024
	ds_read_b128 v[172:175], v242 offset:2048
	ds_read_b128 v[176:179], v242 offset:3072
	ds_read_b128 v[180:183], v242 offset:4096
	ds_read_b128 v[184:187], v242 offset:5120
	ds_read_b128 v[188:191], v242 offset:6144
	ds_read_b128 v[214:217], v242 offset:7168
	global_load_lds_dwordx4 v210, s[24:25]
	s_add_i32 m0, s41, 0xe000
	s_nop 0
	global_load_lds_dwordx4 v212, s[24:25]
	s_waitcnt vmcnt(8)
	s_waitcnt lgkmcnt(0)
	s_barrier
	s_setprio 1
	s_waitcnt lgkmcnt(0)
	v_mfma_f32_16x16x32_bf16 v[140:143], v[124:127], v[164:167], 0
	v_mfma_f32_16x16x32_bf16 v[140:143], v[128:131], v[168:171], v[140:143]
	v_mfma_f32_16x16x32_bf16 v[112:115], v[128:131], v[176:179], 0
	v_mfma_f32_16x16x32_bf16 v[112:115], v[124:127], v[172:175], v[112:115]
	v_mfma_f32_16x16x32_bf16 v[96:99], v[124:127], v[180:183], 0
	v_mfma_f32_16x16x32_bf16 v[96:99], v[128:131], v[184:187], v[96:99]
	v_mfma_f32_16x16x32_bf16 v[80:83], v[128:131], v[214:217], 0
	v_mfma_f32_16x16x32_bf16 v[80:83], v[124:127], v[188:191], v[80:83]
	v_mfma_f32_16x16x32_bf16 v[76:79], v[132:135], v[188:191], 0
	v_mfma_f32_16x16x32_bf16 v[76:79], v[144:147], v[214:217], v[76:79]
	v_mfma_f32_16x16x32_bf16 v[92:95], v[144:147], v[184:187], 0
	v_mfma_f32_16x16x32_bf16 v[92:95], v[132:135], v[180:183], v[92:95]
	v_mfma_f32_16x16x32_bf16 v[108:111], v[132:135], v[172:175], 0
	v_mfma_f32_16x16x32_bf16 v[108:111], v[144:147], v[176:179], v[108:111]
	v_mfma_f32_16x16x32_bf16 v[136:139], v[144:147], v[168:171], 0
	v_mfma_f32_16x16x32_bf16 v[136:139], v[132:135], v[164:167], v[136:139]
	v_mfma_f32_16x16x32_bf16 v[120:123], v[148:151], v[164:167], 0
	v_mfma_f32_16x16x32_bf16 v[120:123], v[152:155], v[168:171], v[120:123]
	v_mfma_f32_16x16x32_bf16 v[104:107], v[152:155], v[176:179], 0
	v_mfma_f32_16x16x32_bf16 v[104:107], v[148:151], v[172:175], v[104:107]
	v_mfma_f32_16x16x32_bf16 v[88:91], v[148:151], v[180:183], 0
	v_mfma_f32_16x16x32_bf16 v[88:91], v[152:155], v[184:187], v[88:91]
	v_mfma_f32_16x16x32_bf16 v[72:75], v[152:155], v[214:217], 0
	v_mfma_f32_16x16x32_bf16 v[72:75], v[148:151], v[188:191], v[72:75]
	v_mfma_f32_16x16x32_bf16 v[68:71], v[156:159], v[188:191], 0
	v_mfma_f32_16x16x32_bf16 v[68:71], v[160:163], v[214:217], v[68:71]
	v_mfma_f32_16x16x32_bf16 v[84:87], v[160:163], v[184:187], 0
	v_mfma_f32_16x16x32_bf16 v[84:87], v[156:159], v[180:183], v[84:87]
	v_mfma_f32_16x16x32_bf16 v[100:103], v[156:159], v[172:175], 0
	v_mfma_f32_16x16x32_bf16 v[100:103], v[160:163], v[176:179], v[100:103]
	v_mfma_f32_16x16x32_bf16 v[116:119], v[160:163], v[168:171], 0
	v_mfma_f32_16x16x32_bf16 v[116:119], v[156:159], v[164:167], v[116:119]
	s_setprio 0
	s_barrier
	s_add_i32 s56, s56, s40
	s_mov_b32 m0, s56
	ds_read_b128 v[164:167], v242 offset:16384
	ds_read_b128 v[168:171], v242 offset:17408
	ds_read_b128 v[172:175], v242 offset:18432
	ds_read_b128 v[176:179], v242 offset:19456
	ds_read_b128 v[180:183], v242 offset:20480
	ds_read_b128 v[184:187], v242 offset:21504
	ds_read_b128 v[188:191], v242 offset:22528
	ds_read_b128 v[214:217], v242 offset:23552
	global_load_lds_dwordx4 v2, s[26:27]
	s_add_i32 m0, s56, 0x2000
	s_add_u32 s56, s26, 0x100000
	s_addc_u32 s57, s27, 0
	s_add_i32 s58, s58, s40
	global_load_lds_dwordx4 v204, s[26:27]
	s_mov_b32 m0, s58
	v_lshl_add_u64 v[224:225], s[36:37], 0, v[206:207]
	global_load_lds_dwordx4 v2, s[56:57]
	s_add_i32 m0, s58, 0x2000
	s_nop 0
	global_load_lds_dwordx4 v204, s[56:57]
	v_lshl_add_u64 v[222:223], s[36:37], 0, v[208:209]
	s_waitcnt vmcnt(6)
	s_waitcnt lgkmcnt(0)
	s_barrier
; #define PG8_STAGE(bufoff, gbase, voff) do { _Pragma("unroll") for (int _i = 0; _i < 2; ++_i) \
;         __builtin_amdgcn_global_load_lds((const unsigned*)((const char*)(gbase) + (voff)[_i]), (PG8_LAS unsigned*)(lds + (bufoff) + ldsw + _i * 8192), 16, 0, 0); } while (0)
; #define PG8_LDA(dst, b, h) do { _Pragma("unroll") for (int m = 0; m < 4; ++m) _Pragma("unroll") for (int k = 0; k < 2; ++k) dst[m][k] = *(const PG8_LAS bf16x8*)(lds + PG8_SA(b, h) + aoff + m * 2048 + k * 1024); } while (0)
; #define PG8_LDB(dst, b, h) do { _Pragma("unroll") for (int n = 0; n < 2; ++n) _Pragma("unroll") for (int k = 0; k < 2; ++k) dst[n][k] = *(const PG8_LAS bf16x8*)(lds + PG8_SB(b, h) + boff + n * 2048 + k * 1024); } while (0)
; #define PG8_WAIT_V(n) asm volatile("s_waitcnt vmcnt(" #n ")" ::: "memory")
; #define PG8_WAIT_L(n) asm volatile("s_waitcnt lgkmcnt(" #n ")" ::: "memory")
; #define PG8_BAR __builtin_amdgcn_s_barrier()
; #define PG8_SCHED __builtin_amdgcn_sched_barrier(0)
; template <class Epi, class Sched, bool ALIGN_EPI = false, bool SP2 = false, bool I8 = false>
; __device__ __forceinline__ void gemm_phase(PG8_LAS unsigned char* lds, const Gemm g, const Sched& S, const Epi& E) {
;     ...
;             PG8_WAIT_V(8); PG8_WAIT_L(0); PG8_BAR; PG8_MMA(1, 0, At, B0); PG8_MMA(1, 1, At, B1); PG8_BAR; PG8_SCHED;
;             PG8_LDB(B0, 1, 0); PG8_LDB(B1, 1, 1); PG8_SCHED; PG8_LDA(At, 1, 0); PG8_STAGE(PG8_SA(0, 1), a2 + hstep, voffA);
;             PG8_WAIT_V(8); PG8_WAIT_L(0); PG8_BAR; PG8_MMA(0, 0, At, B0); PG8_MMA(0, 1, At, B1); PG8_BAR; PG8_SCHED;
;             PG8_LDA(At, 1, 1); PG8_STAGE(PG8_SB(1, 0), b3, voffB); PG8_STAGE(PG8_SB(1, 1), b3 + hstep, voffB); PG8_STAGE(PG8_SA(1, 0), a3, voffA);
;             PG8_WAIT_V(8); PG8_WAIT_L(0); PG8_BAR; PG8_MMA(1, 0, At, B0); PG8_MMA(1, 1, At, B1); PG8_BAR; PG8_SCHED;
	s_setprio 1
	s_waitcnt lgkmcnt(0)
	v_mfma_f32_16x16x32_bf16 v[64:67], v[124:127], v[164:167], 0
	v_mfma_f32_16x16x32_bf16 v[64:67], v[128:131], v[168:171], v[64:67]
	v_mfma_f32_16x16x32_bf16 v[48:51], v[128:131], v[176:179], 0
	v_mfma_f32_16x16x32_bf16 v[48:51], v[124:127], v[172:175], v[48:51]
	v_mfma_f32_16x16x32_bf16 v[32:35], v[124:127], v[180:183], 0
	v_mfma_f32_16x16x32_bf16 v[32:35], v[128:131], v[184:187], v[32:35]
	v_mfma_f32_16x16x32_bf16 v[16:19], v[128:131], v[214:217], 0
	v_mfma_f32_16x16x32_bf16 v[16:19], v[124:127], v[188:191], v[16:19]
	v_mfma_f32_16x16x32_bf16 v[12:15], v[132:135], v[188:191], 0
	v_mfma_f32_16x16x32_bf16 v[12:15], v[144:147], v[214:217], v[12:15]
	v_mfma_f32_16x16x32_bf16 v[28:31], v[144:147], v[184:187], 0
	v_mfma_f32_16x16x32_bf16 v[28:31], v[132:135], v[180:183], v[28:31]
	v_mfma_f32_16x16x32_bf16 v[44:47], v[132:135], v[172:175], 0
	v_mfma_f32_16x16x32_bf16 v[44:47], v[144:147], v[176:179], v[44:47]
	v_mfma_f32_16x16x32_bf16 v[60:63], v[144:147], v[168:171], 0
	v_mfma_f32_16x16x32_bf16 v[60:63], v[132:135], v[164:167], v[60:63]
	v_mfma_f32_16x16x32_bf16 v[56:59], v[148:151], v[164:167], 0
	v_mfma_f32_16x16x32_bf16 v[56:59], v[152:155], v[168:171], v[56:59]
	v_mfma_f32_16x16x32_bf16 v[40:43], v[152:155], v[176:179], 0
	v_mfma_f32_16x16x32_bf16 v[40:43], v[148:151], v[172:175], v[40:43]
	v_mfma_f32_16x16x32_bf16 v[24:27], v[148:151], v[180:183], 0
	v_mfma_f32_16x16x32_bf16 v[24:27], v[152:155], v[184:187], v[24:27]
	v_mfma_f32_16x16x32_bf16 v[8:11], v[152:155], v[214:217], 0
	v_mfma_f32_16x16x32_bf16 v[8:11], v[148:151], v[188:191], v[8:11]
	v_mfma_f32_16x16x32_bf16 v[4:7], v[156:159], v[188:191], 0
	v_mfma_f32_16x16x32_bf16 v[4:7], v[160:163], v[214:217], v[4:7]
	v_mfma_f32_16x16x32_bf16 v[20:23], v[160:163], v[184:187], 0
	v_mfma_f32_16x16x32_bf16 v[20:23], v[156:159], v[180:183], v[20:23]
	v_mfma_f32_16x16x32_bf16 v[36:39], v[156:159], v[172:175], 0
	v_mfma_f32_16x16x32_bf16 v[36:39], v[160:163], v[176:179], v[36:39]
	v_mfma_f32_16x16x32_bf16 v[52:55], v[160:163], v[168:171], 0
	v_mfma_f32_16x16x32_bf16 v[52:55], v[156:159], v[164:167], v[52:55]
	s_setprio 0
	s_barrier
	s_mov_b32 m0, s41
	s_nop 0
	global_load_lds_dwordx4 v[222:223], off
	s_mov_b32 m0, s42
	s_nop 0
	global_load_lds_dwordx4 v[224:225], off
	s_add_i32 s56, 0, 0x18000
	s_add_i32 s57, 0, 0x1c000
	v_add_u32_e32 v144, s56, v240
	v_add_u32_e32 v160, s57, v240
	ds_read_b128 v[124:127], v144
	ds_read_b128 v[128:131], v144 offset:1024
	ds_read_b128 v[132:135], v144 offset:2048
	ds_read_b128 v[144:147], v144 offset:3072
	ds_read_b128 v[148:151], v160
	ds_read_b128 v[152:155], v160 offset:1024
	ds_read_b128 v[156:159], v160 offset:2048
	ds_read_b128 v[160:163], v160 offset:3072
	s_add_u32 s36, s36, 0x100000
	s_addc_u32 s37, s37, 0
	s_mov_b32 m0, s43
	ds_read_b128 v[164:167], v242 offset:32768
	ds_read_b128 v[168:171], v242 offset:33792
	ds_read_b128 v[172:175], v242 offset:34816
	ds_read_b128 v[176:179], v242 offset:35840
	ds_read_b128 v[180:183], v242 offset:36864
	ds_read_b128 v[184:187], v242 offset:37888
	ds_read_b128 v[188:191], v242 offset:38912
	ds_read_b128 v[214:217], v242 offset:39936
	global_load_lds_dwordx4 v208, s[36:37]
	s_mov_b32 m0, s44
	s_nop 0
	global_load_lds_dwordx4 v206, s[36:37]
	s_waitcnt vmcnt(8)
	s_waitcnt lgkmcnt(0)
	s_barrier
	s_setprio 1
	s_waitcnt lgkmcnt(0)
	v_mfma_f32_16x16x32_bf16 v[140:143], v[124:127], v[164:167], v[140:143]
	v_mfma_f32_16x16x32_bf16 v[140:143], v[128:131], v[168:171], v[140:143]
	v_mfma_f32_16x16x32_bf16 v[112:115], v[128:131], v[176:179], v[112:115]
	v_mfma_f32_16x16x32_bf16 v[112:115], v[124:127], v[172:175], v[112:115]
	v_mfma_f32_16x16x32_bf16 v[96:99], v[124:127], v[180:183], v[96:99]
	v_mfma_f32_16x16x32_bf16 v[96:99], v[128:131], v[184:187], v[96:99]
	v_mfma_f32_16x16x32_bf16 v[80:83], v[128:131], v[214:217], v[80:83]
	v_mfma_f32_16x16x32_bf16 v[80:83], v[124:127], v[188:191], v[80:83]
	v_mfma_f32_16x16x32_bf16 v[76:79], v[132:135], v[188:191], v[76:79]
	v_mfma_f32_16x16x32_bf16 v[76:79], v[144:147], v[214:217], v[76:79]
	v_mfma_f32_16x16x32_bf16 v[92:95], v[144:147], v[184:187], v[92:95]
	v_mfma_f32_16x16x32_bf16 v[92:95], v[132:135], v[180:183], v[92:95]
	v_mfma_f32_16x16x32_bf16 v[108:111], v[132:135], v[172:175], v[108:111]
	v_mfma_f32_16x16x32_bf16 v[108:111], v[144:147], v[176:179], v[108:111]
	v_mfma_f32_16x16x32_bf16 v[136:139], v[144:147], v[168:171], v[136:139]
	v_mfma_f32_16x16x32_bf16 v[136:139], v[132:135], v[164:167], v[136:139]
	v_mfma_f32_16x16x32_bf16 v[120:123], v[148:151], v[164:167], v[120:123]
	v_mfma_f32_16x16x32_bf16 v[120:123], v[152:155], v[168:171], v[120:123]
	v_mfma_f32_16x16x32_bf16 v[104:107], v[152:155], v[176:179], v[104:107]
	v_mfma_f32_16x16x32_bf16 v[104:107], v[148:151], v[172:175], v[104:107]
	v_mfma_f32_16x16x32_bf16 v[88:91], v[148:151], v[180:183], v[88:91]
	v_mfma_f32_16x16x32_bf16 v[88:91], v[152:155], v[184:187], v[88:91]
	v_mfma_f32_16x16x32_bf16 v[72:75], v[152:155], v[214:217], v[72:75]
	v_mfma_f32_16x16x32_bf16 v[72:75], v[148:151], v[188:191], v[72:75]
	v_mfma_f32_16x16x32_bf16 v[68:71], v[156:159], v[188:191], v[68:71]
	v_mfma_f32_16x16x32_bf16 v[68:71], v[160:163], v[214:217], v[68:71]
	v_mfma_f32_16x16x32_bf16 v[84:87], v[160:163], v[184:187], v[84:87]
	v_mfma_f32_16x16x32_bf16 v[84:87], v[156:159], v[180:183], v[84:87]
	v_mfma_f32_16x16x32_bf16 v[100:103], v[156:159], v[172:175], v[100:103]
	v_mfma_f32_16x16x32_bf16 v[100:103], v[160:163], v[176:179], v[100:103]
	v_mfma_f32_16x16x32_bf16 v[116:119], v[160:163], v[168:171], v[116:119]
	v_mfma_f32_16x16x32_bf16 v[116:119], v[156:159], v[164:167], v[116:119]
	s_setprio 0
	s_barrier
	s_add_u32 s98, s26, 0x80
	s_addc_u32 s99, s27, 0
	s_add_i32 s36, s56, s40
	s_mov_b32 m0, s36
	ds_read_b128 v[164:167], v242 offset:49152
	ds_read_b128 v[168:171], v242 offset:50176
	ds_read_b128 v[172:175], v242 offset:51200
	ds_read_b128 v[176:179], v242 offset:52224
	ds_read_b128 v[180:183], v242 offset:53248
	ds_read_b128 v[184:187], v242 offset:54272
	ds_read_b128 v[188:191], v242 offset:55296
	ds_read_b128 v[214:217], v242 offset:56320
	global_load_lds_dwordx4 v2, s[98:99]
	s_add_i32 m0, s36, 0x2000
	s_add_u32 s26, s26, 0x100080
	s_addc_u32 s27, s27, 0
	s_add_i32 s36, s57, s40
	global_load_lds_dwordx4 v204, s[98:99]
	s_mov_b32 m0, s36
	s_nop 0
	global_load_lds_dwordx4 v2, s[26:27]
	s_add_i32 m0, s36, 0x2000
	s_nop 0
	global_load_lds_dwordx4 v204, s[26:27]
	s_cmp_eq_u32 s55, 60
	s_cbranch_scc0 .Ldefer_1456_peel
	v_lshl_add_u64 v[218:219], v[222:223], 0, s[84:85]
	s_mov_b32 m0, s45
	s_nop 0
	global_load_lds_dwordx4 v[218:219], off
	v_lshl_add_u64 v[218:219], v[224:225], 0, s[84:85]
	s_mov_b32 m0, s46
	s_nop 0
	global_load_lds_dwordx4 v[218:219], off

; #define PG8_STAGE(bufoff, gbase, voff) do { _Pragma("unroll") for (int _i = 0; _i < 2; ++_i) \
;         __builtin_amdgcn_global_load_lds((const unsigned*)((const char*)(gbase) + (voff)[_i]), (PG8_LAS unsigned*)(lds + (bufoff) + ldsw + _i * 8192), 16, 0, 0); } while (0)
; #define PG8_LDA(dst, b, h) do { _Pragma("unroll") for (int m = 0; m < 4; ++m) _Pragma("unroll") for (int k = 0; k < 2; ++k) dst[m][k] = *(const PG8_LAS bf16x8*)(lds + PG8_SA(b, h) + aoff + m * 2048 + k * 1024); } while (0)
; #define PG8_LDB(dst, b, h) do { _Pragma("unroll") for (int n = 0; n < 2; ++n) _Pragma("unroll") for (int k = 0; k < 2; ++k) dst[n][k] = *(const PG8_LAS bf16x8*)(lds + PG8_SB(b, h) + boff + n * 2048 + k * 1024); } while (0)
; #define PG8_WAIT_V(n) asm volatile("s_waitcnt vmcnt(" #n ")" ::: "memory")
; #define PG8_WAIT_L(n) asm volatile("s_waitcnt lgkmcnt(" #n ")" ::: "memory")
; #define PG8_BAR __builtin_amdgcn_s_barrier()
; #define PG8_SCHED __builtin_amdgcn_sched_barrier(0)
; template <class Epi, class Sched, bool ALIGN_EPI = false, bool SP2 = false, bool I8 = false>
; __device__ __forceinline__ void gemm_phase(PG8_LAS unsigned char* lds, const Gemm g, const Sched& S, const Epi& E) {
;     ...
;         for (int t = 0; t < nt; t += 2) {
;             const bool last = (t == nt - 2);
;             const char* a1 = cA + (size_t)(t + 1) * kstep;
;             const char* a2 = last ? nA : cA + (size_t)(t + 2) * kstep; const char* b2 = last ? nB : cB + (size_t)(t + 2) * kstep;
;             const char* a3 = a2 + kstep; const char* b3 = b2 + kstep;
;             if (last && has_next) S.a_ready(nxt);
;             if constexpr (SP2) {
;             PG8_LDB(B0, 0, 0); PG8_LDB(B1, 0, 1); PG8_SCHED; PG8_LDA(At, 0, 0); PG8_STAGE(PG8_SA(1, 1), a1 + hstep, voffA);
;             PG8_WAIT_V(8); PG8_WAIT_L(0); PG8_BAR; PG8_MMA(0, 0, At, B0); PG8_MMA(0, 1, At, B1); PG8_BAR; PG8_SCHED;
;             PG8_LDA(At, 0, 1); PG8_STAGE(PG8_SB(0, 0), b2, voffB); PG8_STAGE(PG8_SB(0, 1), b2 + hstep, voffB); PG8_STAGE(PG8_SA(0, 0), a2, voffA);
;             PG8_WAIT_V(8); PG8_WAIT_L(0); PG8_BAR; PG8_MMA(1, 0, At, B0); PG8_MMA(1, 1, At, B1); PG8_BAR; PG8_SCHED;
.LBB0_1456:
	s_add_u32 s26, s24, 0xfff00080
	s_addc_u32 s27, s25, -1
	s_add_i32 s56, 0, 0x10000
	s_cmp_eq_u32 s55, 60
	s_cselect_b32 s37, s17, s27
	s_cselect_b32 s36, s51, s26
	s_cselect_b32 s27, s19, s54
	s_cselect_b32 s26, s52, s53
	s_add_i32 s58, 0, 0x14000
	v_add_u32_e32 v144, s56, v240
	v_add_u32_e32 v160, s58, v240
	ds_read_b128 v[124:127], v144
	ds_read_b128 v[128:131], v144 offset:1024
	ds_read_b128 v[132:135], v144 offset:2048
	ds_read_b128 v[144:147], v144 offset:3072
	ds_read_b128 v[148:151], v160
	ds_read_b128 v[152:155], v160 offset:1024
	ds_read_b128 v[156:159], v160 offset:2048
	ds_read_b128 v[160:163], v160 offset:3072
	v_lshl_add_u64 v[218:219], v[222:223], 0, s[84:85]
	s_mov_b32 m0, s45
	s_nop 0
	global_load_lds_dwordx4 v[218:219], off
	v_lshl_add_u64 v[218:219], v[224:225], 0, s[84:85]
	s_mov_b32 m0, s46
	s_nop 0
	global_load_lds_dwordx4 v[218:219], off
	s_add_i32 m0, s41, 0xc000
	ds_read_b128 v[164:167], v242
	ds_read_b128 v[168:171], v242 offset:1024
	ds_read_b128 v[172:175], v242 offset:2048
	ds_read_b128 v[176:179], v242 offset:3072
	ds_read_b128 v[180:183], v242 offset:4096
	ds_read_b128 v[184:187], v242 offset:5120
	ds_read_b128 v[188:191], v242 offset:6144
	ds_read_b128 v[214:217], v242 offset:7168
	global_load_lds_dwordx4 v210, s[24:25]
	s_add_i32 m0, s41, 0xe000
	s_nop 0
	global_load_lds_dwordx4 v212, s[24:25]
	s_waitcnt vmcnt(8)
	s_waitcnt lgkmcnt(0)
	s_barrier
	s_setprio 1
	s_waitcnt lgkmcnt(0)
	v_mfma_f32_16x16x32_bf16 v[140:143], v[124:127], v[164:167], v[140:143]
	v_mfma_f32_16x16x32_bf16 v[140:143], v[128:131], v[168:171], v[140:143]
	v_mfma_f32_16x16x32_bf16 v[112:115], v[128:131], v[176:179], v[112:115]
	v_mfma_f32_16x16x32_bf16 v[112:115], v[124:127], v[172:175], v[112:115]
	v_mfma_f32_16x16x32_bf16 v[96:99], v[124:127], v[180:183], v[96:99]
	v_mfma_f32_16x16x32_bf16 v[96:99], v[128:131], v[184:187], v[96:99]
	v_mfma_f32_16x16x32_bf16 v[80:83], v[128:131], v[214:217], v[80:83]
	v_mfma_f32_16x16x32_bf16 v[80:83], v[124:127], v[188:191], v[80:83]
	v_mfma_f32_16x16x32_bf16 v[76:79], v[132:135], v[188:191], v[76:79]
	v_mfma_f32_16x16x32_bf16 v[76:79], v[144:147], v[214:217], v[76:79]
	v_mfma_f32_16x16x32_bf16 v[92:95], v[144:147], v[184:187], v[92:95]
	v_mfma_f32_16x16x32_bf16 v[92:95], v[132:135], v[180:183], v[92:95]
	v_mfma_f32_16x16x32_bf16 v[108:111], v[132:135], v[172:175], v[108:111]
	v_mfma_f32_16x16x32_bf16 v[108:111], v[144:147], v[176:179], v[108:111]
	v_mfma_f32_16x16x32_bf16 v[136:139], v[144:147], v[168:171], v[136:139]
	v_mfma_f32_16x16x32_bf16 v[136:139], v[132:135], v[164:167], v[136:139]
	v_mfma_f32_16x16x32_bf16 v[120:123], v[148:151], v[164:167], v[120:123]
	v_mfma_f32_16x16x32_bf16 v[120:123], v[152:155], v[168:171], v[120:123]
	v_mfma_f32_16x16x32_bf16 v[104:107], v[152:155], v[176:179], v[104:107]
	v_mfma_f32_16x16x32_bf16 v[104:107], v[148:151], v[172:175], v[104:107]
	v_mfma_f32_16x16x32_bf16 v[88:91], v[148:151], v[180:183], v[88:91]
	v_mfma_f32_16x16x32_bf16 v[88:91], v[152:155], v[184:187], v[88:91]
	v_mfma_f32_16x16x32_bf16 v[72:75], v[152:155], v[214:217], v[72:75]
	v_mfma_f32_16x16x32_bf16 v[72:75], v[148:151], v[188:191], v[72:75]
	v_mfma_f32_16x16x32_bf16 v[68:71], v[156:159], v[188:191], v[68:71]
	v_mfma_f32_16x16x32_bf16 v[68:71], v[160:163], v[214:217], v[68:71]
	v_mfma_f32_16x16x32_bf16 v[84:87], v[160:163], v[184:187], v[84:87]
	v_mfma_f32_16x16x32_bf16 v[84:87], v[156:159], v[180:183], v[84:87]
	v_mfma_f32_16x16x32_bf16 v[100:103], v[156:159], v[172:175], v[100:103]
	v_mfma_f32_16x16x32_bf16 v[100:103], v[160:163], v[176:179], v[100:103]
	v_mfma_f32_16x16x32_bf16 v[116:119], v[160:163], v[168:171], v[116:119]
	v_mfma_f32_16x16x32_bf16 v[116:119], v[156:159], v[164:167], v[116:119]
	s_setprio 0
	s_barrier
	s_add_i32 s56, s56, s40
	s_mov_b32 m0, s56
	ds_read_b128 v[164:167], v242 offset:16384
	ds_read_b128 v[168:171], v242 offset:17408
	ds_read_b128 v[172:175], v242 offset:18432
	ds_read_b128 v[176:179], v242 offset:19456
	ds_read_b128 v[180:183], v242 offset:20480
	ds_read_b128 v[184:187], v242 offset:21504
	ds_read_b128 v[188:191], v242 offset:22528
	ds_read_b128 v[214:217], v242 offset:23552
	global_load_lds_dwordx4 v2, s[26:27]
	s_add_i32 m0, s56, 0x2000
	s_add_u32 s56, s26, 0x100000
	s_addc_u32 s57, s27, 0
	s_add_i32 s58, s58, s40
	global_load_lds_dwordx4 v204, s[26:27]
	s_mov_b32 m0, s58
	v_lshl_add_u64 v[224:225], s[36:37], 0, v[206:207]
	global_load_lds_dwordx4 v2, s[56:57]
	s_add_i32 m0, s58, 0x2000
	s_nop 0
	global_load_lds_dwordx4 v204, s[56:57]
	v_lshl_add_u64 v[222:223], s[36:37], 0, v[208:209]
	s_waitcnt vmcnt(6)
	s_waitcnt lgkmcnt(0)
	s_barrier
; #define PG8_STAGE(bufoff, gbase, voff) do { _Pragma("unroll") for (int _i = 0; _i < 2; ++_i) \
;         __builtin_amdgcn_global_load_lds((const unsigned*)((const char*)(gbase) + (voff)[_i]), (PG8_LAS unsigned*)(lds + (bufoff) + ldsw + _i * 8192), 16, 0, 0); } while (0)
; #define PG8_LDA(dst, b, h) do { _Pragma("unroll") for (int m = 0; m < 4; ++m) _Pragma("unroll") for (int k = 0; k < 2; ++k) dst[m][k] = *(const PG8_LAS bf16x8*)(lds + PG8_SA(b, h) + aoff + m * 2048 + k * 1024); } while (0)
; #define PG8_LDB(dst, b, h) do { _Pragma("unroll") for (int n = 0; n < 2; ++n) _Pragma("unroll") for (int k = 0; k < 2; ++k) dst[n][k] = *(const PG8_LAS bf16x8*)(lds + PG8_SB(b, h) + boff + n * 2048 + k * 1024); } while (0)
; #define PG8_WAIT_V(n) asm volatile("s_waitcnt vmcnt(" #n ")" ::: "memory")
; #define PG8_WAIT_L(n) asm volatile("s_waitcnt lgkmcnt(" #n ")" ::: "memory")
; #define PG8_BAR __builtin_amdgcn_s_barrier()
; #define PG8_SCHED __builtin_amdgcn_sched_barrier(0)
; template <class Epi, class Sched, bool ALIGN_EPI = false, bool SP2 = false, bool I8 = false>
; __device__ __forceinline__ void gemm_phase(PG8_LAS unsigned char* lds, const Gemm g, const Sched& S, const Epi& E) {
;     ...
;             PG8_WAIT_V(8); PG8_WAIT_L(0); PG8_BAR; PG8_MMA(0, 0, At, B0); PG8_MMA(0, 1, At, B1); PG8_BAR; PG8_SCHED;
;             PG8_LDA(At, 0, 1); PG8_STAGE(PG8_SB(0, 0), b2, voffB); PG8_STAGE(PG8_SB(0, 1), b2 + hstep, voffB); PG8_STAGE(PG8_SA(0, 0), a2, voffA);
;             PG8_WAIT_V(8); PG8_WAIT_L(0); PG8_BAR; PG8_MMA(1, 0, At, B0); PG8_MMA(1, 1, At, B1); PG8_BAR; PG8_SCHED;
;             PG8_LDB(B0, 1, 0); PG8_LDB(B1, 1, 1); PG8_SCHED; PG8_LDA(At, 1, 0); PG8_STAGE(PG8_SA(0, 1), a2 + hstep, voffA);
;             PG8_WAIT_V(8); PG8_WAIT_L(0); PG8_BAR; PG8_MMA(0, 0, At, B0); PG8_MMA(0, 1, At, B1); PG8_BAR; PG8_SCHED;
;             PG8_LDA(At, 1, 1); PG8_STAGE(PG8_SB(1, 0), b3, voffB); PG8_STAGE(PG8_SB(1, 1), b3 + hstep, voffB); PG8_STAGE(PG8_SA(1, 0), a3, voffA);
;             PG8_WAIT_V(8); PG8_WAIT_L(0); PG8_BAR; PG8_MMA(1, 0, At, B0); PG8_MMA(1, 1, At, B1); PG8_BAR; PG8_SCHED;
	s_setprio 1
	s_waitcnt lgkmcnt(0)
	v_mfma_f32_16x16x32_bf16 v[64:67], v[124:127], v[164:167], v[64:67]
	v_mfma_f32_16x16x32_bf16 v[64:67], v[128:131], v[168:171], v[64:67]
	v_mfma_f32_16x16x32_bf16 v[48:51], v[128:131], v[176:179], v[48:51]
	v_mfma_f32_16x16x32_bf16 v[48:51], v[124:127], v[172:175], v[48:51]
	v_mfma_f32_16x16x32_bf16 v[32:35], v[124:127], v[180:183], v[32:35]
	v_mfma_f32_16x16x32_bf16 v[32:35], v[128:131], v[184:187], v[32:35]
	v_mfma_f32_16x16x32_bf16 v[16:19], v[128:131], v[214:217], v[16:19]
	v_mfma_f32_16x16x32_bf16 v[16:19], v[124:127], v[188:191], v[16:19]
	v_mfma_f32_16x16x32_bf16 v[12:15], v[132:135], v[188:191], v[12:15]
	v_mfma_f32_16x16x32_bf16 v[12:15], v[144:147], v[214:217], v[12:15]
	v_mfma_f32_16x16x32_bf16 v[28:31], v[144:147], v[184:187], v[28:31]
	v_mfma_f32_16x16x32_bf16 v[28:31], v[132:135], v[180:183], v[28:31]
	v_mfma_f32_16x16x32_bf16 v[44:47], v[132:135], v[172:175], v[44:47]
	v_mfma_f32_16x16x32_bf16 v[44:47], v[144:147], v[176:179], v[44:47]
	v_mfma_f32_16x16x32_bf16 v[60:63], v[144:147], v[168:171], v[60:63]
	v_mfma_f32_16x16x32_bf16 v[60:63], v[132:135], v[164:167], v[60:63]
	v_mfma_f32_16x16x32_bf16 v[56:59], v[148:151], v[164:167], v[56:59]
	v_mfma_f32_16x16x32_bf16 v[56:59], v[152:155], v[168:171], v[56:59]
	v_mfma_f32_16x16x32_bf16 v[40:43], v[152:155], v[176:179], v[40:43]
	v_mfma_f32_16x16x32_bf16 v[40:43], v[148:151], v[172:175], v[40:43]
	v_mfma_f32_16x16x32_bf16 v[24:27], v[148:151], v[180:183], v[24:27]
	v_mfma_f32_16x16x32_bf16 v[24:27], v[152:155], v[184:187], v[24:27]
	v_mfma_f32_16x16x32_bf16 v[8:11], v[152:155], v[214:217], v[8:11]
	v_mfma_f32_16x16x32_bf16 v[8:11], v[148:151], v[188:191], v[8:11]
	v_mfma_f32_16x16x32_bf16 v[4:7], v[156:159], v[188:191], v[4:7]
	v_mfma_f32_16x16x32_bf16 v[4:7], v[160:163], v[214:217], v[4:7]
	v_mfma_f32_16x16x32_bf16 v[20:23], v[160:163], v[184:187], v[20:23]
	v_mfma_f32_16x16x32_bf16 v[20:23], v[156:159], v[180:183], v[20:23]
	v_mfma_f32_16x16x32_bf16 v[36:39], v[156:159], v[172:175], v[36:39]
	v_mfma_f32_16x16x32_bf16 v[36:39], v[160:163], v[176:179], v[36:39]
	v_mfma_f32_16x16x32_bf16 v[52:55], v[160:163], v[168:171], v[52:55]
	v_mfma_f32_16x16x32_bf16 v[52:55], v[156:159], v[164:167], v[52:55]
	s_setprio 0
	s_barrier
	s_mov_b32 m0, s41
	s_nop 0
	global_load_lds_dwordx4 v[222:223], off
	s_mov_b32 m0, s42
	s_nop 0
	global_load_lds_dwordx4 v[224:225], off
	s_add_i32 s56, 0, 0x18000
	s_add_i32 s57, 0, 0x1c000
	v_add_u32_e32 v144, s56, v240
	v_add_u32_e32 v160, s57, v240
	ds_read_b128 v[124:127], v144
	ds_read_b128 v[128:131], v144 offset:1024
	ds_read_b128 v[132:135], v144 offset:2048
	ds_read_b128 v[144:147], v144 offset:3072
	ds_read_b128 v[148:151], v160
	ds_read_b128 v[152:155], v160 offset:1024
	ds_read_b128 v[156:159], v160 offset:2048
	ds_read_b128 v[160:163], v160 offset:3072
	s_add_u32 s36, s36, 0x100000
	s_addc_u32 s37, s37, 0
	s_mov_b32 m0, s43
	ds_read_b128 v[164:167], v242 offset:32768
	ds_read_b128 v[168:171], v242 offset:33792
	ds_read_b128 v[172:175], v242 offset:34816
	ds_read_b128 v[176:179], v242 offset:35840
	ds_read_b128 v[180:183], v242 offset:36864
	ds_read_b128 v[184:187], v242 offset:37888
	ds_read_b128 v[188:191], v242 offset:38912
	ds_read_b128 v[214:217], v242 offset:39936
	global_load_lds_dwordx4 v208, s[36:37]
	s_mov_b32 m0, s44
	s_nop 0
	global_load_lds_dwordx4 v206, s[36:37]
	s_waitcnt vmcnt(8)
	s_waitcnt lgkmcnt(0)
	s_barrier
	s_setprio 1
	s_waitcnt lgkmcnt(0)
	v_mfma_f32_16x16x32_bf16 v[140:143], v[124:127], v[164:167], v[140:143]
	v_mfma_f32_16x16x32_bf16 v[140:143], v[128:131], v[168:171], v[140:143]
	v_mfma_f32_16x16x32_bf16 v[112:115], v[128:131], v[176:179], v[112:115]
	v_mfma_f32_16x16x32_bf16 v[112:115], v[124:127], v[172:175], v[112:115]
	v_mfma_f32_16x16x32_bf16 v[96:99], v[124:127], v[180:183], v[96:99]
	v_mfma_f32_16x16x32_bf16 v[96:99], v[128:131], v[184:187], v[96:99]
	v_mfma_f32_16x16x32_bf16 v[80:83], v[128:131], v[214:217], v[80:83]
	v_mfma_f32_16x16x32_bf16 v[80:83], v[124:127], v[188:191], v[80:83]
	v_mfma_f32_16x16x32_bf16 v[76:79], v[132:135], v[188:191], v[76:79]
	v_mfma_f32_16x16x32_bf16 v[76:79], v[144:147], v[214:217], v[76:79]
	v_mfma_f32_16x16x32_bf16 v[92:95], v[144:147], v[184:187], v[92:95]
	v_mfma_f32_16x16x32_bf16 v[92:95], v[132:135], v[180:183], v[92:95]
	v_mfma_f32_16x16x32_bf16 v[108:111], v[132:135], v[172:175], v[108:111]
	v_mfma_f32_16x16x32_bf16 v[108:111], v[144:147], v[176:179], v[108:111]
	v_mfma_f32_16x16x32_bf16 v[136:139], v[144:147], v[168:171], v[136:139]
	v_mfma_f32_16x16x32_bf16 v[136:139], v[132:135], v[164:167], v[136:139]
	v_mfma_f32_16x16x32_bf16 v[120:123], v[148:151], v[164:167], v[120:123]
	v_mfma_f32_16x16x32_bf16 v[120:123], v[152:155], v[168:171], v[120:123]
	v_mfma_f32_16x16x32_bf16 v[104:107], v[152:155], v[176:179], v[104:107]
	v_mfma_f32_16x16x32_bf16 v[104:107], v[148:151], v[172:175], v[104:107]
	v_mfma_f32_16x16x32_bf16 v[88:91], v[148:151], v[180:183], v[88:91]
	v_mfma_f32_16x16x32_bf16 v[88:91], v[152:155], v[184:187], v[88:91]
	v_mfma_f32_16x16x32_bf16 v[72:75], v[152:155], v[214:217], v[72:75]
	v_mfma_f32_16x16x32_bf16 v[72:75], v[148:151], v[188:191], v[72:75]
	v_mfma_f32_16x16x32_bf16 v[68:71], v[156:159], v[188:191], v[68:71]
	v_mfma_f32_16x16x32_bf16 v[68:71], v[160:163], v[214:217], v[68:71]
	v_mfma_f32_16x16x32_bf16 v[84:87], v[160:163], v[184:187], v[84:87]
	v_mfma_f32_16x16x32_bf16 v[84:87], v[156:159], v[180:183], v[84:87]
	v_mfma_f32_16x16x32_bf16 v[100:103], v[156:159], v[172:175], v[100:103]
	v_mfma_f32_16x16x32_bf16 v[100:103], v[160:163], v[176:179], v[100:103]
	v_mfma_f32_16x16x32_bf16 v[116:119], v[160:163], v[168:171], v[116:119]
	v_mfma_f32_16x16x32_bf16 v[116:119], v[156:159], v[164:167], v[116:119]
	s_setprio 0
	s_barrier
	s_add_u32 s98, s26, 0x80
	s_addc_u32 s99, s27, 0
	s_add_i32 s36, s56, s40
	s_mov_b32 m0, s36
	ds_read_b128 v[164:167], v242 offset:49152
	ds_read_b128 v[168:171], v242 offset:50176
	ds_read_b128 v[172:175], v242 offset:51200
	ds_read_b128 v[176:179], v242 offset:52224
	ds_read_b128 v[180:183], v242 offset:53248
	ds_read_b128 v[184:187], v242 offset:54272
	ds_read_b128 v[188:191], v242 offset:55296
	ds_read_b128 v[214:217], v242 offset:56320
	global_load_lds_dwordx4 v2, s[98:99]
	s_add_i32 m0, s36, 0x2000
	s_add_u32 s26, s26, 0x100080
	s_addc_u32 s27, s27, 0
	s_add_i32 s36, s57, s40
	global_load_lds_dwordx4 v204, s[98:99]
	s_mov_b32 m0, s36
	s_nop 0
	global_load_lds_dwordx4 v2, s[26:27]
	s_add_i32 m0, s36, 0x2000
	s_nop 0
	global_load_lds_dwordx4 v204, s[26:27]
	s_cmp_eq_u32 s55, 60
	s_cbranch_scc0 .Ldefer_1456_body
	v_lshl_add_u64 v[218:219], v[222:223], 0, s[84:85]
	s_mov_b32 m0, s45
	s_nop 0
	global_load_lds_dwordx4 v[218:219], off
	v_lshl_add_u64 v[218:219], v[224:225], 0, s[84:85]
	s_mov_b32 m0, s46
	s_nop 0
	global_load_lds_dwordx4 v[218:219], off

; #define PG8_STAGE(bufoff, gbase, voff) do { _Pragma("unroll") for (int _i = 0; _i < 2; ++_i) \
;         __builtin_amdgcn_global_load_lds((const unsigned*)((const char*)(gbase) + (voff)[_i]), (PG8_LAS unsigned*)(lds + (bufoff) + ldsw + _i * 8192), 16, 0, 0); } while (0)
; #define PG8_LDA(dst, b, h) do { _Pragma("unroll") for (int m = 0; m < 4; ++m) _Pragma("unroll") for (int k = 0; k < 2; ++k) dst[m][k] = *(const PG8_LAS bf16x8*)(lds + PG8_SA(b, h) + aoff + m * 2048 + k * 1024); } while (0)
; #define PG8_LDB(dst, b, h) do { _Pragma("unroll") for (int n = 0; n < 2; ++n) _Pragma("unroll") for (int k = 0; k < 2; ++k) dst[n][k] = *(const PG8_LAS bf16x8*)(lds + PG8_SB(b, h) + boff + n * 2048 + k * 1024); } while (0)
; #define PG8_WAIT_V(n) asm volatile("s_waitcnt vmcnt(" #n ")" ::: "memory")
; #define PG8_WAIT_L(n) asm volatile("s_waitcnt lgkmcnt(" #n ")" ::: "memory")
; #define PG8_BAR __builtin_amdgcn_s_barrier()
; #define PG8_SCHED __builtin_amdgcn_sched_barrier(0)
; template <class Epi, class Sched, bool ALIGN_EPI = false, bool SP2 = false, bool I8 = false>
; __device__ __forceinline__ void gemm_phase(PG8_LAS unsigned char* lds, const Gemm g, const Sched& S, const Epi& E) {
;     ...
;         const bool has_next = S.next(ui + 1, nxt);
;         const char* nA = has_next ? (const char*)g.A + (size_t)nxt.pm * tstep : cA; const char* nB = has_next ? (const char*)g.Bt + (size_t)nxt.pn * tstep : cB;
;         for (int t = 0; t < nt; t += 2) {
;             const bool last = (t == nt - 2);
;             const char* a1 = cA + (size_t)(t + 1) * kstep;
;             const char* a2 = last ? nA : cA + (size_t)(t + 2) * kstep; const char* b2 = last ? nB : cB + (size_t)(t + 2) * kstep;
;             const char* a3 = a2 + kstep; const char* b3 = b2 + kstep;
;             if (last && has_next) S.a_ready(nxt);
;             if constexpr (SP2) {
;             PG8_LDB(B0, 0, 0); PG8_LDB(B1, 0, 1); PG8_SCHED; PG8_LDA(At, 0, 0); PG8_STAGE(PG8_SA(1, 1), a1 + hstep, voffA);
;             PG8_WAIT_V(8); PG8_WAIT_L(0); PG8_BAR; PG8_MMA(0, 0, At, B0); PG8_MMA(0, 1, At, B1); PG8_BAR; PG8_SCHED;
;             PG8_LDA(At, 0, 1); PG8_STAGE(PG8_SB(0, 0), b2, voffB); PG8_STAGE(PG8_SB(0, 1), b2 + hstep, voffB); PG8_STAGE(PG8_SA(0, 0), a2, voffA);
;             PG8_WAIT_V(8); PG8_WAIT_L(0); PG8_BAR; PG8_MMA(1, 0, At, B0); PG8_MMA(1, 1, At, B1); PG8_BAR; PG8_SCHED;
.LBB0_1590:
	s_ashr_i32 s25, s24, 31
	s_lshl_b64 s[26:27], s[24:25], 20
	s_add_u32 s26, s28, s26
	s_addc_u32 s27, s42, s27
	s_and_b64 s[36:37], s[10:11], exec
	s_cselect_b32 s25, s27, s41
	s_cselect_b32 s57, s26, s40
	s_ashr_i32 s23, s22, 31
	s_lshl_b64 s[36:37], s[22:23], 20
	s_add_u32 s36, s43, s36
	s_addc_u32 s37, s46, s37
	s_and_b64 s[48:49], s[10:11], exec
	s_cselect_b32 s23, s37, s45
	s_cselect_b32 s58, s36, s44
	s_add_u32 s40, s40, 0x80080
	s_addc_u32 s41, s41, 0
	s_add_u32 s59, s44, 0x100
	s_addc_u32 s60, s45, 0
	s_mov_b32 s61, -2
	s_add_u32 s44, s40, 0xfff80080
	s_addc_u32 s45, s41, -1
	s_add_i32 s64, 0, 0x10000
	s_cmp_eq_u32 s61, 28
	s_cselect_b32 s49, s25, s45
	s_cselect_b32 s48, s57, s44
	s_cselect_b32 s45, s23, s60
	s_cselect_b32 s44, s58, s59
	s_add_i32 s67, 0, 0x14000
	v_add_u32_e32 v144, s64, v167
	v_add_u32_e32 v158, s67, v167
	ds_read_b128 v[36:39], v144
	ds_read_b128 v[44:47], v144 offset:1024
	ds_read_b128 v[140:143], v144 offset:2048
	ds_read_b128 v[144:147], v144 offset:3072
	ds_read_b128 v[160:163], v158
	ds_read_b128 v[172:175], v158 offset:1024
	ds_read_b128 v[176:179], v158 offset:2048
	ds_read_b128 v[180:183], v158 offset:3072
	s_add_i32 m0, s50, 0xc000
	ds_read_b128 v[184:187], v171
	ds_read_b128 v[188:191], v171 offset:1024
	ds_read_b128 v[204:207], v171 offset:2048
	ds_read_b128 v[208:211], v171 offset:3072
	ds_read_b128 v[212:215], v171 offset:4096
	ds_read_b128 v[216:219], v171 offset:5120
	ds_read_b128 v[220:223], v171 offset:6144
	ds_read_b128 v[224:227], v171 offset:7168
	global_load_lds_dwordx4 v154, s[40:41]
	s_add_i32 m0, s50, 0xe000
	s_nop 0
	global_load_lds_dwordx4 v156, s[40:41]
	s_waitcnt vmcnt(8)
	s_waitcnt lgkmcnt(0)
	s_barrier
	s_setprio 1
	s_waitcnt lgkmcnt(0)
	v_mfma_i32_16x16x64_i8 v[136:139], v[36:39], v[184:187], 0
	v_mfma_i32_16x16x64_i8 v[136:139], v[44:47], v[188:191], v[136:139]
	v_mfma_i32_16x16x64_i8 v[120:123], v[44:47], v[208:211], 0
	v_mfma_i32_16x16x64_i8 v[120:123], v[36:39], v[204:207], v[120:123]
	v_mfma_i32_16x16x64_i8 v[104:107], v[36:39], v[212:215], 0
	v_mfma_i32_16x16x64_i8 v[104:107], v[44:47], v[216:219], v[104:107]
	v_mfma_i32_16x16x64_i8 v[88:91], v[44:47], v[224:227], 0
	v_mfma_i32_16x16x64_i8 v[88:91], v[36:39], v[220:223], v[88:91]
	v_mfma_i32_16x16x64_i8 v[80:83], v[140:143], v[220:223], 0
	v_mfma_i32_16x16x64_i8 v[80:83], v[144:147], v[224:227], v[80:83]
	v_mfma_i32_16x16x64_i8 v[96:99], v[144:147], v[216:219], 0
	v_mfma_i32_16x16x64_i8 v[96:99], v[140:143], v[212:215], v[96:99]
	v_mfma_i32_16x16x64_i8 v[112:115], v[140:143], v[204:207], 0
	v_mfma_i32_16x16x64_i8 v[112:115], v[144:147], v[208:211], v[112:115]
	v_mfma_i32_16x16x64_i8 v[128:131], v[144:147], v[188:191], 0
	v_mfma_i32_16x16x64_i8 v[128:131], v[140:143], v[184:187], v[128:131]
	v_mfma_i32_16x16x64_i8 v[132:135], v[160:163], v[184:187], 0
	v_mfma_i32_16x16x64_i8 v[132:135], v[172:175], v[188:191], v[132:135]
	v_mfma_i32_16x16x64_i8 v[116:119], v[172:175], v[208:211], 0
	v_mfma_i32_16x16x64_i8 v[116:119], v[160:163], v[204:207], v[116:119]
	v_mfma_i32_16x16x64_i8 v[100:103], v[160:163], v[212:215], 0
	v_mfma_i32_16x16x64_i8 v[100:103], v[172:175], v[216:219], v[100:103]
	v_mfma_i32_16x16x64_i8 v[84:87], v[172:175], v[224:227], 0
	v_mfma_i32_16x16x64_i8 v[84:87], v[160:163], v[220:223], v[84:87]
	v_mfma_i32_16x16x64_i8 v[76:79], v[176:179], v[220:223], 0
	v_mfma_i32_16x16x64_i8 v[76:79], v[180:183], v[224:227], v[76:79]
	v_mfma_i32_16x16x64_i8 v[92:95], v[180:183], v[216:219], 0
	v_mfma_i32_16x16x64_i8 v[92:95], v[176:179], v[212:215], v[92:95]
	v_mfma_i32_16x16x64_i8 v[108:111], v[176:179], v[204:207], 0
	v_mfma_i32_16x16x64_i8 v[108:111], v[180:183], v[208:211], v[108:111]
	v_mfma_i32_16x16x64_i8 v[124:127], v[180:183], v[188:191], 0
	v_mfma_i32_16x16x64_i8 v[124:127], v[176:179], v[184:187], v[124:127]
	s_setprio 0
	s_barrier
	s_add_i32 s64, s64, s47
	s_mov_b32 m0, s64
	ds_read_b128 v[184:187], v171 offset:16384
	ds_read_b128 v[188:191], v171 offset:17408
	ds_read_b128 v[204:207], v171 offset:18432
	ds_read_b128 v[208:211], v171 offset:19456
	ds_read_b128 v[212:215], v171 offset:20480
	ds_read_b128 v[216:219], v171 offset:21504
	ds_read_b128 v[220:223], v171 offset:22528
	ds_read_b128 v[224:227], v171 offset:23552
	global_load_lds_dwordx4 v2, s[44:45]
	s_add_i32 m0, s64, 0x2000
	s_add_u32 s64, s44, 0x80000
	s_addc_u32 s65, s45, 0
	s_add_i32 s67, s67, s47
	global_load_lds_dwordx4 v148, s[44:45]
	s_mov_b32 m0, s67
	v_lshl_add_u64 v[242:243], s[48:49], 0, v[150:151]
	global_load_lds_dwordx4 v2, s[64:65]
	s_add_i32 m0, s67, 0x2000
	s_nop 0
	global_load_lds_dwordx4 v148, s[64:65]
	v_lshl_add_u64 v[240:241], s[48:49], 0, v[152:153]
	s_waitcnt vmcnt(6)
	s_waitcnt lgkmcnt(0)
	s_barrier
; #define PG8_STAGE(bufoff, gbase, voff) do { _Pragma("unroll") for (int _i = 0; _i < 2; ++_i) \
;         __builtin_amdgcn_global_load_lds((const unsigned*)((const char*)(gbase) + (voff)[_i]), (PG8_LAS unsigned*)(lds + (bufoff) + ldsw + _i * 8192), 16, 0, 0); } while (0)
; #define PG8_LDA(dst, b, h) do { _Pragma("unroll") for (int m = 0; m < 4; ++m) _Pragma("unroll") for (int k = 0; k < 2; ++k) dst[m][k] = *(const PG8_LAS bf16x8*)(lds + PG8_SA(b, h) + aoff + m * 2048 + k * 1024); } while (0)
; #define PG8_LDB(dst, b, h) do { _Pragma("unroll") for (int n = 0; n < 2; ++n) _Pragma("unroll") for (int k = 0; k < 2; ++k) dst[n][k] = *(const PG8_LAS bf16x8*)(lds + PG8_SB(b, h) + boff + n * 2048 + k * 1024); } while (0)
; #define PG8_WAIT_V(n) asm volatile("s_waitcnt vmcnt(" #n ")" ::: "memory")
; #define PG8_WAIT_L(n) asm volatile("s_waitcnt lgkmcnt(" #n ")" ::: "memory")
; #define PG8_BAR __builtin_amdgcn_s_barrier()
; #define PG8_SCHED __builtin_amdgcn_sched_barrier(0)
; template <class Epi, class Sched, bool ALIGN_EPI = false, bool SP2 = false, bool I8 = false>
; __device__ __forceinline__ void gemm_phase(PG8_LAS unsigned char* lds, const Gemm g, const Sched& S, const Epi& E) {
;     ...
;             PG8_WAIT_V(8); PG8_WAIT_L(0); PG8_BAR; PG8_MMA(1, 0, At, B0); PG8_MMA(1, 1, At, B1); PG8_BAR; PG8_SCHED;
;             PG8_LDB(B0, 1, 0); PG8_LDB(B1, 1, 1); PG8_SCHED; PG8_LDA(At, 1, 0); PG8_STAGE(PG8_SA(0, 1), a2 + hstep, voffA);
;             PG8_WAIT_V(8); PG8_WAIT_L(0); PG8_BAR; PG8_MMA(0, 0, At, B0); PG8_MMA(0, 1, At, B1); PG8_BAR; PG8_SCHED;
;             PG8_LDA(At, 1, 1); PG8_STAGE(PG8_SB(1, 0), b3, voffB); PG8_STAGE(PG8_SB(1, 1), b3 + hstep, voffB); PG8_STAGE(PG8_SA(1, 0), a3, voffA);
;             PG8_WAIT_V(8); PG8_WAIT_L(0); PG8_BAR; PG8_MMA(1, 0, At, B0); PG8_MMA(1, 1, At, B1); PG8_BAR; PG8_SCHED;
	s_setprio 1
	s_waitcnt lgkmcnt(0)
	v_mfma_i32_16x16x64_i8 v[72:75], v[36:39], v[184:187], 0
	v_mfma_i32_16x16x64_i8 v[72:75], v[44:47], v[188:191], v[72:75]
	v_mfma_i32_16x16x64_i8 v[56:59], v[44:47], v[208:211], 0
	v_mfma_i32_16x16x64_i8 v[56:59], v[36:39], v[204:207], v[56:59]
	v_mfma_i32_16x16x64_i8 v[32:35], v[36:39], v[212:215], 0
	v_mfma_i32_16x16x64_i8 v[32:35], v[44:47], v[216:219], v[32:35]
	v_mfma_i32_16x16x64_i8 v[16:19], v[44:47], v[224:227], 0
	v_mfma_i32_16x16x64_i8 v[16:19], v[36:39], v[220:223], v[16:19]
	v_mfma_i32_16x16x64_i8 v[8:11], v[140:143], v[220:223], 0
	v_mfma_i32_16x16x64_i8 v[8:11], v[144:147], v[224:227], v[8:11]
	v_mfma_i32_16x16x64_i8 v[24:27], v[144:147], v[216:219], 0
	v_mfma_i32_16x16x64_i8 v[24:27], v[140:143], v[212:215], v[24:27]
	v_mfma_i32_16x16x64_i8 v[48:51], v[140:143], v[204:207], 0
	v_mfma_i32_16x16x64_i8 v[48:51], v[144:147], v[208:211], v[48:51]
	v_mfma_i32_16x16x64_i8 v[64:67], v[144:147], v[188:191], 0
	v_mfma_i32_16x16x64_i8 v[64:67], v[140:143], v[184:187], v[64:67]
	v_mfma_i32_16x16x64_i8 v[36:39], v[160:163], v[184:187], 0
	v_mfma_i32_16x16x64_i8 v[36:39], v[172:175], v[188:191], v[36:39]
	v_mfma_i32_16x16x64_i8 v[52:55], v[172:175], v[208:211], 0
	v_mfma_i32_16x16x64_i8 v[52:55], v[160:163], v[204:207], v[52:55]
	v_mfma_i32_16x16x64_i8 v[28:31], v[160:163], v[212:215], 0
	v_mfma_i32_16x16x64_i8 v[28:31], v[172:175], v[216:219], v[28:31]
	v_mfma_i32_16x16x64_i8 v[12:15], v[172:175], v[224:227], 0
	v_mfma_i32_16x16x64_i8 v[12:15], v[160:163], v[220:223], v[12:15]
	v_mfma_i32_16x16x64_i8 v[4:7], v[176:179], v[220:223], 0
	v_mfma_i32_16x16x64_i8 v[4:7], v[180:183], v[224:227], v[4:7]
	v_mfma_i32_16x16x64_i8 v[20:23], v[180:183], v[216:219], 0
	v_mfma_i32_16x16x64_i8 v[20:23], v[176:179], v[212:215], v[20:23]
	v_mfma_i32_16x16x64_i8 v[40:43], v[176:179], v[204:207], 0
	v_mfma_i32_16x16x64_i8 v[40:43], v[180:183], v[208:211], v[40:43]
	v_mfma_i32_16x16x64_i8 v[44:47], v[180:183], v[188:191], 0
	v_mfma_i32_16x16x64_i8 v[44:47], v[176:179], v[184:187], v[44:47]
	s_setprio 0
	s_barrier
	s_mov_b32 m0, s50
	s_nop 0
	global_load_lds_dwordx4 v[240:241], off
	s_mov_b32 m0, s51
	s_nop 0
	global_load_lds_dwordx4 v[242:243], off
	s_add_i32 s64, 0, 0x18000
	s_add_i32 s65, 0, 0x1c000
	v_add_u32_e32 v144, s64, v167
	v_add_u32_e32 v158, s65, v167
	ds_read_b128 v[60:63], v144
	ds_read_b128 v[68:71], v144 offset:1024
	ds_read_b128 v[140:143], v144 offset:2048
	ds_read_b128 v[144:147], v144 offset:3072
	ds_read_b128 v[160:163], v158
	ds_read_b128 v[172:175], v158 offset:1024
	ds_read_b128 v[176:179], v158 offset:2048
	ds_read_b128 v[180:183], v158 offset:3072
	s_add_u32 s48, s48, 0x80000
	s_addc_u32 s49, s49, 0
	s_mov_b32 m0, s52
	ds_read_b128 v[184:187], v171 offset:32768
	ds_read_b128 v[188:191], v171 offset:33792
	ds_read_b128 v[204:207], v171 offset:34816
	ds_read_b128 v[208:211], v171 offset:35840
	ds_read_b128 v[212:215], v171 offset:36864
	ds_read_b128 v[216:219], v171 offset:37888
	ds_read_b128 v[220:223], v171 offset:38912
	ds_read_b128 v[224:227], v171 offset:39936
	global_load_lds_dwordx4 v152, s[48:49]
	s_mov_b32 m0, s53
	s_nop 0
	global_load_lds_dwordx4 v150, s[48:49]
	s_waitcnt vmcnt(8)
	s_waitcnt lgkmcnt(0)
	s_barrier
	s_setprio 1
	s_waitcnt lgkmcnt(0)
	v_mfma_i32_16x16x64_i8 v[136:139], v[60:63], v[184:187], v[136:139]
	v_mfma_i32_16x16x64_i8 v[136:139], v[68:71], v[188:191], v[136:139]
	v_mfma_i32_16x16x64_i8 v[120:123], v[68:71], v[208:211], v[120:123]
	v_mfma_i32_16x16x64_i8 v[120:123], v[60:63], v[204:207], v[120:123]
	v_mfma_i32_16x16x64_i8 v[104:107], v[60:63], v[212:215], v[104:107]
	v_mfma_i32_16x16x64_i8 v[104:107], v[68:71], v[216:219], v[104:107]
	v_mfma_i32_16x16x64_i8 v[88:91], v[68:71], v[224:227], v[88:91]
	v_mfma_i32_16x16x64_i8 v[88:91], v[60:63], v[220:223], v[88:91]
	v_mfma_i32_16x16x64_i8 v[80:83], v[140:143], v[220:223], v[80:83]
	v_mfma_i32_16x16x64_i8 v[80:83], v[144:147], v[224:227], v[80:83]
	v_mfma_i32_16x16x64_i8 v[96:99], v[144:147], v[216:219], v[96:99]
	v_mfma_i32_16x16x64_i8 v[96:99], v[140:143], v[212:215], v[96:99]
	v_mfma_i32_16x16x64_i8 v[112:115], v[140:143], v[204:207], v[112:115]
	v_mfma_i32_16x16x64_i8 v[112:115], v[144:147], v[208:211], v[112:115]
	v_mfma_i32_16x16x64_i8 v[128:131], v[144:147], v[188:191], v[128:131]
	v_mfma_i32_16x16x64_i8 v[128:131], v[140:143], v[184:187], v[128:131]
	v_mfma_i32_16x16x64_i8 v[132:135], v[160:163], v[184:187], v[132:135]
	v_mfma_i32_16x16x64_i8 v[132:135], v[172:175], v[188:191], v[132:135]
	v_mfma_i32_16x16x64_i8 v[116:119], v[172:175], v[208:211], v[116:119]
	v_mfma_i32_16x16x64_i8 v[116:119], v[160:163], v[204:207], v[116:119]
	v_mfma_i32_16x16x64_i8 v[100:103], v[160:163], v[212:215], v[100:103]
	v_mfma_i32_16x16x64_i8 v[100:103], v[172:175], v[216:219], v[100:103]
	v_mfma_i32_16x16x64_i8 v[84:87], v[172:175], v[224:227], v[84:87]
	v_mfma_i32_16x16x64_i8 v[84:87], v[160:163], v[220:223], v[84:87]
	v_mfma_i32_16x16x64_i8 v[76:79], v[176:179], v[220:223], v[76:79]
	v_mfma_i32_16x16x64_i8 v[76:79], v[180:183], v[224:227], v[76:79]
	v_mfma_i32_16x16x64_i8 v[92:95], v[180:183], v[216:219], v[92:95]
	v_mfma_i32_16x16x64_i8 v[92:95], v[176:179], v[212:215], v[92:95]
	v_mfma_i32_16x16x64_i8 v[108:111], v[176:179], v[204:207], v[108:111]
	v_mfma_i32_16x16x64_i8 v[108:111], v[180:183], v[208:211], v[108:111]
	v_mfma_i32_16x16x64_i8 v[124:127], v[180:183], v[188:191], v[124:127]
	v_mfma_i32_16x16x64_i8 v[124:127], v[176:179], v[184:187], v[124:127]
	s_setprio 0
	s_barrier
	s_add_u32 s98, s44, 0x80
	s_addc_u32 s99, s45, 0
	s_add_i32 s48, s64, s47
	s_mov_b32 m0, s48
	ds_read_b128 v[184:187], v171 offset:49152
	ds_read_b128 v[188:191], v171 offset:50176
	ds_read_b128 v[204:207], v171 offset:51200
	ds_read_b128 v[208:211], v171 offset:52224
	ds_read_b128 v[212:215], v171 offset:53248
	ds_read_b128 v[216:219], v171 offset:54272
	ds_read_b128 v[220:223], v171 offset:55296
	ds_read_b128 v[224:227], v171 offset:56320
	global_load_lds_dwordx4 v2, s[98:99]
	s_add_i32 m0, s48, 0x2000
	s_add_u32 s44, s44, 0x80080
	s_addc_u32 s45, s45, 0
	s_add_i32 s48, s65, s47
	global_load_lds_dwordx4 v148, s[98:99]
	s_mov_b32 m0, s48
	s_nop 0
	global_load_lds_dwordx4 v2, s[44:45]
	s_add_i32 m0, s48, 0x2000
	s_nop 0
	global_load_lds_dwordx4 v148, s[44:45]
	s_cmp_eq_u32 s61, 28
	s_cbranch_scc0 .Ldefer_1591_peel
	v_lshl_add_u64 v[164:165], v[240:241], 0, s[84:85]
	s_mov_b32 m0, s54
	s_nop 0
	global_load_lds_dwordx4 v[164:165], off
	v_lshl_add_u64 v[164:165], v[242:243], 0, s[84:85]
	s_mov_b32 m0, s55
	s_nop 0
	global_load_lds_dwordx4 v[164:165], off

; #define PG8_STAGE(bufoff, gbase, voff) do { _Pragma("unroll") for (int _i = 0; _i < 2; ++_i) \
;         __builtin_amdgcn_global_load_lds((const unsigned*)((const char*)(gbase) + (voff)[_i]), (PG8_LAS unsigned*)(lds + (bufoff) + ldsw + _i * 8192), 16, 0, 0); } while (0)
; #define PG8_LDA(dst, b, h) do { _Pragma("unroll") for (int m = 0; m < 4; ++m) _Pragma("unroll") for (int k = 0; k < 2; ++k) dst[m][k] = *(const PG8_LAS bf16x8*)(lds + PG8_SA(b, h) + aoff + m * 2048 + k * 1024); } while (0)
; #define PG8_LDB(dst, b, h) do { _Pragma("unroll") for (int n = 0; n < 2; ++n) _Pragma("unroll") for (int k = 0; k < 2; ++k) dst[n][k] = *(const PG8_LAS bf16x8*)(lds + PG8_SB(b, h) + boff + n * 2048 + k * 1024); } while (0)
; #define PG8_WAIT_V(n) asm volatile("s_waitcnt vmcnt(" #n ")" ::: "memory")
; #define PG8_WAIT_L(n) asm volatile("s_waitcnt lgkmcnt(" #n ")" ::: "memory")
; #define PG8_BAR __builtin_amdgcn_s_barrier()
; #define PG8_SCHED __builtin_amdgcn_sched_barrier(0)
; template <class Epi, class Sched, bool ALIGN_EPI = false, bool SP2 = false, bool I8 = false>
; __device__ __forceinline__ void gemm_phase(PG8_LAS unsigned char* lds, const Gemm g, const Sched& S, const Epi& E) {
;     ...
;             const bool last = (t == nt - 2);
;             const char* a1 = cA + (size_t)(t + 1) * kstep;
;             const char* a2 = last ? nA : cA + (size_t)(t + 2) * kstep; const char* b2 = last ? nB : cB + (size_t)(t + 2) * kstep;
;             const char* a3 = a2 + kstep; const char* b3 = b2 + kstep;
;             if (last && has_next) S.a_ready(nxt);
;             if constexpr (SP2) {
;             PG8_LDB(B0, 0, 0); PG8_LDB(B1, 0, 1); PG8_SCHED; PG8_LDA(At, 0, 0); PG8_STAGE(PG8_SA(1, 1), a1 + hstep, voffA);
;             PG8_WAIT_V(8); PG8_WAIT_L(0); PG8_BAR; PG8_MMA(0, 0, At, B0); PG8_MMA(0, 1, At, B1); PG8_BAR; PG8_SCHED;
;             PG8_LDA(At, 0, 1); PG8_STAGE(PG8_SB(0, 0), b2, voffB); PG8_STAGE(PG8_SB(0, 1), b2 + hstep, voffB); PG8_STAGE(PG8_SA(0, 0), a2, voffA);
;             PG8_WAIT_V(8); PG8_WAIT_L(0); PG8_BAR; PG8_MMA(1, 0, At, B0); PG8_MMA(1, 1, At, B1); PG8_BAR; PG8_SCHED;
.LBB0_1591:
	s_add_u32 s44, s40, 0xfff80080
	s_addc_u32 s45, s41, -1
	s_add_i32 s64, 0, 0x10000
	s_cmp_eq_u32 s61, 28
	s_cselect_b32 s49, s25, s45
	s_cselect_b32 s48, s57, s44
	s_cselect_b32 s45, s23, s60
	s_cselect_b32 s44, s58, s59
	s_add_i32 s67, 0, 0x14000
	v_add_u32_e32 v144, s64, v167
	v_add_u32_e32 v158, s67, v167
	ds_read_b128 v[36:39], v144
	ds_read_b128 v[44:47], v144 offset:1024
	ds_read_b128 v[140:143], v144 offset:2048
	ds_read_b128 v[144:147], v144 offset:3072
	ds_read_b128 v[160:163], v158
	ds_read_b128 v[172:175], v158 offset:1024
	ds_read_b128 v[176:179], v158 offset:2048
	ds_read_b128 v[180:183], v158 offset:3072
	v_lshl_add_u64 v[164:165], v[240:241], 0, s[84:85]
	s_mov_b32 m0, s54
	s_nop 0
	global_load_lds_dwordx4 v[164:165], off
	v_lshl_add_u64 v[164:165], v[242:243], 0, s[84:85]
	s_mov_b32 m0, s55
	s_nop 0
	global_load_lds_dwordx4 v[164:165], off
	s_add_i32 m0, s50, 0xc000
	ds_read_b128 v[184:187], v171
	ds_read_b128 v[188:191], v171 offset:1024
	ds_read_b128 v[204:207], v171 offset:2048
	ds_read_b128 v[208:211], v171 offset:3072
	ds_read_b128 v[212:215], v171 offset:4096
	ds_read_b128 v[216:219], v171 offset:5120
	ds_read_b128 v[220:223], v171 offset:6144
	ds_read_b128 v[224:227], v171 offset:7168
	global_load_lds_dwordx4 v154, s[40:41]
	s_add_i32 m0, s50, 0xe000
	s_nop 0
	global_load_lds_dwordx4 v156, s[40:41]
	s_waitcnt vmcnt(8)
	s_waitcnt lgkmcnt(0)
	s_barrier
	s_setprio 1
	s_waitcnt lgkmcnt(0)
	v_mfma_i32_16x16x64_i8 v[136:139], v[36:39], v[184:187], v[136:139]
	v_mfma_i32_16x16x64_i8 v[136:139], v[44:47], v[188:191], v[136:139]
	v_mfma_i32_16x16x64_i8 v[120:123], v[44:47], v[208:211], v[120:123]
	v_mfma_i32_16x16x64_i8 v[120:123], v[36:39], v[204:207], v[120:123]
	v_mfma_i32_16x16x64_i8 v[104:107], v[36:39], v[212:215], v[104:107]
	v_mfma_i32_16x16x64_i8 v[104:107], v[44:47], v[216:219], v[104:107]
	v_mfma_i32_16x16x64_i8 v[88:91], v[44:47], v[224:227], v[88:91]
	v_mfma_i32_16x16x64_i8 v[88:91], v[36:39], v[220:223], v[88:91]
	v_mfma_i32_16x16x64_i8 v[80:83], v[140:143], v[220:223], v[80:83]
	v_mfma_i32_16x16x64_i8 v[80:83], v[144:147], v[224:227], v[80:83]
	v_mfma_i32_16x16x64_i8 v[96:99], v[144:147], v[216:219], v[96:99]
	v_mfma_i32_16x16x64_i8 v[96:99], v[140:143], v[212:215], v[96:99]
	v_mfma_i32_16x16x64_i8 v[112:115], v[140:143], v[204:207], v[112:115]
	v_mfma_i32_16x16x64_i8 v[112:115], v[144:147], v[208:211], v[112:115]
	v_mfma_i32_16x16x64_i8 v[128:131], v[144:147], v[188:191], v[128:131]
	v_mfma_i32_16x16x64_i8 v[128:131], v[140:143], v[184:187], v[128:131]
	v_mfma_i32_16x16x64_i8 v[132:135], v[160:163], v[184:187], v[132:135]
	v_mfma_i32_16x16x64_i8 v[132:135], v[172:175], v[188:191], v[132:135]
	v_mfma_i32_16x16x64_i8 v[116:119], v[172:175], v[208:211], v[116:119]
	v_mfma_i32_16x16x64_i8 v[116:119], v[160:163], v[204:207], v[116:119]
	v_mfma_i32_16x16x64_i8 v[100:103], v[160:163], v[212:215], v[100:103]
	v_mfma_i32_16x16x64_i8 v[100:103], v[172:175], v[216:219], v[100:103]
	v_mfma_i32_16x16x64_i8 v[84:87], v[172:175], v[224:227], v[84:87]
	v_mfma_i32_16x16x64_i8 v[84:87], v[160:163], v[220:223], v[84:87]
	v_mfma_i32_16x16x64_i8 v[76:79], v[176:179], v[220:223], v[76:79]
	v_mfma_i32_16x16x64_i8 v[76:79], v[180:183], v[224:227], v[76:79]
	v_mfma_i32_16x16x64_i8 v[92:95], v[180:183], v[216:219], v[92:95]
	v_mfma_i32_16x16x64_i8 v[92:95], v[176:179], v[212:215], v[92:95]
	v_mfma_i32_16x16x64_i8 v[108:111], v[176:179], v[204:207], v[108:111]
	v_mfma_i32_16x16x64_i8 v[108:111], v[180:183], v[208:211], v[108:111]
	v_mfma_i32_16x16x64_i8 v[124:127], v[180:183], v[188:191], v[124:127]
	v_mfma_i32_16x16x64_i8 v[124:127], v[176:179], v[184:187], v[124:127]
	s_setprio 0
	s_barrier
	s_add_i32 s64, s64, s47
	s_mov_b32 m0, s64
	ds_read_b128 v[184:187], v171 offset:16384
	ds_read_b128 v[188:191], v171 offset:17408
	ds_read_b128 v[204:207], v171 offset:18432
	ds_read_b128 v[208:211], v171 offset:19456
	ds_read_b128 v[212:215], v171 offset:20480
	ds_read_b128 v[216:219], v171 offset:21504
	ds_read_b128 v[220:223], v171 offset:22528
	ds_read_b128 v[224:227], v171 offset:23552
	global_load_lds_dwordx4 v2, s[44:45]
	s_add_i32 m0, s64, 0x2000
	s_add_u32 s64, s44, 0x80000
	s_addc_u32 s65, s45, 0
	s_add_i32 s67, s67, s47
	global_load_lds_dwordx4 v148, s[44:45]
	s_mov_b32 m0, s67
	v_lshl_add_u64 v[242:243], s[48:49], 0, v[150:151]
	global_load_lds_dwordx4 v2, s[64:65]
	s_add_i32 m0, s67, 0x2000
	s_nop 0
	global_load_lds_dwordx4 v148, s[64:65]
	v_lshl_add_u64 v[240:241], s[48:49], 0, v[152:153]
	s_waitcnt vmcnt(6)
	s_waitcnt lgkmcnt(0)
	s_barrier
; #define PG8_STAGE(bufoff, gbase, voff) do { _Pragma("unroll") for (int _i = 0; _i < 2; ++_i) \
;         __builtin_amdgcn_global_load_lds((const unsigned*)((const char*)(gbase) + (voff)[_i]), (PG8_LAS unsigned*)(lds + (bufoff) + ldsw + _i * 8192), 16, 0, 0); } while (0)
; #define PG8_LDA(dst, b, h) do { _Pragma("unroll") for (int m = 0; m < 4; ++m) _Pragma("unroll") for (int k = 0; k < 2; ++k) dst[m][k] = *(const PG8_LAS bf16x8*)(lds + PG8_SA(b, h) + aoff + m * 2048 + k * 1024); } while (0)
; #define PG8_LDB(dst, b, h) do { _Pragma("unroll") for (int n = 0; n < 2; ++n) _Pragma("unroll") for (int k = 0; k < 2; ++k) dst[n][k] = *(const PG8_LAS bf16x8*)(lds + PG8_SB(b, h) + boff + n * 2048 + k * 1024); } while (0)
; #define PG8_WAIT_V(n) asm volatile("s_waitcnt vmcnt(" #n ")" ::: "memory")
; #define PG8_WAIT_L(n) asm volatile("s_waitcnt lgkmcnt(" #n ")" ::: "memory")
; #define PG8_BAR __builtin_amdgcn_s_barrier()
; #define PG8_SCHED __builtin_amdgcn_sched_barrier(0)
; template <class Epi, class Sched, bool ALIGN_EPI = false, bool SP2 = false, bool I8 = false>
; __device__ __forceinline__ void gemm_phase(PG8_LAS unsigned char* lds, const Gemm g, const Sched& S, const Epi& E) {
;     ...
;             PG8_WAIT_V(8); PG8_WAIT_L(0); PG8_BAR; PG8_MMA(1, 0, At, B0); PG8_MMA(1, 1, At, B1); PG8_BAR; PG8_SCHED;
;             PG8_LDB(B0, 1, 0); PG8_LDB(B1, 1, 1); PG8_SCHED; PG8_LDA(At, 1, 0); PG8_STAGE(PG8_SA(0, 1), a2 + hstep, voffA);
;             PG8_WAIT_V(8); PG8_WAIT_L(0); PG8_BAR; PG8_MMA(0, 0, At, B0); PG8_MMA(0, 1, At, B1); PG8_BAR; PG8_SCHED;
;             PG8_LDA(At, 1, 1); PG8_STAGE(PG8_SB(1, 0), b3, voffB); PG8_STAGE(PG8_SB(1, 1), b3 + hstep, voffB); PG8_STAGE(PG8_SA(1, 0), a3, voffA);
;             PG8_WAIT_V(8); PG8_WAIT_L(0); PG8_BAR; PG8_MMA(1, 0, At, B0); PG8_MMA(1, 1, At, B1); PG8_BAR; PG8_SCHED;
	s_setprio 1
	s_waitcnt lgkmcnt(0)
	v_mfma_i32_16x16x64_i8 v[72:75], v[36:39], v[184:187], v[72:75]
	v_mfma_i32_16x16x64_i8 v[72:75], v[44:47], v[188:191], v[72:75]
	v_mfma_i32_16x16x64_i8 v[56:59], v[44:47], v[208:211], v[56:59]
	v_mfma_i32_16x16x64_i8 v[56:59], v[36:39], v[204:207], v[56:59]
	v_mfma_i32_16x16x64_i8 v[32:35], v[36:39], v[212:215], v[32:35]
	v_mfma_i32_16x16x64_i8 v[32:35], v[44:47], v[216:219], v[32:35]
	v_mfma_i32_16x16x64_i8 v[16:19], v[44:47], v[224:227], v[16:19]
	v_mfma_i32_16x16x64_i8 v[16:19], v[36:39], v[220:223], v[16:19]
	v_mfma_i32_16x16x64_i8 v[8:11], v[140:143], v[220:223], v[8:11]
	v_mfma_i32_16x16x64_i8 v[8:11], v[144:147], v[224:227], v[8:11]
	v_mfma_i32_16x16x64_i8 v[24:27], v[144:147], v[216:219], v[24:27]
	v_mfma_i32_16x16x64_i8 v[24:27], v[140:143], v[212:215], v[24:27]
	v_mfma_i32_16x16x64_i8 v[48:51], v[140:143], v[204:207], v[48:51]
	v_mfma_i32_16x16x64_i8 v[48:51], v[144:147], v[208:211], v[48:51]
	v_mfma_i32_16x16x64_i8 v[64:67], v[144:147], v[188:191], v[64:67]
	v_mfma_i32_16x16x64_i8 v[64:67], v[140:143], v[184:187], v[64:67]
	v_mfma_i32_16x16x64_i8 v[36:39], v[160:163], v[184:187], v[68:71]
	v_mfma_i32_16x16x64_i8 v[36:39], v[172:175], v[188:191], v[36:39]
	v_mfma_i32_16x16x64_i8 v[52:55], v[172:175], v[208:211], v[52:55]
	v_mfma_i32_16x16x64_i8 v[52:55], v[160:163], v[204:207], v[52:55]
	v_mfma_i32_16x16x64_i8 v[28:31], v[160:163], v[212:215], v[28:31]
	v_mfma_i32_16x16x64_i8 v[28:31], v[172:175], v[216:219], v[28:31]
	v_mfma_i32_16x16x64_i8 v[12:15], v[172:175], v[224:227], v[12:15]
	v_mfma_i32_16x16x64_i8 v[12:15], v[160:163], v[220:223], v[12:15]
	v_mfma_i32_16x16x64_i8 v[4:7], v[176:179], v[220:223], v[4:7]
	v_mfma_i32_16x16x64_i8 v[4:7], v[180:183], v[224:227], v[4:7]
	v_mfma_i32_16x16x64_i8 v[20:23], v[180:183], v[216:219], v[20:23]
	v_mfma_i32_16x16x64_i8 v[20:23], v[176:179], v[212:215], v[20:23]
	v_mfma_i32_16x16x64_i8 v[40:43], v[176:179], v[204:207], v[40:43]
	v_mfma_i32_16x16x64_i8 v[40:43], v[180:183], v[208:211], v[40:43]
	v_mfma_i32_16x16x64_i8 v[44:47], v[180:183], v[188:191], v[60:63]
	v_mfma_i32_16x16x64_i8 v[44:47], v[176:179], v[184:187], v[44:47]
	s_setprio 0
	s_barrier
	s_mov_b32 m0, s50
	s_nop 0
	global_load_lds_dwordx4 v[240:241], off
	s_mov_b32 m0, s51
	s_nop 0
	global_load_lds_dwordx4 v[242:243], off
	s_add_i32 s64, 0, 0x18000
	s_add_i32 s65, 0, 0x1c000
	v_add_u32_e32 v144, s64, v167
	v_add_u32_e32 v158, s65, v167
	ds_read_b128 v[60:63], v144
	ds_read_b128 v[68:71], v144 offset:1024
	ds_read_b128 v[140:143], v144 offset:2048
	ds_read_b128 v[144:147], v144 offset:3072
	ds_read_b128 v[160:163], v158
	ds_read_b128 v[172:175], v158 offset:1024
	ds_read_b128 v[176:179], v158 offset:2048
	ds_read_b128 v[180:183], v158 offset:3072
	s_add_u32 s48, s48, 0x80000
	s_addc_u32 s49, s49, 0
	s_mov_b32 m0, s52
	ds_read_b128 v[184:187], v171 offset:32768
	ds_read_b128 v[188:191], v171 offset:33792
	ds_read_b128 v[204:207], v171 offset:34816
	ds_read_b128 v[208:211], v171 offset:35840
	ds_read_b128 v[212:215], v171 offset:36864
	ds_read_b128 v[216:219], v171 offset:37888
	ds_read_b128 v[220:223], v171 offset:38912
	ds_read_b128 v[224:227], v171 offset:39936
	global_load_lds_dwordx4 v152, s[48:49]
	s_mov_b32 m0, s53
	s_nop 0
	global_load_lds_dwordx4 v150, s[48:49]
	s_waitcnt vmcnt(8)
	s_waitcnt lgkmcnt(0)
	s_barrier
	s_setprio 1
	s_waitcnt lgkmcnt(0)
	v_mfma_i32_16x16x64_i8 v[136:139], v[60:63], v[184:187], v[136:139]
	v_mfma_i32_16x16x64_i8 v[136:139], v[68:71], v[188:191], v[136:139]
	v_mfma_i32_16x16x64_i8 v[120:123], v[68:71], v[208:211], v[120:123]
	v_mfma_i32_16x16x64_i8 v[120:123], v[60:63], v[204:207], v[120:123]
	v_mfma_i32_16x16x64_i8 v[104:107], v[60:63], v[212:215], v[104:107]
	v_mfma_i32_16x16x64_i8 v[104:107], v[68:71], v[216:219], v[104:107]
	v_mfma_i32_16x16x64_i8 v[88:91], v[68:71], v[224:227], v[88:91]
	v_mfma_i32_16x16x64_i8 v[88:91], v[60:63], v[220:223], v[88:91]
	v_mfma_i32_16x16x64_i8 v[80:83], v[140:143], v[220:223], v[80:83]
	v_mfma_i32_16x16x64_i8 v[80:83], v[144:147], v[224:227], v[80:83]
	v_mfma_i32_16x16x64_i8 v[96:99], v[144:147], v[216:219], v[96:99]
	v_mfma_i32_16x16x64_i8 v[96:99], v[140:143], v[212:215], v[96:99]
	v_mfma_i32_16x16x64_i8 v[112:115], v[140:143], v[204:207], v[112:115]
	v_mfma_i32_16x16x64_i8 v[112:115], v[144:147], v[208:211], v[112:115]
	v_mfma_i32_16x16x64_i8 v[128:131], v[144:147], v[188:191], v[128:131]
	v_mfma_i32_16x16x64_i8 v[128:131], v[140:143], v[184:187], v[128:131]
	v_mfma_i32_16x16x64_i8 v[132:135], v[160:163], v[184:187], v[132:135]
	v_mfma_i32_16x16x64_i8 v[132:135], v[172:175], v[188:191], v[132:135]
	v_mfma_i32_16x16x64_i8 v[116:119], v[172:175], v[208:211], v[116:119]
	v_mfma_i32_16x16x64_i8 v[116:119], v[160:163], v[204:207], v[116:119]
	v_mfma_i32_16x16x64_i8 v[100:103], v[160:163], v[212:215], v[100:103]
	v_mfma_i32_16x16x64_i8 v[100:103], v[172:175], v[216:219], v[100:103]
	v_mfma_i32_16x16x64_i8 v[84:87], v[172:175], v[224:227], v[84:87]
	v_mfma_i32_16x16x64_i8 v[84:87], v[160:163], v[220:223], v[84:87]
	v_mfma_i32_16x16x64_i8 v[76:79], v[176:179], v[220:223], v[76:79]
	v_mfma_i32_16x16x64_i8 v[76:79], v[180:183], v[224:227], v[76:79]
	v_mfma_i32_16x16x64_i8 v[92:95], v[180:183], v[216:219], v[92:95]
	v_mfma_i32_16x16x64_i8 v[92:95], v[176:179], v[212:215], v[92:95]
	v_mfma_i32_16x16x64_i8 v[108:111], v[176:179], v[204:207], v[108:111]
	v_mfma_i32_16x16x64_i8 v[108:111], v[180:183], v[208:211], v[108:111]
	v_mfma_i32_16x16x64_i8 v[124:127], v[180:183], v[188:191], v[124:127]
	v_mfma_i32_16x16x64_i8 v[124:127], v[176:179], v[184:187], v[124:127]
	s_setprio 0
	s_barrier
	s_add_u32 s98, s44, 0x80
	s_addc_u32 s99, s45, 0
	s_add_i32 s48, s64, s47
	s_mov_b32 m0, s48
	ds_read_b128 v[184:187], v171 offset:49152
	ds_read_b128 v[188:191], v171 offset:50176
	ds_read_b128 v[204:207], v171 offset:51200
	ds_read_b128 v[208:211], v171 offset:52224
	ds_read_b128 v[212:215], v171 offset:53248
	ds_read_b128 v[216:219], v171 offset:54272
	ds_read_b128 v[220:223], v171 offset:55296
	ds_read_b128 v[224:227], v171 offset:56320
	global_load_lds_dwordx4 v2, s[98:99]
	s_add_i32 m0, s48, 0x2000
	s_add_u32 s44, s44, 0x80080
	s_addc_u32 s45, s45, 0
	s_add_i32 s48, s65, s47
	global_load_lds_dwordx4 v148, s[98:99]
	s_mov_b32 m0, s48
	s_nop 0
	global_load_lds_dwordx4 v2, s[44:45]
	s_add_i32 m0, s48, 0x2000
	s_nop 0
	global_load_lds_dwordx4 v148, s[44:45]
	s_cmp_eq_u32 s61, 28
	s_cbranch_scc0 .Ldefer_1591_body
	v_lshl_add_u64 v[164:165], v[240:241], 0, s[84:85]
	s_mov_b32 m0, s54
	s_nop 0
	global_load_lds_dwordx4 v[164:165], off
	v_lshl_add_u64 v[164:165], v[242:243], 0, s[84:85]
	s_mov_b32 m0, s55
	s_nop 0
	global_load_lds_dwordx4 v[164:165], off

; #define PG8_STAGE(bufoff, gbase, voff) do { _Pragma("unroll") for (int _i = 0; _i < 2; ++_i) \
;         __builtin_amdgcn_global_load_lds((const unsigned*)((const char*)(gbase) + (voff)[_i]), (PG8_LAS unsigned*)(lds + (bufoff) + ldsw + _i * 8192), 16, 0, 0); } while (0)
; #define PG8_LDA(dst, b, h) do { _Pragma("unroll") for (int m = 0; m < 4; ++m) _Pragma("unroll") for (int k = 0; k < 2; ++k) dst[m][k] = *(const PG8_LAS bf16x8*)(lds + PG8_SA(b, h) + aoff + m * 2048 + k * 1024); } while (0)
; #define PG8_LDB(dst, b, h) do { _Pragma("unroll") for (int n = 0; n < 2; ++n) _Pragma("unroll") for (int k = 0; k < 2; ++k) dst[n][k] = *(const PG8_LAS bf16x8*)(lds + PG8_SB(b, h) + boff + n * 2048 + k * 1024); } while (0)
; #define PG8_WAIT_V(n) asm volatile("s_waitcnt vmcnt(" #n ")" ::: "memory")
; #define PG8_WAIT_L(n) asm volatile("s_waitcnt lgkmcnt(" #n ")" ::: "memory")
; #define PG8_BAR __builtin_amdgcn_s_barrier()
; #define PG8_SCHED __builtin_amdgcn_sched_barrier(0)
; template <class Epi, class Sched, bool ALIGN_EPI = false, bool SP2 = false, bool I8 = false>
; __device__ __forceinline__ void gemm_phase(PG8_LAS unsigned char* lds, const Gemm g, const Sched& S, const Epi& E) {
;     ...
;             const bool last = (t == nt - 2);
;             const char* a1 = cA + (size_t)(t + 1) * kstep;
;             const char* a2 = last ? nA : cA + (size_t)(t + 2) * kstep; const char* b2 = last ? nB : cB + (size_t)(t + 2) * kstep;
;             const char* a3 = a2 + kstep; const char* b3 = b2 + kstep;
;             if (last && has_next) S.a_ready(nxt);
;             if constexpr (SP2) {
;             PG8_LDB(B0, 0, 0); PG8_LDB(B1, 0, 1); PG8_SCHED; PG8_LDA(At, 0, 0); PG8_STAGE(PG8_SA(1, 1), a1 + hstep, voffA);
;             PG8_WAIT_V(8); PG8_WAIT_L(0); PG8_BAR; PG8_MMA(0, 0, At, B0); PG8_MMA(0, 1, At, B1); PG8_BAR; PG8_SCHED;
;             PG8_LDA(At, 0, 1); PG8_STAGE(PG8_SB(0, 0), b2, voffB); PG8_STAGE(PG8_SB(0, 1), b2 + hstep, voffB); PG8_STAGE(PG8_SA(0, 0), a2, voffA);
;             PG8_WAIT_V(8); PG8_WAIT_L(0); PG8_BAR; PG8_MMA(1, 0, At, B0); PG8_MMA(1, 1, At, B1); PG8_BAR; PG8_SCHED;
.LBB0_1699:
	s_add_u32 s53, s24, 0x100
	s_addc_u32 s54, s25, 0
	s_mov_b32 s55, -2
	s_add_u32 s24, s22, 0x100
	s_addc_u32 s25, s23, 0
	s_add_i32 s56, 0, 0x10000
	s_cmpk_eq_i32 s55, 0xa8
	s_cselect_b32 s37, s13, s25
	s_cselect_b32 s36, s12, s24
	s_cselect_b32 s27, s21, s54
	s_cselect_b32 s26, s20, s53
	s_add_i32 s57, 0, 0x14000
	v_add_u32_e32 v144, s56, v240
	v_add_u32_e32 v160, s57, v240
	ds_read_b128 v[124:127], v144
	ds_read_b128 v[128:131], v144 offset:1024
	ds_read_b128 v[132:135], v144 offset:2048
	ds_read_b128 v[144:147], v144 offset:3072
	ds_read_b128 v[148:151], v160
	ds_read_b128 v[152:155], v160 offset:1024
	ds_read_b128 v[156:159], v160 offset:2048
	ds_read_b128 v[160:163], v160 offset:3072
	v_lshl_add_u64 v[218:219], s[22:23], 0, v[210:211]
	s_add_i32 m0, s42, 0xc000
	ds_read_b128 v[164:167], v242
	ds_read_b128 v[168:171], v242 offset:1024
	ds_read_b128 v[172:175], v242 offset:2048
	ds_read_b128 v[176:179], v242 offset:3072
	ds_read_b128 v[180:183], v242 offset:4096
	ds_read_b128 v[184:187], v242 offset:5120
	ds_read_b128 v[188:191], v242 offset:6144
	ds_read_b128 v[214:217], v242 offset:7168
	global_load_lds_dwordx4 v[218:219], off
	v_lshl_add_u64 v[218:219], s[22:23], 0, v[212:213]
	s_add_i32 m0, s42, 0xe000
	s_nop 0
	global_load_lds_dwordx4 v[218:219], off
	s_waitcnt vmcnt(8)
	s_waitcnt lgkmcnt(0)
	s_barrier
	s_setprio 1
	s_waitcnt lgkmcnt(0)
	v_mfma_f32_16x16x32_bf16 v[140:143], v[124:127], v[164:167], 0
	v_mfma_f32_16x16x32_bf16 v[140:143], v[128:131], v[168:171], v[140:143]
	v_mfma_f32_16x16x32_bf16 v[112:115], v[128:131], v[176:179], 0
	v_mfma_f32_16x16x32_bf16 v[112:115], v[124:127], v[172:175], v[112:115]
	v_mfma_f32_16x16x32_bf16 v[96:99], v[124:127], v[180:183], 0
	v_mfma_f32_16x16x32_bf16 v[96:99], v[128:131], v[184:187], v[96:99]
	v_mfma_f32_16x16x32_bf16 v[80:83], v[128:131], v[214:217], 0
	v_mfma_f32_16x16x32_bf16 v[80:83], v[124:127], v[188:191], v[80:83]
	v_mfma_f32_16x16x32_bf16 v[76:79], v[132:135], v[188:191], 0
	v_mfma_f32_16x16x32_bf16 v[76:79], v[144:147], v[214:217], v[76:79]
	v_mfma_f32_16x16x32_bf16 v[92:95], v[144:147], v[184:187], 0
	v_mfma_f32_16x16x32_bf16 v[92:95], v[132:135], v[180:183], v[92:95]
	v_mfma_f32_16x16x32_bf16 v[108:111], v[132:135], v[172:175], 0
	v_mfma_f32_16x16x32_bf16 v[108:111], v[144:147], v[176:179], v[108:111]
	v_mfma_f32_16x16x32_bf16 v[136:139], v[144:147], v[168:171], 0
	v_mfma_f32_16x16x32_bf16 v[136:139], v[132:135], v[164:167], v[136:139]
	v_mfma_f32_16x16x32_bf16 v[120:123], v[148:151], v[164:167], 0
	v_mfma_f32_16x16x32_bf16 v[120:123], v[152:155], v[168:171], v[120:123]
	v_mfma_f32_16x16x32_bf16 v[104:107], v[152:155], v[176:179], 0
	v_mfma_f32_16x16x32_bf16 v[104:107], v[148:151], v[172:175], v[104:107]
	v_mfma_f32_16x16x32_bf16 v[88:91], v[148:151], v[180:183], 0
	v_mfma_f32_16x16x32_bf16 v[88:91], v[152:155], v[184:187], v[88:91]
	v_mfma_f32_16x16x32_bf16 v[72:75], v[152:155], v[214:217], 0
	v_mfma_f32_16x16x32_bf16 v[72:75], v[148:151], v[188:191], v[72:75]
	v_mfma_f32_16x16x32_bf16 v[68:71], v[156:159], v[188:191], 0
	v_mfma_f32_16x16x32_bf16 v[68:71], v[160:163], v[214:217], v[68:71]
	v_mfma_f32_16x16x32_bf16 v[84:87], v[160:163], v[184:187], 0
	v_mfma_f32_16x16x32_bf16 v[84:87], v[156:159], v[180:183], v[84:87]
	v_mfma_f32_16x16x32_bf16 v[100:103], v[156:159], v[172:175], 0
	v_mfma_f32_16x16x32_bf16 v[100:103], v[160:163], v[176:179], v[100:103]
	v_mfma_f32_16x16x32_bf16 v[116:119], v[160:163], v[168:171], 0
	v_mfma_f32_16x16x32_bf16 v[116:119], v[156:159], v[164:167], v[116:119]
	s_setprio 0
	s_barrier
	s_add_i32 s22, s56, s41
	s_mov_b32 m0, s22
	ds_read_b128 v[164:167], v242 offset:16384
	ds_read_b128 v[168:171], v242 offset:17408
	ds_read_b128 v[172:175], v242 offset:18432
	ds_read_b128 v[176:179], v242 offset:19456
	ds_read_b128 v[180:183], v242 offset:20480
	ds_read_b128 v[184:187], v242 offset:21504
	ds_read_b128 v[188:191], v242 offset:22528
	ds_read_b128 v[214:217], v242 offset:23552
	global_load_lds_dwordx4 v2, s[26:27]
	s_add_i32 m0, s22, 0x2000
	s_add_u32 s22, s26, 0x2b0000
	s_addc_u32 s23, s27, 0
	s_add_i32 s56, s57, s41
	global_load_lds_dwordx4 v204, s[26:27]
	s_mov_b32 m0, s56
	v_lshl_add_u64 v[224:225], s[36:37], 0, v[206:207]
	global_load_lds_dwordx4 v2, s[22:23]
	s_add_i32 m0, s56, 0x2000
	s_nop 0
	global_load_lds_dwordx4 v204, s[22:23]
	v_lshl_add_u64 v[222:223], s[36:37], 0, v[208:209]
	s_waitcnt vmcnt(6)
	s_waitcnt lgkmcnt(0)
	s_barrier
	s_setprio 1
	s_waitcnt lgkmcnt(0)
	v_mfma_f32_16x16x32_bf16 v[64:67], v[124:127], v[164:167], 0
	v_mfma_f32_16x16x32_bf16 v[64:67], v[128:131], v[168:171], v[64:67]
	v_mfma_f32_16x16x32_bf16 v[48:51], v[128:131], v[176:179], 0
	v_mfma_f32_16x16x32_bf16 v[48:51], v[124:127], v[172:175], v[48:51]
	v_mfma_f32_16x16x32_bf16 v[32:35], v[124:127], v[180:183], 0
	v_mfma_f32_16x16x32_bf16 v[32:35], v[128:131], v[184:187], v[32:35]
	v_mfma_f32_16x16x32_bf16 v[16:19], v[128:131], v[214:217], 0
	v_mfma_f32_16x16x32_bf16 v[16:19], v[124:127], v[188:191], v[16:19]
	v_mfma_f32_16x16x32_bf16 v[12:15], v[132:135], v[188:191], 0
	v_mfma_f32_16x16x32_bf16 v[12:15], v[144:147], v[214:217], v[12:15]
	v_mfma_f32_16x16x32_bf16 v[28:31], v[144:147], v[184:187], 0
	v_mfma_f32_16x16x32_bf16 v[28:31], v[132:135], v[180:183], v[28:31]
	v_mfma_f32_16x16x32_bf16 v[44:47], v[132:135], v[172:175], 0
	v_mfma_f32_16x16x32_bf16 v[44:47], v[144:147], v[176:179], v[44:47]
	v_mfma_f32_16x16x32_bf16 v[60:63], v[144:147], v[168:171], 0
	v_mfma_f32_16x16x32_bf16 v[60:63], v[132:135], v[164:167], v[60:63]
	v_mfma_f32_16x16x32_bf16 v[56:59], v[148:151], v[164:167], 0
	v_mfma_f32_16x16x32_bf16 v[56:59], v[152:155], v[168:171], v[56:59]
	v_mfma_f32_16x16x32_bf16 v[40:43], v[152:155], v[176:179], 0
	v_mfma_f32_16x16x32_bf16 v[40:43], v[148:151], v[172:175], v[40:43]
	v_mfma_f32_16x16x32_bf16 v[24:27], v[148:151], v[180:183], 0
	v_mfma_f32_16x16x32_bf16 v[24:27], v[152:155], v[184:187], v[24:27]
	v_mfma_f32_16x16x32_bf16 v[8:11], v[152:155], v[214:217], 0
	v_mfma_f32_16x16x32_bf16 v[8:11], v[148:151], v[188:191], v[8:11]
	v_mfma_f32_16x16x32_bf16 v[4:7], v[156:159], v[188:191], 0
	v_mfma_f32_16x16x32_bf16 v[4:7], v[160:163], v[214:217], v[4:7]
	v_mfma_f32_16x16x32_bf16 v[20:23], v[160:163], v[184:187], 0
	v_mfma_f32_16x16x32_bf16 v[20:23], v[156:159], v[180:183], v[20:23]
	v_mfma_f32_16x16x32_bf16 v[36:39], v[156:159], v[172:175], 0
	v_mfma_f32_16x16x32_bf16 v[36:39], v[160:163], v[176:179], v[36:39]
	v_mfma_f32_16x16x32_bf16 v[52:55], v[160:163], v[168:171], 0
	v_mfma_f32_16x16x32_bf16 v[52:55], v[156:159], v[164:167], v[52:55]
	s_setprio 0
	s_barrier
; #define PG8_STAGE(bufoff, gbase, voff) do { _Pragma("unroll") for (int _i = 0; _i < 2; ++_i) \
;         __builtin_amdgcn_global_load_lds((const unsigned*)((const char*)(gbase) + (voff)[_i]), (PG8_LAS unsigned*)(lds + (bufoff) + ldsw + _i * 8192), 16, 0, 0); } while (0)
; #define PG8_LDA(dst, b, h) do { _Pragma("unroll") for (int m = 0; m < 4; ++m) _Pragma("unroll") for (int k = 0; k < 2; ++k) dst[m][k] = *(const PG8_LAS bf16x8*)(lds + PG8_SA(b, h) + aoff + m * 2048 + k * 1024); } while (0)
; #define PG8_LDB(dst, b, h) do { _Pragma("unroll") for (int n = 0; n < 2; ++n) _Pragma("unroll") for (int k = 0; k < 2; ++k) dst[n][k] = *(const PG8_LAS bf16x8*)(lds + PG8_SB(b, h) + boff + n * 2048 + k * 1024); } while (0)
; #define PG8_WAIT_V(n) asm volatile("s_waitcnt vmcnt(" #n ")" ::: "memory")
; #define PG8_WAIT_L(n) asm volatile("s_waitcnt lgkmcnt(" #n ")" ::: "memory")
; #define PG8_BAR __builtin_amdgcn_s_barrier()
; #define PG8_SCHED __builtin_amdgcn_sched_barrier(0)
; template <class Epi, class Sched, bool ALIGN_EPI = false, bool SP2 = false, bool I8 = false>
; __device__ __forceinline__ void gemm_phase(PG8_LAS unsigned char* lds, const Gemm g, const Sched& S, const Epi& E) {
;     ...
;             PG8_LDB(B0, 1, 0); PG8_LDB(B1, 1, 1); PG8_SCHED; PG8_LDA(At, 1, 0); PG8_STAGE(PG8_SA(0, 1), a2 + hstep, voffA);
;             PG8_WAIT_V(8); PG8_WAIT_L(0); PG8_BAR; PG8_MMA(0, 0, At, B0); PG8_MMA(0, 1, At, B1); PG8_BAR; PG8_SCHED;
;             PG8_LDA(At, 1, 1); PG8_STAGE(PG8_SB(1, 0), b3, voffB); PG8_STAGE(PG8_SB(1, 1), b3 + hstep, voffB); PG8_STAGE(PG8_SA(1, 0), a3, voffA);
;             PG8_WAIT_V(8); PG8_WAIT_L(0); PG8_BAR; PG8_MMA(1, 0, At, B0); PG8_MMA(1, 1, At, B1); PG8_BAR; PG8_SCHED;
	s_mov_b32 m0, s42
	s_nop 0
	global_load_lds_dwordx4 v[222:223], off
	s_mov_b32 m0, s43
	s_nop 0
	global_load_lds_dwordx4 v[224:225], off
	s_add_i32 s56, 0, 0x18000
	s_add_i32 s57, 0, 0x1c000
	v_add_u32_e32 v144, s56, v240
	v_add_u32_e32 v160, s57, v240
	ds_read_b128 v[124:127], v144
	ds_read_b128 v[128:131], v144 offset:1024
	ds_read_b128 v[132:135], v144 offset:2048
	ds_read_b128 v[144:147], v144 offset:3072
	ds_read_b128 v[148:151], v160
	ds_read_b128 v[152:155], v160 offset:1024
	ds_read_b128 v[156:159], v160 offset:2048
	ds_read_b128 v[160:163], v160 offset:3072
	s_add_u32 s22, s36, 0x2b0000
	s_addc_u32 s23, s37, 0
	s_mov_b32 m0, s44
	ds_read_b128 v[164:167], v242 offset:32768
	ds_read_b128 v[168:171], v242 offset:33792
	ds_read_b128 v[172:175], v242 offset:34816
	ds_read_b128 v[176:179], v242 offset:35840
	ds_read_b128 v[180:183], v242 offset:36864
	ds_read_b128 v[184:187], v242 offset:37888
	ds_read_b128 v[188:191], v242 offset:38912
	ds_read_b128 v[214:217], v242 offset:39936
	global_load_lds_dwordx4 v208, s[22:23]
	s_mov_b32 m0, s45
	s_nop 0
	global_load_lds_dwordx4 v206, s[22:23]
	s_waitcnt vmcnt(8)
	s_waitcnt lgkmcnt(0)
	s_barrier
	s_setprio 1
	s_waitcnt lgkmcnt(0)
	v_mfma_f32_16x16x32_bf16 v[140:143], v[124:127], v[164:167], v[140:143]
	v_mfma_f32_16x16x32_bf16 v[140:143], v[128:131], v[168:171], v[140:143]
	v_mfma_f32_16x16x32_bf16 v[112:115], v[128:131], v[176:179], v[112:115]
	v_mfma_f32_16x16x32_bf16 v[112:115], v[124:127], v[172:175], v[112:115]
	v_mfma_f32_16x16x32_bf16 v[96:99], v[124:127], v[180:183], v[96:99]
	v_mfma_f32_16x16x32_bf16 v[96:99], v[128:131], v[184:187], v[96:99]
	v_mfma_f32_16x16x32_bf16 v[80:83], v[128:131], v[214:217], v[80:83]
	v_mfma_f32_16x16x32_bf16 v[80:83], v[124:127], v[188:191], v[80:83]
	v_mfma_f32_16x16x32_bf16 v[76:79], v[132:135], v[188:191], v[76:79]
	v_mfma_f32_16x16x32_bf16 v[76:79], v[144:147], v[214:217], v[76:79]
	v_mfma_f32_16x16x32_bf16 v[92:95], v[144:147], v[184:187], v[92:95]
	v_mfma_f32_16x16x32_bf16 v[92:95], v[132:135], v[180:183], v[92:95]
	v_mfma_f32_16x16x32_bf16 v[108:111], v[132:135], v[172:175], v[108:111]
	v_mfma_f32_16x16x32_bf16 v[108:111], v[144:147], v[176:179], v[108:111]
	v_mfma_f32_16x16x32_bf16 v[136:139], v[144:147], v[168:171], v[136:139]
	v_mfma_f32_16x16x32_bf16 v[136:139], v[132:135], v[164:167], v[136:139]
	v_mfma_f32_16x16x32_bf16 v[120:123], v[148:151], v[164:167], v[120:123]
	v_mfma_f32_16x16x32_bf16 v[120:123], v[152:155], v[168:171], v[120:123]
	v_mfma_f32_16x16x32_bf16 v[104:107], v[152:155], v[176:179], v[104:107]
	v_mfma_f32_16x16x32_bf16 v[104:107], v[148:151], v[172:175], v[104:107]
	v_mfma_f32_16x16x32_bf16 v[88:91], v[148:151], v[180:183], v[88:91]
	v_mfma_f32_16x16x32_bf16 v[88:91], v[152:155], v[184:187], v[88:91]
	v_mfma_f32_16x16x32_bf16 v[72:75], v[152:155], v[214:217], v[72:75]
	v_mfma_f32_16x16x32_bf16 v[72:75], v[148:151], v[188:191], v[72:75]
	v_mfma_f32_16x16x32_bf16 v[68:71], v[156:159], v[188:191], v[68:71]
	v_mfma_f32_16x16x32_bf16 v[68:71], v[160:163], v[214:217], v[68:71]
	v_mfma_f32_16x16x32_bf16 v[84:87], v[160:163], v[184:187], v[84:87]
	v_mfma_f32_16x16x32_bf16 v[84:87], v[156:159], v[180:183], v[84:87]
	v_mfma_f32_16x16x32_bf16 v[100:103], v[156:159], v[172:175], v[100:103]
	v_mfma_f32_16x16x32_bf16 v[100:103], v[160:163], v[176:179], v[100:103]
	v_mfma_f32_16x16x32_bf16 v[116:119], v[160:163], v[168:171], v[116:119]
	v_mfma_f32_16x16x32_bf16 v[116:119], v[156:159], v[164:167], v[116:119]
	s_setprio 0
	s_barrier
	s_add_u32 s98, s26, 0x80
	s_addc_u32 s99, s27, 0
	s_add_i32 s22, s56, s41
	s_mov_b32 m0, s22
	ds_read_b128 v[164:167], v242 offset:49152
	ds_read_b128 v[168:171], v242 offset:50176
	ds_read_b128 v[172:175], v242 offset:51200
	ds_read_b128 v[176:179], v242 offset:52224
	ds_read_b128 v[180:183], v242 offset:53248
	ds_read_b128 v[184:187], v242 offset:54272
	ds_read_b128 v[188:191], v242 offset:55296
	ds_read_b128 v[214:217], v242 offset:56320
	global_load_lds_dwordx4 v2, s[98:99]
	s_add_i32 m0, s22, 0x2000
	s_add_u32 s22, s26, 0x2b0080
	s_addc_u32 s23, s27, 0
	s_add_i32 s26, s57, s41
	global_load_lds_dwordx4 v204, s[98:99]
	s_mov_b32 m0, s26
	s_nop 0
	global_load_lds_dwordx4 v2, s[22:23]
	s_add_i32 m0, s26, 0x2000
	s_nop 0
	global_load_lds_dwordx4 v204, s[22:23]
	s_cmpk_eq_i32 s55, 0xa8
	s_cbranch_scc0 .Ldefer_1700_peel
	v_lshl_add_u64 v[218:219], v[222:223], 0, s[84:85]
	s_mov_b32 m0, s46
	s_nop 0
	global_load_lds_dwordx4 v[218:219], off
	v_lshl_add_u64 v[218:219], v[224:225], 0, s[84:85]
	s_mov_b32 m0, s47
	s_nop 0
	global_load_lds_dwordx4 v[218:219], off

; #define PG8_STAGE(bufoff, gbase, voff) do { _Pragma("unroll") for (int _i = 0; _i < 2; ++_i) \
;         __builtin_amdgcn_global_load_lds((const unsigned*)((const char*)(gbase) + (voff)[_i]), (PG8_LAS unsigned*)(lds + (bufoff) + ldsw + _i * 8192), 16, 0, 0); } while (0)
; #define PG8_LDA(dst, b, h) do { _Pragma("unroll") for (int m = 0; m < 4; ++m) _Pragma("unroll") for (int k = 0; k < 2; ++k) dst[m][k] = *(const PG8_LAS bf16x8*)(lds + PG8_SA(b, h) + aoff + m * 2048 + k * 1024); } while (0)
; #define PG8_LDB(dst, b, h) do { _Pragma("unroll") for (int n = 0; n < 2; ++n) _Pragma("unroll") for (int k = 0; k < 2; ++k) dst[n][k] = *(const PG8_LAS bf16x8*)(lds + PG8_SB(b, h) + boff + n * 2048 + k * 1024); } while (0)
; #define PG8_WAIT_V(n) asm volatile("s_waitcnt vmcnt(" #n ")" ::: "memory")
; #define PG8_WAIT_L(n) asm volatile("s_waitcnt lgkmcnt(" #n ")" ::: "memory")
; #define PG8_BAR __builtin_amdgcn_s_barrier()
; #define PG8_SCHED __builtin_amdgcn_sched_barrier(0)
; template <class Epi, class Sched, bool ALIGN_EPI = false, bool SP2 = false, bool I8 = false>
; __device__ __forceinline__ void gemm_phase(PG8_LAS unsigned char* lds, const Gemm g, const Sched& S, const Epi& E) {
;     ...
;             const bool last = (t == nt - 2);
;             const char* a1 = cA + (size_t)(t + 1) * kstep;
;             const char* a2 = last ? nA : cA + (size_t)(t + 2) * kstep; const char* b2 = last ? nB : cB + (size_t)(t + 2) * kstep;
;             const char* a3 = a2 + kstep; const char* b3 = b2 + kstep;
;             if (last && has_next) S.a_ready(nxt);
;             if constexpr (SP2) {
;             PG8_LDB(B0, 0, 0); PG8_LDB(B1, 0, 1); PG8_SCHED; PG8_LDA(At, 0, 0); PG8_STAGE(PG8_SA(1, 1), a1 + hstep, voffA);
;             PG8_WAIT_V(8); PG8_WAIT_L(0); PG8_BAR; PG8_MMA(0, 0, At, B0); PG8_MMA(0, 1, At, B1); PG8_BAR; PG8_SCHED;
;             PG8_LDA(At, 0, 1); PG8_STAGE(PG8_SB(0, 0), b2, voffB); PG8_STAGE(PG8_SB(0, 1), b2 + hstep, voffB); PG8_STAGE(PG8_SA(0, 0), a2, voffA);
;             PG8_WAIT_V(8); PG8_WAIT_L(0); PG8_BAR; PG8_MMA(1, 0, At, B0); PG8_MMA(1, 1, At, B1); PG8_BAR; PG8_SCHED;
.LBB0_1700:
	s_add_u32 s24, s22, 0x100
	s_addc_u32 s25, s23, 0
	s_add_i32 s56, 0, 0x10000
	s_cmpk_eq_i32 s55, 0xa8
	s_cselect_b32 s37, s13, s25
	s_cselect_b32 s36, s12, s24
	s_cselect_b32 s27, s21, s54
	s_cselect_b32 s26, s20, s53
	s_add_i32 s57, 0, 0x14000
	v_add_u32_e32 v144, s56, v240
	v_add_u32_e32 v160, s57, v240
	ds_read_b128 v[124:127], v144
	ds_read_b128 v[128:131], v144 offset:1024
	ds_read_b128 v[132:135], v144 offset:2048
	ds_read_b128 v[144:147], v144 offset:3072
	ds_read_b128 v[148:151], v160
	ds_read_b128 v[152:155], v160 offset:1024
	ds_read_b128 v[156:159], v160 offset:2048
	ds_read_b128 v[160:163], v160 offset:3072
	v_lshl_add_u64 v[218:219], v[222:223], 0, s[84:85]
	s_mov_b32 m0, s46
	s_nop 0
	global_load_lds_dwordx4 v[218:219], off
	v_lshl_add_u64 v[218:219], v[224:225], 0, s[84:85]
	s_mov_b32 m0, s47
	s_nop 0
	global_load_lds_dwordx4 v[218:219], off
	v_lshl_add_u64 v[218:219], s[22:23], 0, v[210:211]
	s_add_i32 m0, s42, 0xc000
	ds_read_b128 v[164:167], v242
	ds_read_b128 v[168:171], v242 offset:1024
	ds_read_b128 v[172:175], v242 offset:2048
	ds_read_b128 v[176:179], v242 offset:3072
	ds_read_b128 v[180:183], v242 offset:4096
	ds_read_b128 v[184:187], v242 offset:5120
	ds_read_b128 v[188:191], v242 offset:6144
	ds_read_b128 v[214:217], v242 offset:7168
	global_load_lds_dwordx4 v[218:219], off
	v_lshl_add_u64 v[218:219], s[22:23], 0, v[212:213]
	s_add_i32 m0, s42, 0xe000
	s_nop 0
	global_load_lds_dwordx4 v[218:219], off
	s_waitcnt vmcnt(8)
	s_waitcnt lgkmcnt(0)
	s_barrier
	s_setprio 1
	s_waitcnt lgkmcnt(0)
	v_mfma_f32_16x16x32_bf16 v[140:143], v[124:127], v[164:167], v[140:143]
	v_mfma_f32_16x16x32_bf16 v[140:143], v[128:131], v[168:171], v[140:143]
	v_mfma_f32_16x16x32_bf16 v[112:115], v[128:131], v[176:179], v[112:115]
	v_mfma_f32_16x16x32_bf16 v[112:115], v[124:127], v[172:175], v[112:115]
	v_mfma_f32_16x16x32_bf16 v[96:99], v[124:127], v[180:183], v[96:99]
	v_mfma_f32_16x16x32_bf16 v[96:99], v[128:131], v[184:187], v[96:99]
	v_mfma_f32_16x16x32_bf16 v[80:83], v[128:131], v[214:217], v[80:83]
	v_mfma_f32_16x16x32_bf16 v[80:83], v[124:127], v[188:191], v[80:83]
	v_mfma_f32_16x16x32_bf16 v[76:79], v[132:135], v[188:191], v[76:79]
	v_mfma_f32_16x16x32_bf16 v[76:79], v[144:147], v[214:217], v[76:79]
	v_mfma_f32_16x16x32_bf16 v[92:95], v[144:147], v[184:187], v[92:95]
	v_mfma_f32_16x16x32_bf16 v[92:95], v[132:135], v[180:183], v[92:95]
	v_mfma_f32_16x16x32_bf16 v[108:111], v[132:135], v[172:175], v[108:111]
	v_mfma_f32_16x16x32_bf16 v[108:111], v[144:147], v[176:179], v[108:111]
	v_mfma_f32_16x16x32_bf16 v[136:139], v[144:147], v[168:171], v[136:139]
	v_mfma_f32_16x16x32_bf16 v[136:139], v[132:135], v[164:167], v[136:139]
	v_mfma_f32_16x16x32_bf16 v[120:123], v[148:151], v[164:167], v[120:123]
	v_mfma_f32_16x16x32_bf16 v[120:123], v[152:155], v[168:171], v[120:123]
	v_mfma_f32_16x16x32_bf16 v[104:107], v[152:155], v[176:179], v[104:107]
	v_mfma_f32_16x16x32_bf16 v[104:107], v[148:151], v[172:175], v[104:107]
	v_mfma_f32_16x16x32_bf16 v[88:91], v[148:151], v[180:183], v[88:91]
	v_mfma_f32_16x16x32_bf16 v[88:91], v[152:155], v[184:187], v[88:91]
	v_mfma_f32_16x16x32_bf16 v[72:75], v[152:155], v[214:217], v[72:75]
	v_mfma_f32_16x16x32_bf16 v[72:75], v[148:151], v[188:191], v[72:75]
	v_mfma_f32_16x16x32_bf16 v[68:71], v[156:159], v[188:191], v[68:71]
	v_mfma_f32_16x16x32_bf16 v[68:71], v[160:163], v[214:217], v[68:71]
	v_mfma_f32_16x16x32_bf16 v[84:87], v[160:163], v[184:187], v[84:87]
	v_mfma_f32_16x16x32_bf16 v[84:87], v[156:159], v[180:183], v[84:87]
	v_mfma_f32_16x16x32_bf16 v[100:103], v[156:159], v[172:175], v[100:103]
	v_mfma_f32_16x16x32_bf16 v[100:103], v[160:163], v[176:179], v[100:103]
	v_mfma_f32_16x16x32_bf16 v[116:119], v[160:163], v[168:171], v[116:119]
	v_mfma_f32_16x16x32_bf16 v[116:119], v[156:159], v[164:167], v[116:119]
	s_setprio 0
	s_barrier
	s_add_i32 s22, s56, s41
	s_mov_b32 m0, s22
	ds_read_b128 v[164:167], v242 offset:16384
	ds_read_b128 v[168:171], v242 offset:17408
	ds_read_b128 v[172:175], v242 offset:18432
	ds_read_b128 v[176:179], v242 offset:19456
	ds_read_b128 v[180:183], v242 offset:20480
	ds_read_b128 v[184:187], v242 offset:21504
	ds_read_b128 v[188:191], v242 offset:22528
	ds_read_b128 v[214:217], v242 offset:23552
	global_load_lds_dwordx4 v2, s[26:27]
	s_add_i32 m0, s22, 0x2000
	s_add_u32 s22, s26, 0x2b0000
	s_addc_u32 s23, s27, 0
	s_add_i32 s56, s57, s41
	global_load_lds_dwordx4 v204, s[26:27]
	s_mov_b32 m0, s56
	v_lshl_add_u64 v[224:225], s[36:37], 0, v[206:207]
	global_load_lds_dwordx4 v2, s[22:23]
	s_add_i32 m0, s56, 0x2000
	s_nop 0
	global_load_lds_dwordx4 v204, s[22:23]
	v_lshl_add_u64 v[222:223], s[36:37], 0, v[208:209]
	s_waitcnt vmcnt(6)
	s_waitcnt lgkmcnt(0)
	s_barrier
; #define PG8_STAGE(bufoff, gbase, voff) do { _Pragma("unroll") for (int _i = 0; _i < 2; ++_i) \
;         __builtin_amdgcn_global_load_lds((const unsigned*)((const char*)(gbase) + (voff)[_i]), (PG8_LAS unsigned*)(lds + (bufoff) + ldsw + _i * 8192), 16, 0, 0); } while (0)
; #define PG8_LDA(dst, b, h) do { _Pragma("unroll") for (int m = 0; m < 4; ++m) _Pragma("unroll") for (int k = 0; k < 2; ++k) dst[m][k] = *(const PG8_LAS bf16x8*)(lds + PG8_SA(b, h) + aoff + m * 2048 + k * 1024); } while (0)
; #define PG8_LDB(dst, b, h) do { _Pragma("unroll") for (int n = 0; n < 2; ++n) _Pragma("unroll") for (int k = 0; k < 2; ++k) dst[n][k] = *(const PG8_LAS bf16x8*)(lds + PG8_SB(b, h) + boff + n * 2048 + k * 1024); } while (0)
; #define PG8_WAIT_V(n) asm volatile("s_waitcnt vmcnt(" #n ")" ::: "memory")
; #define PG8_WAIT_L(n) asm volatile("s_waitcnt lgkmcnt(" #n ")" ::: "memory")
; #define PG8_BAR __builtin_amdgcn_s_barrier()
; #define PG8_SCHED __builtin_amdgcn_sched_barrier(0)
; template <class Epi, class Sched, bool ALIGN_EPI = false, bool SP2 = false, bool I8 = false>
; __device__ __forceinline__ void gemm_phase(PG8_LAS unsigned char* lds, const Gemm g, const Sched& S, const Epi& E) {
;     ...
;             PG8_WAIT_V(8); PG8_WAIT_L(0); PG8_BAR; PG8_MMA(1, 0, At, B0); PG8_MMA(1, 1, At, B1); PG8_BAR; PG8_SCHED;
;             PG8_LDB(B0, 1, 0); PG8_LDB(B1, 1, 1); PG8_SCHED; PG8_LDA(At, 1, 0); PG8_STAGE(PG8_SA(0, 1), a2 + hstep, voffA);
;             PG8_WAIT_V(8); PG8_WAIT_L(0); PG8_BAR; PG8_MMA(0, 0, At, B0); PG8_MMA(0, 1, At, B1); PG8_BAR; PG8_SCHED;
;             PG8_LDA(At, 1, 1); PG8_STAGE(PG8_SB(1, 0), b3, voffB); PG8_STAGE(PG8_SB(1, 1), b3 + hstep, voffB); PG8_STAGE(PG8_SA(1, 0), a3, voffA);
;             PG8_WAIT_V(8); PG8_WAIT_L(0); PG8_BAR; PG8_MMA(1, 0, At, B0); PG8_MMA(1, 1, At, B1); PG8_BAR; PG8_SCHED;
	s_setprio 1
	s_waitcnt lgkmcnt(0)
	v_mfma_f32_16x16x32_bf16 v[64:67], v[124:127], v[164:167], v[64:67]
	v_mfma_f32_16x16x32_bf16 v[64:67], v[128:131], v[168:171], v[64:67]
	v_mfma_f32_16x16x32_bf16 v[48:51], v[128:131], v[176:179], v[48:51]
	v_mfma_f32_16x16x32_bf16 v[48:51], v[124:127], v[172:175], v[48:51]
	v_mfma_f32_16x16x32_bf16 v[32:35], v[124:127], v[180:183], v[32:35]
	v_mfma_f32_16x16x32_bf16 v[32:35], v[128:131], v[184:187], v[32:35]
	v_mfma_f32_16x16x32_bf16 v[16:19], v[128:131], v[214:217], v[16:19]
	v_mfma_f32_16x16x32_bf16 v[16:19], v[124:127], v[188:191], v[16:19]
	v_mfma_f32_16x16x32_bf16 v[12:15], v[132:135], v[188:191], v[12:15]
	v_mfma_f32_16x16x32_bf16 v[12:15], v[144:147], v[214:217], v[12:15]
	v_mfma_f32_16x16x32_bf16 v[28:31], v[144:147], v[184:187], v[28:31]
	v_mfma_f32_16x16x32_bf16 v[28:31], v[132:135], v[180:183], v[28:31]
	v_mfma_f32_16x16x32_bf16 v[44:47], v[132:135], v[172:175], v[44:47]
	v_mfma_f32_16x16x32_bf16 v[44:47], v[144:147], v[176:179], v[44:47]
	v_mfma_f32_16x16x32_bf16 v[60:63], v[144:147], v[168:171], v[60:63]
	v_mfma_f32_16x16x32_bf16 v[60:63], v[132:135], v[164:167], v[60:63]
	v_mfma_f32_16x16x32_bf16 v[56:59], v[148:151], v[164:167], v[56:59]
	v_mfma_f32_16x16x32_bf16 v[56:59], v[152:155], v[168:171], v[56:59]
	v_mfma_f32_16x16x32_bf16 v[40:43], v[152:155], v[176:179], v[40:43]
	v_mfma_f32_16x16x32_bf16 v[40:43], v[148:151], v[172:175], v[40:43]
	v_mfma_f32_16x16x32_bf16 v[24:27], v[148:151], v[180:183], v[24:27]
	v_mfma_f32_16x16x32_bf16 v[24:27], v[152:155], v[184:187], v[24:27]
	v_mfma_f32_16x16x32_bf16 v[8:11], v[152:155], v[214:217], v[8:11]
	v_mfma_f32_16x16x32_bf16 v[8:11], v[148:151], v[188:191], v[8:11]
	v_mfma_f32_16x16x32_bf16 v[4:7], v[156:159], v[188:191], v[4:7]
	v_mfma_f32_16x16x32_bf16 v[4:7], v[160:163], v[214:217], v[4:7]
	v_mfma_f32_16x16x32_bf16 v[20:23], v[160:163], v[184:187], v[20:23]
	v_mfma_f32_16x16x32_bf16 v[20:23], v[156:159], v[180:183], v[20:23]
	v_mfma_f32_16x16x32_bf16 v[36:39], v[156:159], v[172:175], v[36:39]
	v_mfma_f32_16x16x32_bf16 v[36:39], v[160:163], v[176:179], v[36:39]
	v_mfma_f32_16x16x32_bf16 v[52:55], v[160:163], v[168:171], v[52:55]
	v_mfma_f32_16x16x32_bf16 v[52:55], v[156:159], v[164:167], v[52:55]
	s_setprio 0
	s_barrier
	s_mov_b32 m0, s42
	s_nop 0
	global_load_lds_dwordx4 v[222:223], off
	s_mov_b32 m0, s43
	s_nop 0
	global_load_lds_dwordx4 v[224:225], off
	s_add_i32 s56, 0, 0x18000
	s_add_i32 s57, 0, 0x1c000
	v_add_u32_e32 v144, s56, v240
	v_add_u32_e32 v160, s57, v240
	ds_read_b128 v[124:127], v144
	ds_read_b128 v[128:131], v144 offset:1024
	ds_read_b128 v[132:135], v144 offset:2048
	ds_read_b128 v[144:147], v144 offset:3072
	ds_read_b128 v[148:151], v160
	ds_read_b128 v[152:155], v160 offset:1024
	ds_read_b128 v[156:159], v160 offset:2048
	ds_read_b128 v[160:163], v160 offset:3072
	s_add_u32 s22, s36, 0x2b0000
	s_addc_u32 s23, s37, 0
	s_mov_b32 m0, s44
	ds_read_b128 v[164:167], v242 offset:32768
	ds_read_b128 v[168:171], v242 offset:33792
	ds_read_b128 v[172:175], v242 offset:34816
	ds_read_b128 v[176:179], v242 offset:35840
	ds_read_b128 v[180:183], v242 offset:36864
	ds_read_b128 v[184:187], v242 offset:37888
	ds_read_b128 v[188:191], v242 offset:38912
	ds_read_b128 v[214:217], v242 offset:39936
	global_load_lds_dwordx4 v208, s[22:23]
	s_mov_b32 m0, s45
	s_nop 0
	global_load_lds_dwordx4 v206, s[22:23]
	s_waitcnt vmcnt(8)
	s_waitcnt lgkmcnt(0)
	s_barrier
	s_setprio 1
	s_waitcnt lgkmcnt(0)
	v_mfma_f32_16x16x32_bf16 v[140:143], v[124:127], v[164:167], v[140:143]
	v_mfma_f32_16x16x32_bf16 v[140:143], v[128:131], v[168:171], v[140:143]
	v_mfma_f32_16x16x32_bf16 v[112:115], v[128:131], v[176:179], v[112:115]
	v_mfma_f32_16x16x32_bf16 v[112:115], v[124:127], v[172:175], v[112:115]
	v_mfma_f32_16x16x32_bf16 v[96:99], v[124:127], v[180:183], v[96:99]
	v_mfma_f32_16x16x32_bf16 v[96:99], v[128:131], v[184:187], v[96:99]
	v_mfma_f32_16x16x32_bf16 v[80:83], v[128:131], v[214:217], v[80:83]
	v_mfma_f32_16x16x32_bf16 v[80:83], v[124:127], v[188:191], v[80:83]
	v_mfma_f32_16x16x32_bf16 v[76:79], v[132:135], v[188:191], v[76:79]
	v_mfma_f32_16x16x32_bf16 v[76:79], v[144:147], v[214:217], v[76:79]
	v_mfma_f32_16x16x32_bf16 v[92:95], v[144:147], v[184:187], v[92:95]
	v_mfma_f32_16x16x32_bf16 v[92:95], v[132:135], v[180:183], v[92:95]
	v_mfma_f32_16x16x32_bf16 v[108:111], v[132:135], v[172:175], v[108:111]
	v_mfma_f32_16x16x32_bf16 v[108:111], v[144:147], v[176:179], v[108:111]
	v_mfma_f32_16x16x32_bf16 v[136:139], v[144:147], v[168:171], v[136:139]
	v_mfma_f32_16x16x32_bf16 v[136:139], v[132:135], v[164:167], v[136:139]
	v_mfma_f32_16x16x32_bf16 v[120:123], v[148:151], v[164:167], v[120:123]
	v_mfma_f32_16x16x32_bf16 v[120:123], v[152:155], v[168:171], v[120:123]
	v_mfma_f32_16x16x32_bf16 v[104:107], v[152:155], v[176:179], v[104:107]
	v_mfma_f32_16x16x32_bf16 v[104:107], v[148:151], v[172:175], v[104:107]
	v_mfma_f32_16x16x32_bf16 v[88:91], v[148:151], v[180:183], v[88:91]
	v_mfma_f32_16x16x32_bf16 v[88:91], v[152:155], v[184:187], v[88:91]
	v_mfma_f32_16x16x32_bf16 v[72:75], v[152:155], v[214:217], v[72:75]
	v_mfma_f32_16x16x32_bf16 v[72:75], v[148:151], v[188:191], v[72:75]
	v_mfma_f32_16x16x32_bf16 v[68:71], v[156:159], v[188:191], v[68:71]
	v_mfma_f32_16x16x32_bf16 v[68:71], v[160:163], v[214:217], v[68:71]
	v_mfma_f32_16x16x32_bf16 v[84:87], v[160:163], v[184:187], v[84:87]
	v_mfma_f32_16x16x32_bf16 v[84:87], v[156:159], v[180:183], v[84:87]
	v_mfma_f32_16x16x32_bf16 v[100:103], v[156:159], v[172:175], v[100:103]
	v_mfma_f32_16x16x32_bf16 v[100:103], v[160:163], v[176:179], v[100:103]
	v_mfma_f32_16x16x32_bf16 v[116:119], v[160:163], v[168:171], v[116:119]
	v_mfma_f32_16x16x32_bf16 v[116:119], v[156:159], v[164:167], v[116:119]
	s_setprio 0
	s_barrier
	s_add_u32 s98, s26, 0x80
	s_addc_u32 s99, s27, 0
	s_add_i32 s22, s56, s41
	s_mov_b32 m0, s22
	ds_read_b128 v[164:167], v242 offset:49152
	ds_read_b128 v[168:171], v242 offset:50176
	ds_read_b128 v[172:175], v242 offset:51200
	ds_read_b128 v[176:179], v242 offset:52224
	ds_read_b128 v[180:183], v242 offset:53248
	ds_read_b128 v[184:187], v242 offset:54272
	ds_read_b128 v[188:191], v242 offset:55296
	ds_read_b128 v[214:217], v242 offset:56320
	global_load_lds_dwordx4 v2, s[98:99]
	s_add_i32 m0, s22, 0x2000
	s_add_u32 s22, s26, 0x2b0080
	s_addc_u32 s23, s27, 0
	s_add_i32 s26, s57, s41
	global_load_lds_dwordx4 v204, s[98:99]
	s_mov_b32 m0, s26
	s_nop 0
	global_load_lds_dwordx4 v2, s[22:23]
	s_add_i32 m0, s26, 0x2000
	s_nop 0
	global_load_lds_dwordx4 v204, s[22:23]
	s_cmpk_eq_i32 s55, 0xa8
	s_cbranch_scc0 .Ldefer_1700_body
	v_lshl_add_u64 v[218:219], v[222:223], 0, s[84:85]
	s_mov_b32 m0, s46
	s_nop 0
	global_load_lds_dwordx4 v[218:219], off
	v_lshl_add_u64 v[218:219], v[224:225], 0, s[84:85]
	s_mov_b32 m0, s47
	s_nop 0
	global_load_lds_dwordx4 v[218:219], off

; #define PG8_STAGE(bufoff, gbase, voff) do { _Pragma("unroll") for (int _i = 0; _i < 2; ++_i) \
;         __builtin_amdgcn_global_load_lds((const unsigned*)((const char*)(gbase) + (voff)[_i]), (PG8_LAS unsigned*)(lds + (bufoff) + ldsw + _i * 8192), 16, 0, 0); } while (0)
; #define PG8_LDA(dst, b, h) do { _Pragma("unroll") for (int m = 0; m < 4; ++m) _Pragma("unroll") for (int k = 0; k < 2; ++k) dst[m][k] = *(const PG8_LAS bf16x8*)(lds + PG8_SA(b, h) + aoff + m * 2048 + k * 1024); } while (0)
; #define PG8_LDB(dst, b, h) do { _Pragma("unroll") for (int n = 0; n < 2; ++n) _Pragma("unroll") for (int k = 0; k < 2; ++k) dst[n][k] = *(const PG8_LAS bf16x8*)(lds + PG8_SB(b, h) + boff + n * 2048 + k * 1024); } while (0)
; #define PG8_WAIT_V(n) asm volatile("s_waitcnt vmcnt(" #n ")" ::: "memory")
; #define PG8_WAIT_L(n) asm volatile("s_waitcnt lgkmcnt(" #n ")" ::: "memory")
; #define PG8_BAR __builtin_amdgcn_s_barrier()
; #define PG8_SCHED __builtin_amdgcn_sched_barrier(0)
; template <class Epi, class Sched, bool ALIGN_EPI = false, bool SP2 = false, bool I8 = false>
; __device__ __forceinline__ void gemm_phase(PG8_LAS unsigned char* lds, const Gemm g, const Sched& S, const Epi& E) {
;     ...
;         const bool has_next = S.next(ui + 1, nxt);
;         const char* nA = has_next ? (const char*)g.A + (size_t)nxt.pm * tstep : cA; const char* nB = has_next ? (const char*)g.Bt + (size_t)nxt.pn * tstep : cB;
;         for (int t = 0; t < nt; t += 2) {
;             const bool last = (t == nt - 2);
;             const char* a1 = cA + (size_t)(t + 1) * kstep;
;             const char* a2 = last ? nA : cA + (size_t)(t + 2) * kstep; const char* b2 = last ? nB : cB + (size_t)(t + 2) * kstep;
;             const char* a3 = a2 + kstep; const char* b3 = b2 + kstep;
;             if (last && has_next) S.a_ready(nxt);
;             if constexpr (SP2) {
;             PG8_LDB(B0, 0, 0); PG8_LDB(B1, 0, 1); PG8_SCHED; PG8_LDA(At, 0, 0); PG8_STAGE(PG8_SA(1, 1), a1 + hstep, voffA);
;             PG8_WAIT_V(8); PG8_WAIT_L(0); PG8_BAR; PG8_MMA(0, 0, At, B0); PG8_MMA(0, 1, At, B1); PG8_BAR; PG8_SCHED;
;             PG8_LDA(At, 0, 1); PG8_STAGE(PG8_SB(0, 0), b2, voffB); PG8_STAGE(PG8_SB(0, 1), b2 + hstep, voffB); PG8_STAGE(PG8_SA(0, 0), a2, voffA);
;             PG8_WAIT_V(8); PG8_WAIT_L(0); PG8_BAR; PG8_MMA(1, 0, At, B0); PG8_MMA(1, 1, At, B1); PG8_BAR; PG8_SCHED;
.LBB0_1842:
	s_ashr_i32 s45, s44, 31
	s_lshl_b64 s[34:35], s[44:45], 20
	s_add_u32 s50, s47, s34
	s_addc_u32 s51, s52, s35
	s_and_b64 s[34:35], s[8:9], exec
	s_cselect_b32 s11, s51, s55
	s_cselect_b32 s13, s50, s54
	s_ashr_i32 s49, s48, 31
	s_lshl_b64 s[34:35], s[48:49], 20
	s_add_u32 s56, s53, s34
	s_addc_u32 s57, s64, s35
	s_and_b64 s[34:35], s[8:9], exec
	s_cselect_b32 s34, s57, s59
	s_cselect_b32 s35, s56, s58
	s_add_u32 s54, s54, 0x80080
	s_addc_u32 s55, s55, 0
	s_add_u32 s45, s58, 0x100
	s_addc_u32 s49, s59, 0
	s_mov_b32 s86, -2
	s_waitcnt lgkmcnt(0)
	s_add_u32 s58, s54, 0xfff80080
	s_addc_u32 s59, s55, -1
	s_add_i32 s87, 0, 0x10000
	s_cmp_eq_u32 s86, 28
	s_cselect_b32 s61, s11, s59
	s_cselect_b32 s60, s13, s58
	s_cselect_b32 s59, s34, s49
	s_cselect_b32 s58, s35, s45
	s_add_i32 vcc_lo, 0, 0x14000
	v_add_u32_e32 v40, s87, v217
	v_add_u32_e32 v160, vcc_lo, v217
	ds_read_b128 v[28:31], v40
	ds_read_b128 v[32:35], v40 offset:1024
	ds_read_b128 v[36:39], v40 offset:2048
	ds_read_b128 v[40:43], v40 offset:3072
	ds_read_b128 v[140:143], v160
	ds_read_b128 v[144:147], v160 offset:1024
	ds_read_b128 v[156:159], v160 offset:2048
	ds_read_b128 v[160:163], v160 offset:3072
	s_add_i32 m0, s65, 0xc000
	ds_read_b128 v[164:167], v219
	ds_read_b128 v[168:171], v219 offset:1024
	ds_read_b128 v[172:175], v219 offset:2048
	ds_read_b128 v[176:179], v219 offset:3072
	ds_read_b128 v[204:207], v219 offset:4096
	ds_read_b128 v[208:211], v219 offset:5120
	ds_read_b128 v[212:215], v219 offset:6144
	ds_read_b128 v[220:223], v219 offset:7168
	global_load_lds_dwordx4 v186, s[54:55]
	s_add_i32 m0, s65, 0xe000
	s_nop 0
	global_load_lds_dwordx4 v188, s[54:55]
	s_waitcnt vmcnt(8)
	s_waitcnt lgkmcnt(0)
	s_barrier
	s_setprio 1
	s_waitcnt lgkmcnt(0)
	v_mfma_i32_16x16x64_i8 v[152:155], v[28:31], v[164:167], 0
	v_mfma_i32_16x16x64_i8 v[152:155], v[32:35], v[168:171], v[152:155]
	v_mfma_i32_16x16x64_i8 v[128:131], v[32:35], v[176:179], 0
	v_mfma_i32_16x16x64_i8 v[128:131], v[28:31], v[172:175], v[128:131]
	v_mfma_i32_16x16x64_i8 v[112:115], v[28:31], v[204:207], 0
	v_mfma_i32_16x16x64_i8 v[112:115], v[32:35], v[208:211], v[112:115]
	v_mfma_i32_16x16x64_i8 v[96:99], v[32:35], v[220:223], 0
	v_mfma_i32_16x16x64_i8 v[96:99], v[28:31], v[212:215], v[96:99]
	v_mfma_i32_16x16x64_i8 v[92:95], v[36:39], v[212:215], 0
	v_mfma_i32_16x16x64_i8 v[92:95], v[40:43], v[220:223], v[92:95]
	v_mfma_i32_16x16x64_i8 v[108:111], v[40:43], v[208:211], 0
	v_mfma_i32_16x16x64_i8 v[108:111], v[36:39], v[204:207], v[108:111]
	v_mfma_i32_16x16x64_i8 v[124:127], v[36:39], v[172:175], 0
	v_mfma_i32_16x16x64_i8 v[124:127], v[40:43], v[176:179], v[124:127]
	v_mfma_i32_16x16x64_i8 v[148:151], v[40:43], v[168:171], 0
	v_mfma_i32_16x16x64_i8 v[148:151], v[36:39], v[164:167], v[148:151]
	v_mfma_i32_16x16x64_i8 v[136:139], v[140:143], v[164:167], 0
	v_mfma_i32_16x16x64_i8 v[136:139], v[144:147], v[168:171], v[136:139]
	v_mfma_i32_16x16x64_i8 v[120:123], v[144:147], v[176:179], 0
	v_mfma_i32_16x16x64_i8 v[120:123], v[140:143], v[172:175], v[120:123]
	v_mfma_i32_16x16x64_i8 v[104:107], v[140:143], v[204:207], 0
	v_mfma_i32_16x16x64_i8 v[104:107], v[144:147], v[208:211], v[104:107]
	v_mfma_i32_16x16x64_i8 v[88:91], v[144:147], v[220:223], 0
	v_mfma_i32_16x16x64_i8 v[88:91], v[140:143], v[212:215], v[88:91]
	v_mfma_i32_16x16x64_i8 v[84:87], v[156:159], v[212:215], 0
	v_mfma_i32_16x16x64_i8 v[84:87], v[160:163], v[220:223], v[84:87]
	v_mfma_i32_16x16x64_i8 v[100:103], v[160:163], v[208:211], 0
	v_mfma_i32_16x16x64_i8 v[100:103], v[156:159], v[204:207], v[100:103]
	v_mfma_i32_16x16x64_i8 v[116:119], v[156:159], v[172:175], 0
	v_mfma_i32_16x16x64_i8 v[116:119], v[160:163], v[176:179], v[116:119]
	v_mfma_i32_16x16x64_i8 v[132:135], v[160:163], v[168:171], 0
	v_mfma_i32_16x16x64_i8 v[132:135], v[156:159], v[164:167], v[132:135]
	s_setprio 0
	s_barrier
	s_add_i32 s87, s87, s46
	s_mov_b32 m0, s87
	ds_read_b128 v[164:167], v219 offset:16384
	ds_read_b128 v[168:171], v219 offset:17408
	ds_read_b128 v[172:175], v219 offset:18432
	ds_read_b128 v[176:179], v219 offset:19456
	ds_read_b128 v[204:207], v219 offset:20480
	ds_read_b128 v[208:211], v219 offset:21504
	ds_read_b128 v[212:215], v219 offset:22528
	ds_read_b128 v[220:223], v219 offset:23552
	global_load_lds_dwordx4 v2, s[58:59]
	s_add_i32 m0, s87, 0x2000
	s_add_u32 s96, s58, 0x80000
	s_addc_u32 s97, s59, 0
	s_add_i32 s87, vcc_lo, s46
	global_load_lds_dwordx4 v184, s[58:59]
	s_mov_b32 m0, s87
	v_lshl_add_u64 v[228:229], s[60:61], 0, v[182:183]
	global_load_lds_dwordx4 v2, s[96:97]
	s_add_i32 m0, s87, 0x2000
	s_nop 0
	global_load_lds_dwordx4 v184, s[96:97]
	v_lshl_add_u64 v[226:227], s[60:61], 0, v[180:181]
	s_waitcnt vmcnt(6)
	s_waitcnt lgkmcnt(0)
	s_barrier
; #define PG8_STAGE(bufoff, gbase, voff) do { _Pragma("unroll") for (int _i = 0; _i < 2; ++_i) \
;         __builtin_amdgcn_global_load_lds((const unsigned*)((const char*)(gbase) + (voff)[_i]), (PG8_LAS unsigned*)(lds + (bufoff) + ldsw + _i * 8192), 16, 0, 0); } while (0)
; #define PG8_LDA(dst, b, h) do { _Pragma("unroll") for (int m = 0; m < 4; ++m) _Pragma("unroll") for (int k = 0; k < 2; ++k) dst[m][k] = *(const PG8_LAS bf16x8*)(lds + PG8_SA(b, h) + aoff + m * 2048 + k * 1024); } while (0)
; #define PG8_LDB(dst, b, h) do { _Pragma("unroll") for (int n = 0; n < 2; ++n) _Pragma("unroll") for (int k = 0; k < 2; ++k) dst[n][k] = *(const PG8_LAS bf16x8*)(lds + PG8_SB(b, h) + boff + n * 2048 + k * 1024); } while (0)
; #define PG8_WAIT_V(n) asm volatile("s_waitcnt vmcnt(" #n ")" ::: "memory")
; #define PG8_WAIT_L(n) asm volatile("s_waitcnt lgkmcnt(" #n ")" ::: "memory")
; #define PG8_BAR __builtin_amdgcn_s_barrier()
; #define PG8_SCHED __builtin_amdgcn_sched_barrier(0)
; template <class Epi, class Sched, bool ALIGN_EPI = false, bool SP2 = false, bool I8 = false>
; __device__ __forceinline__ void gemm_phase(PG8_LAS unsigned char* lds, const Gemm g, const Sched& S, const Epi& E) {
;     ...
;             PG8_WAIT_V(8); PG8_WAIT_L(0); PG8_BAR; PG8_MMA(1, 0, At, B0); PG8_MMA(1, 1, At, B1); PG8_BAR; PG8_SCHED;
;             PG8_LDB(B0, 1, 0); PG8_LDB(B1, 1, 1); PG8_SCHED; PG8_LDA(At, 1, 0); PG8_STAGE(PG8_SA(0, 1), a2 + hstep, voffA);
;             PG8_WAIT_V(8); PG8_WAIT_L(0); PG8_BAR; PG8_MMA(0, 0, At, B0); PG8_MMA(0, 1, At, B1); PG8_BAR; PG8_SCHED;
;             PG8_LDA(At, 1, 1); PG8_STAGE(PG8_SB(1, 0), b3, voffB); PG8_STAGE(PG8_SB(1, 1), b3 + hstep, voffB); PG8_STAGE(PG8_SA(1, 0), a3, voffA);
;             PG8_WAIT_V(8); PG8_WAIT_L(0); PG8_BAR; PG8_MMA(1, 0, At, B0); PG8_MMA(1, 1, At, B1); PG8_BAR; PG8_SCHED;
	s_setprio 1
	s_waitcnt lgkmcnt(0)
	v_mfma_i32_16x16x64_i8 v[80:83], v[28:31], v[164:167], 0
	v_mfma_i32_16x16x64_i8 v[80:83], v[32:35], v[168:171], v[80:83]
	v_mfma_i32_16x16x64_i8 v[64:67], v[32:35], v[176:179], 0
	v_mfma_i32_16x16x64_i8 v[64:67], v[28:31], v[172:175], v[64:67]
	v_mfma_i32_16x16x64_i8 v[48:51], v[28:31], v[204:207], 0
	v_mfma_i32_16x16x64_i8 v[48:51], v[32:35], v[208:211], v[48:51]
	v_mfma_i32_16x16x64_i8 v[16:19], v[32:35], v[220:223], 0
	v_mfma_i32_16x16x64_i8 v[16:19], v[28:31], v[212:215], v[16:19]
	v_mfma_i32_16x16x64_i8 v[12:15], v[36:39], v[212:215], 0
	v_mfma_i32_16x16x64_i8 v[12:15], v[40:43], v[220:223], v[12:15]
	v_mfma_i32_16x16x64_i8 v[44:47], v[40:43], v[208:211], 0
	v_mfma_i32_16x16x64_i8 v[44:47], v[36:39], v[204:207], v[44:47]
	v_mfma_i32_16x16x64_i8 v[60:63], v[36:39], v[172:175], 0
	v_mfma_i32_16x16x64_i8 v[60:63], v[40:43], v[176:179], v[60:63]
	v_mfma_i32_16x16x64_i8 v[76:79], v[40:43], v[168:171], 0
	v_mfma_i32_16x16x64_i8 v[76:79], v[36:39], v[164:167], v[76:79]
	v_mfma_i32_16x16x64_i8 v[28:31], v[140:143], v[164:167], 0
	v_mfma_i32_16x16x64_i8 v[28:31], v[144:147], v[168:171], v[28:31]
	v_mfma_i32_16x16x64_i8 v[36:39], v[144:147], v[176:179], 0
	v_mfma_i32_16x16x64_i8 v[36:39], v[140:143], v[172:175], v[36:39]
	v_mfma_i32_16x16x64_i8 v[24:27], v[140:143], v[204:207], 0
	v_mfma_i32_16x16x64_i8 v[24:27], v[144:147], v[208:211], v[24:27]
	v_mfma_i32_16x16x64_i8 v[8:11], v[144:147], v[220:223], 0
	v_mfma_i32_16x16x64_i8 v[8:11], v[140:143], v[212:215], v[8:11]
	v_mfma_i32_16x16x64_i8 v[4:7], v[156:159], v[212:215], 0
	v_mfma_i32_16x16x64_i8 v[4:7], v[160:163], v[220:223], v[4:7]
	v_mfma_i32_16x16x64_i8 v[20:23], v[160:163], v[208:211], 0
	v_mfma_i32_16x16x64_i8 v[20:23], v[156:159], v[204:207], v[20:23]
	v_mfma_i32_16x16x64_i8 v[40:43], v[156:159], v[172:175], 0
	v_mfma_i32_16x16x64_i8 v[40:43], v[160:163], v[176:179], v[40:43]
	v_mfma_i32_16x16x64_i8 v[32:35], v[160:163], v[168:171], 0
	v_mfma_i32_16x16x64_i8 v[32:35], v[156:159], v[164:167], v[32:35]
	s_setprio 0
	s_barrier
	s_mov_b32 m0, s65
	s_nop 0
	global_load_lds_dwordx4 v[226:227], off
	s_mov_b32 m0, s67
	s_nop 0
	global_load_lds_dwordx4 v[228:229], off
	s_add_i32 s87, 0, 0x18000
	s_add_i32 s96, 0, 0x1c000
	v_add_u32_e32 v72, s87, v217
	v_add_u32_e32 v160, s96, v217
	ds_read_b128 v[52:55], v72
	ds_read_b128 v[56:59], v72 offset:1024
	ds_read_b128 v[68:71], v72 offset:2048
	ds_read_b128 v[72:75], v72 offset:3072
	ds_read_b128 v[140:143], v160
	ds_read_b128 v[144:147], v160 offset:1024
	ds_read_b128 v[156:159], v160 offset:2048
	ds_read_b128 v[160:163], v160 offset:3072
	s_add_u32 s60, s60, 0x80000
	s_addc_u32 s61, s61, 0
	s_mov_b32 m0, s72
	ds_read_b128 v[164:167], v219 offset:32768
	ds_read_b128 v[168:171], v219 offset:33792
	ds_read_b128 v[172:175], v219 offset:34816
	ds_read_b128 v[176:179], v219 offset:35840
	ds_read_b128 v[204:207], v219 offset:36864
	ds_read_b128 v[208:211], v219 offset:37888
	ds_read_b128 v[212:215], v219 offset:38912
	ds_read_b128 v[220:223], v219 offset:39936
	global_load_lds_dwordx4 v180, s[60:61]
	s_mov_b32 m0, s73
	s_nop 0
	global_load_lds_dwordx4 v182, s[60:61]
	s_waitcnt vmcnt(8)
	s_waitcnt lgkmcnt(0)
	s_barrier
	s_setprio 1
	s_waitcnt lgkmcnt(0)
	v_mfma_i32_16x16x64_i8 v[152:155], v[52:55], v[164:167], v[152:155]
	v_mfma_i32_16x16x64_i8 v[152:155], v[56:59], v[168:171], v[152:155]
	v_mfma_i32_16x16x64_i8 v[128:131], v[56:59], v[176:179], v[128:131]
	v_mfma_i32_16x16x64_i8 v[128:131], v[52:55], v[172:175], v[128:131]
	v_mfma_i32_16x16x64_i8 v[112:115], v[52:55], v[204:207], v[112:115]
	v_mfma_i32_16x16x64_i8 v[112:115], v[56:59], v[208:211], v[112:115]
	v_mfma_i32_16x16x64_i8 v[96:99], v[56:59], v[220:223], v[96:99]
	v_mfma_i32_16x16x64_i8 v[96:99], v[52:55], v[212:215], v[96:99]
	v_mfma_i32_16x16x64_i8 v[92:95], v[68:71], v[212:215], v[92:95]
	v_mfma_i32_16x16x64_i8 v[92:95], v[72:75], v[220:223], v[92:95]
	v_mfma_i32_16x16x64_i8 v[108:111], v[72:75], v[208:211], v[108:111]
	v_mfma_i32_16x16x64_i8 v[108:111], v[68:71], v[204:207], v[108:111]
	v_mfma_i32_16x16x64_i8 v[124:127], v[68:71], v[172:175], v[124:127]
	v_mfma_i32_16x16x64_i8 v[124:127], v[72:75], v[176:179], v[124:127]
	v_mfma_i32_16x16x64_i8 v[148:151], v[72:75], v[168:171], v[148:151]
	v_mfma_i32_16x16x64_i8 v[148:151], v[68:71], v[164:167], v[148:151]
	v_mfma_i32_16x16x64_i8 v[136:139], v[140:143], v[164:167], v[136:139]
	v_mfma_i32_16x16x64_i8 v[136:139], v[144:147], v[168:171], v[136:139]
	v_mfma_i32_16x16x64_i8 v[120:123], v[144:147], v[176:179], v[120:123]
	v_mfma_i32_16x16x64_i8 v[120:123], v[140:143], v[172:175], v[120:123]
	v_mfma_i32_16x16x64_i8 v[104:107], v[140:143], v[204:207], v[104:107]
	v_mfma_i32_16x16x64_i8 v[104:107], v[144:147], v[208:211], v[104:107]
	v_mfma_i32_16x16x64_i8 v[88:91], v[144:147], v[220:223], v[88:91]
	v_mfma_i32_16x16x64_i8 v[88:91], v[140:143], v[212:215], v[88:91]
	v_mfma_i32_16x16x64_i8 v[84:87], v[156:159], v[212:215], v[84:87]
	v_mfma_i32_16x16x64_i8 v[84:87], v[160:163], v[220:223], v[84:87]
	v_mfma_i32_16x16x64_i8 v[100:103], v[160:163], v[208:211], v[100:103]
	v_mfma_i32_16x16x64_i8 v[100:103], v[156:159], v[204:207], v[100:103]
	v_mfma_i32_16x16x64_i8 v[116:119], v[156:159], v[172:175], v[116:119]
	v_mfma_i32_16x16x64_i8 v[116:119], v[160:163], v[176:179], v[116:119]
	v_mfma_i32_16x16x64_i8 v[132:135], v[160:163], v[168:171], v[132:135]
	v_mfma_i32_16x16x64_i8 v[132:135], v[156:159], v[164:167], v[132:135]
	s_setprio 0
	s_barrier
	s_add_u32 s98, s58, 0x80
	s_addc_u32 s99, s59, 0
	s_add_i32 s60, s87, s46
	s_mov_b32 m0, s60
	ds_read_b128 v[164:167], v219 offset:49152
	ds_read_b128 v[168:171], v219 offset:50176
	ds_read_b128 v[172:175], v219 offset:51200
	ds_read_b128 v[176:179], v219 offset:52224
	ds_read_b128 v[204:207], v219 offset:53248
	ds_read_b128 v[208:211], v219 offset:54272
	ds_read_b128 v[212:215], v219 offset:55296
	ds_read_b128 v[220:223], v219 offset:56320
	global_load_lds_dwordx4 v2, s[98:99]
	s_add_i32 m0, s60, 0x2000
	s_add_u32 s58, s58, 0x80080
	s_addc_u32 s59, s59, 0
	s_add_i32 s60, s96, s46
	global_load_lds_dwordx4 v184, s[98:99]
	s_mov_b32 m0, s60
	s_nop 0
	global_load_lds_dwordx4 v2, s[58:59]
	s_add_i32 m0, s60, 0x2000
	s_nop 0
	global_load_lds_dwordx4 v184, s[58:59]
	s_cmp_eq_u32 s86, 28
	s_cbranch_scc0 .Ldefer_1843_peel
	v_lshl_add_u64 v[190:191], v[226:227], 0, s[84:85]
	s_mov_b32 m0, s28
	s_nop 0
	global_load_lds_dwordx4 v[190:191], off
	v_lshl_add_u64 v[190:191], v[228:229], 0, s[84:85]
	s_mov_b32 m0, s77
	s_nop 0
	global_load_lds_dwordx4 v[190:191], off

; #define PG8_STAGE(bufoff, gbase, voff) do { _Pragma("unroll") for (int _i = 0; _i < 2; ++_i) \
;         __builtin_amdgcn_global_load_lds((const unsigned*)((const char*)(gbase) + (voff)[_i]), (PG8_LAS unsigned*)(lds + (bufoff) + ldsw + _i * 8192), 16, 0, 0); } while (0)
; #define PG8_LDA(dst, b, h) do { _Pragma("unroll") for (int m = 0; m < 4; ++m) _Pragma("unroll") for (int k = 0; k < 2; ++k) dst[m][k] = *(const PG8_LAS bf16x8*)(lds + PG8_SA(b, h) + aoff + m * 2048 + k * 1024); } while (0)
; #define PG8_LDB(dst, b, h) do { _Pragma("unroll") for (int n = 0; n < 2; ++n) _Pragma("unroll") for (int k = 0; k < 2; ++k) dst[n][k] = *(const PG8_LAS bf16x8*)(lds + PG8_SB(b, h) + boff + n * 2048 + k * 1024); } while (0)
; #define PG8_WAIT_V(n) asm volatile("s_waitcnt vmcnt(" #n ")" ::: "memory")
; #define PG8_WAIT_L(n) asm volatile("s_waitcnt lgkmcnt(" #n ")" ::: "memory")
; #define PG8_BAR __builtin_amdgcn_s_barrier()
; #define PG8_SCHED __builtin_amdgcn_sched_barrier(0)
; template <class Epi, class Sched, bool ALIGN_EPI = false, bool SP2 = false, bool I8 = false>
; __device__ __forceinline__ void gemm_phase(PG8_LAS unsigned char* lds, const Gemm g, const Sched& S, const Epi& E) {
;     ...
;             const bool last = (t == nt - 2);
;             const char* a1 = cA + (size_t)(t + 1) * kstep;
;             const char* a2 = last ? nA : cA + (size_t)(t + 2) * kstep; const char* b2 = last ? nB : cB + (size_t)(t + 2) * kstep;
;             const char* a3 = a2 + kstep; const char* b3 = b2 + kstep;
;             if (last && has_next) S.a_ready(nxt);
;             if constexpr (SP2) {
;             PG8_LDB(B0, 0, 0); PG8_LDB(B1, 0, 1); PG8_SCHED; PG8_LDA(At, 0, 0); PG8_STAGE(PG8_SA(1, 1), a1 + hstep, voffA);
;             PG8_WAIT_V(8); PG8_WAIT_L(0); PG8_BAR; PG8_MMA(0, 0, At, B0); PG8_MMA(0, 1, At, B1); PG8_BAR; PG8_SCHED;
;             PG8_LDA(At, 0, 1); PG8_STAGE(PG8_SB(0, 0), b2, voffB); PG8_STAGE(PG8_SB(0, 1), b2 + hstep, voffB); PG8_STAGE(PG8_SA(0, 0), a2, voffA);
;             PG8_WAIT_V(8); PG8_WAIT_L(0); PG8_BAR; PG8_MMA(1, 0, At, B0); PG8_MMA(1, 1, At, B1); PG8_BAR; PG8_SCHED;
.LBB0_1843:
	s_add_u32 s58, s54, 0xfff80080
	s_addc_u32 s59, s55, -1
	s_add_i32 s87, 0, 0x10000
	s_cmp_eq_u32 s86, 28
	s_cselect_b32 s61, s11, s59
	s_cselect_b32 s60, s13, s58
	s_cselect_b32 s59, s34, s49
	s_cselect_b32 s58, s35, s45
	s_add_i32 vcc_lo, 0, 0x14000
	v_add_u32_e32 v40, s87, v217
	v_add_u32_e32 v160, vcc_lo, v217
	ds_read_b128 v[28:31], v40
	ds_read_b128 v[32:35], v40 offset:1024
	ds_read_b128 v[36:39], v40 offset:2048
	ds_read_b128 v[40:43], v40 offset:3072
	ds_read_b128 v[140:143], v160
	ds_read_b128 v[144:147], v160 offset:1024
	ds_read_b128 v[156:159], v160 offset:2048
	ds_read_b128 v[160:163], v160 offset:3072
	v_lshl_add_u64 v[190:191], v[226:227], 0, s[84:85]
	s_mov_b32 m0, s28
	s_nop 0
	global_load_lds_dwordx4 v[190:191], off
	v_lshl_add_u64 v[190:191], v[228:229], 0, s[84:85]
	s_mov_b32 m0, s77
	s_nop 0
	global_load_lds_dwordx4 v[190:191], off
	s_add_i32 m0, s65, 0xc000
	ds_read_b128 v[164:167], v219
	ds_read_b128 v[168:171], v219 offset:1024
	ds_read_b128 v[172:175], v219 offset:2048
	ds_read_b128 v[176:179], v219 offset:3072
	ds_read_b128 v[204:207], v219 offset:4096
	ds_read_b128 v[208:211], v219 offset:5120
	ds_read_b128 v[212:215], v219 offset:6144
	ds_read_b128 v[220:223], v219 offset:7168
	global_load_lds_dwordx4 v186, s[54:55]
	s_add_i32 m0, s65, 0xe000
	s_nop 0
	global_load_lds_dwordx4 v188, s[54:55]
	s_waitcnt vmcnt(8)
	s_waitcnt lgkmcnt(0)
	s_barrier
	s_setprio 1
	s_waitcnt lgkmcnt(0)
	v_mfma_i32_16x16x64_i8 v[152:155], v[28:31], v[164:167], v[152:155]
	v_mfma_i32_16x16x64_i8 v[152:155], v[32:35], v[168:171], v[152:155]
	v_mfma_i32_16x16x64_i8 v[128:131], v[32:35], v[176:179], v[128:131]
	v_mfma_i32_16x16x64_i8 v[128:131], v[28:31], v[172:175], v[128:131]
	v_mfma_i32_16x16x64_i8 v[112:115], v[28:31], v[204:207], v[112:115]
	v_mfma_i32_16x16x64_i8 v[112:115], v[32:35], v[208:211], v[112:115]
	v_mfma_i32_16x16x64_i8 v[96:99], v[32:35], v[220:223], v[96:99]
	v_mfma_i32_16x16x64_i8 v[96:99], v[28:31], v[212:215], v[96:99]
	v_mfma_i32_16x16x64_i8 v[92:95], v[36:39], v[212:215], v[92:95]
	v_mfma_i32_16x16x64_i8 v[92:95], v[40:43], v[220:223], v[92:95]
	v_mfma_i32_16x16x64_i8 v[108:111], v[40:43], v[208:211], v[108:111]
	v_mfma_i32_16x16x64_i8 v[108:111], v[36:39], v[204:207], v[108:111]
	v_mfma_i32_16x16x64_i8 v[124:127], v[36:39], v[172:175], v[124:127]
	v_mfma_i32_16x16x64_i8 v[124:127], v[40:43], v[176:179], v[124:127]
	v_mfma_i32_16x16x64_i8 v[148:151], v[40:43], v[168:171], v[148:151]
	v_mfma_i32_16x16x64_i8 v[148:151], v[36:39], v[164:167], v[148:151]
	v_mfma_i32_16x16x64_i8 v[136:139], v[140:143], v[164:167], v[136:139]
	v_mfma_i32_16x16x64_i8 v[136:139], v[144:147], v[168:171], v[136:139]
	v_mfma_i32_16x16x64_i8 v[120:123], v[144:147], v[176:179], v[120:123]
	v_mfma_i32_16x16x64_i8 v[120:123], v[140:143], v[172:175], v[120:123]
	v_mfma_i32_16x16x64_i8 v[104:107], v[140:143], v[204:207], v[104:107]
	v_mfma_i32_16x16x64_i8 v[104:107], v[144:147], v[208:211], v[104:107]
	v_mfma_i32_16x16x64_i8 v[88:91], v[144:147], v[220:223], v[88:91]
	v_mfma_i32_16x16x64_i8 v[88:91], v[140:143], v[212:215], v[88:91]
	v_mfma_i32_16x16x64_i8 v[84:87], v[156:159], v[212:215], v[84:87]
	v_mfma_i32_16x16x64_i8 v[84:87], v[160:163], v[220:223], v[84:87]
	v_mfma_i32_16x16x64_i8 v[100:103], v[160:163], v[208:211], v[100:103]
	v_mfma_i32_16x16x64_i8 v[100:103], v[156:159], v[204:207], v[100:103]
	v_mfma_i32_16x16x64_i8 v[116:119], v[156:159], v[172:175], v[116:119]
	v_mfma_i32_16x16x64_i8 v[116:119], v[160:163], v[176:179], v[116:119]
	v_mfma_i32_16x16x64_i8 v[132:135], v[160:163], v[168:171], v[132:135]
	v_mfma_i32_16x16x64_i8 v[132:135], v[156:159], v[164:167], v[132:135]
	s_setprio 0
	s_barrier
	s_add_i32 s87, s87, s46
	s_mov_b32 m0, s87
	ds_read_b128 v[164:167], v219 offset:16384
	ds_read_b128 v[168:171], v219 offset:17408
	ds_read_b128 v[172:175], v219 offset:18432
	ds_read_b128 v[176:179], v219 offset:19456
	ds_read_b128 v[204:207], v219 offset:20480
	ds_read_b128 v[208:211], v219 offset:21504
	ds_read_b128 v[212:215], v219 offset:22528
	ds_read_b128 v[220:223], v219 offset:23552
	global_load_lds_dwordx4 v2, s[58:59]
	s_add_i32 m0, s87, 0x2000
	s_add_u32 s96, s58, 0x80000
	s_addc_u32 s97, s59, 0
	s_add_i32 s87, vcc_lo, s46
	global_load_lds_dwordx4 v184, s[58:59]
	s_mov_b32 m0, s87
	v_lshl_add_u64 v[228:229], s[60:61], 0, v[182:183]
	global_load_lds_dwordx4 v2, s[96:97]
	s_add_i32 m0, s87, 0x2000
	s_nop 0
	global_load_lds_dwordx4 v184, s[96:97]
	v_lshl_add_u64 v[226:227], s[60:61], 0, v[180:181]
	s_waitcnt vmcnt(6)
	s_waitcnt lgkmcnt(0)
	s_barrier
; #define PG8_STAGE(bufoff, gbase, voff) do { _Pragma("unroll") for (int _i = 0; _i < 2; ++_i) \
;         __builtin_amdgcn_global_load_lds((const unsigned*)((const char*)(gbase) + (voff)[_i]), (PG8_LAS unsigned*)(lds + (bufoff) + ldsw + _i * 8192), 16, 0, 0); } while (0)
; #define PG8_LDA(dst, b, h) do { _Pragma("unroll") for (int m = 0; m < 4; ++m) _Pragma("unroll") for (int k = 0; k < 2; ++k) dst[m][k] = *(const PG8_LAS bf16x8*)(lds + PG8_SA(b, h) + aoff + m * 2048 + k * 1024); } while (0)
; #define PG8_LDB(dst, b, h) do { _Pragma("unroll") for (int n = 0; n < 2; ++n) _Pragma("unroll") for (int k = 0; k < 2; ++k) dst[n][k] = *(const PG8_LAS bf16x8*)(lds + PG8_SB(b, h) + boff + n * 2048 + k * 1024); } while (0)
; #define PG8_WAIT_V(n) asm volatile("s_waitcnt vmcnt(" #n ")" ::: "memory")
; #define PG8_WAIT_L(n) asm volatile("s_waitcnt lgkmcnt(" #n ")" ::: "memory")
; #define PG8_BAR __builtin_amdgcn_s_barrier()
; #define PG8_SCHED __builtin_amdgcn_sched_barrier(0)
; template <class Epi, class Sched, bool ALIGN_EPI = false, bool SP2 = false, bool I8 = false>
; __device__ __forceinline__ void gemm_phase(PG8_LAS unsigned char* lds, const Gemm g, const Sched& S, const Epi& E) {
;     ...
;             PG8_WAIT_V(8); PG8_WAIT_L(0); PG8_BAR; PG8_MMA(1, 0, At, B0); PG8_MMA(1, 1, At, B1); PG8_BAR; PG8_SCHED;
;             PG8_LDB(B0, 1, 0); PG8_LDB(B1, 1, 1); PG8_SCHED; PG8_LDA(At, 1, 0); PG8_STAGE(PG8_SA(0, 1), a2 + hstep, voffA);
;             PG8_WAIT_V(8); PG8_WAIT_L(0); PG8_BAR; PG8_MMA(0, 0, At, B0); PG8_MMA(0, 1, At, B1); PG8_BAR; PG8_SCHED;
;             PG8_LDA(At, 1, 1); PG8_STAGE(PG8_SB(1, 0), b3, voffB); PG8_STAGE(PG8_SB(1, 1), b3 + hstep, voffB); PG8_STAGE(PG8_SA(1, 0), a3, voffA);
;             PG8_WAIT_V(8); PG8_WAIT_L(0); PG8_BAR; PG8_MMA(1, 0, At, B0); PG8_MMA(1, 1, At, B1); PG8_BAR; PG8_SCHED;
	s_setprio 1
	s_waitcnt lgkmcnt(0)
	v_mfma_i32_16x16x64_i8 v[80:83], v[28:31], v[164:167], v[80:83]
	v_mfma_i32_16x16x64_i8 v[80:83], v[32:35], v[168:171], v[80:83]
	v_mfma_i32_16x16x64_i8 v[64:67], v[32:35], v[176:179], v[64:67]
	v_mfma_i32_16x16x64_i8 v[64:67], v[28:31], v[172:175], v[64:67]
	v_mfma_i32_16x16x64_i8 v[48:51], v[28:31], v[204:207], v[48:51]
	v_mfma_i32_16x16x64_i8 v[48:51], v[32:35], v[208:211], v[48:51]
	v_mfma_i32_16x16x64_i8 v[16:19], v[32:35], v[220:223], v[16:19]
	v_mfma_i32_16x16x64_i8 v[16:19], v[28:31], v[212:215], v[16:19]
	v_mfma_i32_16x16x64_i8 v[12:15], v[36:39], v[212:215], v[12:15]
	v_mfma_i32_16x16x64_i8 v[12:15], v[40:43], v[220:223], v[12:15]
	v_mfma_i32_16x16x64_i8 v[44:47], v[40:43], v[208:211], v[44:47]
	v_mfma_i32_16x16x64_i8 v[44:47], v[36:39], v[204:207], v[44:47]
	v_mfma_i32_16x16x64_i8 v[60:63], v[36:39], v[172:175], v[60:63]
	v_mfma_i32_16x16x64_i8 v[60:63], v[40:43], v[176:179], v[60:63]
	v_mfma_i32_16x16x64_i8 v[76:79], v[40:43], v[168:171], v[76:79]
	v_mfma_i32_16x16x64_i8 v[76:79], v[36:39], v[164:167], v[76:79]
	v_mfma_i32_16x16x64_i8 v[28:31], v[140:143], v[164:167], v[72:75]
	v_mfma_i32_16x16x64_i8 v[28:31], v[144:147], v[168:171], v[28:31]
	v_mfma_i32_16x16x64_i8 v[36:39], v[144:147], v[176:179], v[56:59]
	v_mfma_i32_16x16x64_i8 v[36:39], v[140:143], v[172:175], v[36:39]
	v_mfma_i32_16x16x64_i8 v[24:27], v[140:143], v[204:207], v[24:27]
	v_mfma_i32_16x16x64_i8 v[24:27], v[144:147], v[208:211], v[24:27]
	v_mfma_i32_16x16x64_i8 v[8:11], v[144:147], v[220:223], v[8:11]
	v_mfma_i32_16x16x64_i8 v[8:11], v[140:143], v[212:215], v[8:11]
	v_mfma_i32_16x16x64_i8 v[4:7], v[156:159], v[212:215], v[4:7]
	v_mfma_i32_16x16x64_i8 v[4:7], v[160:163], v[220:223], v[4:7]
	v_mfma_i32_16x16x64_i8 v[20:23], v[160:163], v[208:211], v[20:23]
	v_mfma_i32_16x16x64_i8 v[20:23], v[156:159], v[204:207], v[20:23]
	v_mfma_i32_16x16x64_i8 v[40:43], v[156:159], v[172:175], v[52:55]
	v_mfma_i32_16x16x64_i8 v[40:43], v[160:163], v[176:179], v[40:43]
	v_mfma_i32_16x16x64_i8 v[32:35], v[160:163], v[168:171], v[68:71]
	v_mfma_i32_16x16x64_i8 v[32:35], v[156:159], v[164:167], v[32:35]
	s_setprio 0
	s_barrier
	s_mov_b32 m0, s65
	s_nop 0
	global_load_lds_dwordx4 v[226:227], off
	s_mov_b32 m0, s67
	s_nop 0
	global_load_lds_dwordx4 v[228:229], off
	s_add_i32 s87, 0, 0x18000
	s_add_i32 s96, 0, 0x1c000
	v_add_u32_e32 v72, s87, v217
	v_add_u32_e32 v160, s96, v217
	ds_read_b128 v[52:55], v72
	ds_read_b128 v[56:59], v72 offset:1024
	ds_read_b128 v[68:71], v72 offset:2048
	ds_read_b128 v[72:75], v72 offset:3072
	ds_read_b128 v[140:143], v160
	ds_read_b128 v[144:147], v160 offset:1024
	ds_read_b128 v[156:159], v160 offset:2048
	ds_read_b128 v[160:163], v160 offset:3072
	s_add_u32 s60, s60, 0x80000
	s_addc_u32 s61, s61, 0
	s_mov_b32 m0, s72
	ds_read_b128 v[164:167], v219 offset:32768
	ds_read_b128 v[168:171], v219 offset:33792
	ds_read_b128 v[172:175], v219 offset:34816
	ds_read_b128 v[176:179], v219 offset:35840
	ds_read_b128 v[204:207], v219 offset:36864
	ds_read_b128 v[208:211], v219 offset:37888
	ds_read_b128 v[212:215], v219 offset:38912
	ds_read_b128 v[220:223], v219 offset:39936
	global_load_lds_dwordx4 v180, s[60:61]
	s_mov_b32 m0, s73
	s_nop 0
	global_load_lds_dwordx4 v182, s[60:61]
	s_waitcnt vmcnt(8)
	s_waitcnt lgkmcnt(0)
	s_barrier
	s_setprio 1
	s_waitcnt lgkmcnt(0)
	v_mfma_i32_16x16x64_i8 v[152:155], v[52:55], v[164:167], v[152:155]
	v_mfma_i32_16x16x64_i8 v[152:155], v[56:59], v[168:171], v[152:155]
	v_mfma_i32_16x16x64_i8 v[128:131], v[56:59], v[176:179], v[128:131]
	v_mfma_i32_16x16x64_i8 v[128:131], v[52:55], v[172:175], v[128:131]
	v_mfma_i32_16x16x64_i8 v[112:115], v[52:55], v[204:207], v[112:115]
	v_mfma_i32_16x16x64_i8 v[112:115], v[56:59], v[208:211], v[112:115]
	v_mfma_i32_16x16x64_i8 v[96:99], v[56:59], v[220:223], v[96:99]
	v_mfma_i32_16x16x64_i8 v[96:99], v[52:55], v[212:215], v[96:99]
	v_mfma_i32_16x16x64_i8 v[92:95], v[68:71], v[212:215], v[92:95]
	v_mfma_i32_16x16x64_i8 v[92:95], v[72:75], v[220:223], v[92:95]
	v_mfma_i32_16x16x64_i8 v[108:111], v[72:75], v[208:211], v[108:111]
	v_mfma_i32_16x16x64_i8 v[108:111], v[68:71], v[204:207], v[108:111]
	v_mfma_i32_16x16x64_i8 v[124:127], v[68:71], v[172:175], v[124:127]
	v_mfma_i32_16x16x64_i8 v[124:127], v[72:75], v[176:179], v[124:127]
	v_mfma_i32_16x16x64_i8 v[148:151], v[72:75], v[168:171], v[148:151]
	v_mfma_i32_16x16x64_i8 v[148:151], v[68:71], v[164:167], v[148:151]
	v_mfma_i32_16x16x64_i8 v[136:139], v[140:143], v[164:167], v[136:139]
	v_mfma_i32_16x16x64_i8 v[136:139], v[144:147], v[168:171], v[136:139]
	v_mfma_i32_16x16x64_i8 v[120:123], v[144:147], v[176:179], v[120:123]
	v_mfma_i32_16x16x64_i8 v[120:123], v[140:143], v[172:175], v[120:123]
	v_mfma_i32_16x16x64_i8 v[104:107], v[140:143], v[204:207], v[104:107]
	v_mfma_i32_16x16x64_i8 v[104:107], v[144:147], v[208:211], v[104:107]
	v_mfma_i32_16x16x64_i8 v[88:91], v[144:147], v[220:223], v[88:91]
	v_mfma_i32_16x16x64_i8 v[88:91], v[140:143], v[212:215], v[88:91]
	v_mfma_i32_16x16x64_i8 v[84:87], v[156:159], v[212:215], v[84:87]
	v_mfma_i32_16x16x64_i8 v[84:87], v[160:163], v[220:223], v[84:87]
	v_mfma_i32_16x16x64_i8 v[100:103], v[160:163], v[208:211], v[100:103]
	v_mfma_i32_16x16x64_i8 v[100:103], v[156:159], v[204:207], v[100:103]
	v_mfma_i32_16x16x64_i8 v[116:119], v[156:159], v[172:175], v[116:119]
	v_mfma_i32_16x16x64_i8 v[116:119], v[160:163], v[176:179], v[116:119]
	v_mfma_i32_16x16x64_i8 v[132:135], v[160:163], v[168:171], v[132:135]
	v_mfma_i32_16x16x64_i8 v[132:135], v[156:159], v[164:167], v[132:135]
	s_setprio 0
	s_barrier
	s_add_u32 s98, s58, 0x80
	s_addc_u32 s99, s59, 0
	s_add_i32 s60, s87, s46
	s_mov_b32 m0, s60
	ds_read_b128 v[164:167], v219 offset:49152
	ds_read_b128 v[168:171], v219 offset:50176
	ds_read_b128 v[172:175], v219 offset:51200
	ds_read_b128 v[176:179], v219 offset:52224
	ds_read_b128 v[204:207], v219 offset:53248
	ds_read_b128 v[208:211], v219 offset:54272
	ds_read_b128 v[212:215], v219 offset:55296
	ds_read_b128 v[220:223], v219 offset:56320
	global_load_lds_dwordx4 v2, s[98:99]
	s_add_i32 m0, s60, 0x2000
	s_add_u32 s58, s58, 0x80080
	s_addc_u32 s59, s59, 0
	s_add_i32 s60, s96, s46
	global_load_lds_dwordx4 v184, s[98:99]
	s_mov_b32 m0, s60
	s_nop 0
	global_load_lds_dwordx4 v2, s[58:59]
	s_add_i32 m0, s60, 0x2000
	s_nop 0
	global_load_lds_dwordx4 v184, s[58:59]
	s_cmp_eq_u32 s86, 28
	s_cbranch_scc0 .Ldefer_1843_body
	v_lshl_add_u64 v[190:191], v[226:227], 0, s[84:85]
	s_mov_b32 m0, s28
	s_nop 0
	global_load_lds_dwordx4 v[190:191], off
	v_lshl_add_u64 v[190:191], v[228:229], 0, s[84:85]
	s_mov_b32 m0, s77
	s_nop 0
	global_load_lds_dwordx4 v[190:191], off
